# A/B: all 112 per-phase s_setprio 1/0 flips in the GEMM K loops removed (timing-only change)
# speedup vs baseline: 1.0133x; 1.0133x over previous
; #define PG8_STAGE(bufoff, gbase, voff) do { _Pragma("unroll") for (int _i = 0; _i < 2; ++_i) \
;     __builtin_amdgcn_global_load_lds((const unsigned*)((const char*)(gbase) + (voff)[_i]), (LAS unsigned*)(lds + (bufoff) + ldsw + _i * 8192), 16, 0, 0); } while (0)
; #define PG8_LDA(dst, b, h) do { _Pragma("unroll") for (int m = 0; m < 4; ++m) _Pragma("unroll") for (int k = 0; k < 2; ++k) dst[m][k] = *(const LAS bf16x8*)(lds + PG8_SA(b, h) + aoff + m * 2048 + k * 1024); } while (0)
; #define PG8_LDB(dst, b, h) do { _Pragma("unroll") for (int n = 0; n < 2; ++n) _Pragma("unroll") for (int k = 0; k < 2; ++k) dst[n][k] = *(const LAS bf16x8*)(lds + PG8_SB(b, h) + boff + n * 2048 + k * 1024); } while (0)
; #define PG8_MMA(ai, bj, At, Bt) do { __builtin_amdgcn_s_setprio(1); _Pragma("unroll") for (int m = 0; m < 4; ++m) _Pragma("unroll") for (int n = 0; n < 2; ++n) _Pragma("unroll") for (int k = 0; k < 2; ++k) \
;     acc[ai][bj][m][n] = __builtin_amdgcn_mfma_f32_16x16x32_bf16(Bt[n][k], At[m][k], acc[ai][bj][m][n], 0, 0, 0); __builtin_amdgcn_s_setprio(0); } while (0)
; #define PG8_WAIT_L(n) asm volatile("s_waitcnt lgkmcnt(" #n ")" ::: "memory")
; #define PG8_BAR __builtin_amdgcn_s_barrier()
; #define PG8_SCHED __builtin_amdgcn_sched_barrier(0)
; template <class Epi, class Sched, bool ABLK = false>
; __device__ __forceinline__ void gemm_phase(LAS unsigned char* lds, const Gemm g, const Sched& S, const Epi& E) {
;     ...
;     for (int t = 0; t < nt; t += 2) {
;       const bool last = (t == nt - 2);
;       const char* a1 = cA + (size_t)(t + 1) * kstep;
;       const char* a2 = last ? nA : cA + (size_t)(t + 2) * kstep; const char* b2 = last ? nB : cB + (size_t)(t + 2) * kstepB;
;       const char* a3 = a2 + kstep; const char* b3 = b2 + kstepB;
;       PG8_LDB(B0, 0, 0); PG8_SCHED; PG8_LDA(At, 0, 0); PG8_STAGE(PG8_SA(1, 1), a1 + hstep, voffA);
;       PG8_WAIT_L(8); PG8_BAR; PG8_WAIT_L(0); PG8_MMA(0, 0, At, B0); PG8_BAR; PG8_SCHED;
;       PG8_LDB(B1, 0, 1); PG8_STAGE(PG8_SB(0, 0), b2, voffB);
;       PG8_BAR; PG8_WAIT_L(0); PG8_MMA(0, 1, At, B1); PG8_BAR;
;       PG8_LDA(At, 0, 1); PG8_STAGE(PG8_SA(0, 0), a2, voffA);
;       PG8_BAR; PG8_WAIT_L(0); PG8_MMA(1, 0, At, B0); PG8_BAR; PG8_SCHED;
.LBB0_178:
	s_add_u32 s42, s38, 0xfff80080
	s_addc_u32 s43, s39, -1
	s_add_i32 s49, 0, 0x10000
	v_add_u32_e32 v140, s49, v143
	ds_read_b128 v[148:151], v140
	ds_read_b128 v[152:155], v140 offset:1024
	ds_read_b128 v[156:159], v140 offset:2048
	ds_read_b128 v[160:163], v140 offset:3072
	s_cmp_eq_u32 s48, 28
	s_cselect_b32 s45, s29, s43
	s_cselect_b32 s44, s28, s42
	s_cselect_b32 s43, s15, s47
	s_cselect_b32 s42, s21, s46
	v_lshl_add_u64 v[140:141], s[38:39], 0, v[136:137]
	s_add_i32 m0, s11, 0xc000
	ds_read_b128 v[164:167], v146
	ds_read_b128 v[168:171], v146 offset:1024
	ds_read_b128 v[172:175], v146 offset:2048
	ds_read_b128 v[176:179], v146 offset:3072
	ds_read_b128 v[180:183], v146 offset:4096
	ds_read_b128 v[184:187], v146 offset:5120
	ds_read_b128 v[188:191], v146 offset:6144
	ds_read_b128 v[192:195], v146 offset:7168
	global_load_lds_dwordx4 v[140:141], off
	v_lshl_add_u64 v[140:141], s[38:39], 0, v[138:139]
	s_add_i32 m0, s11, 0xe000
	s_nop 0
	global_load_lds_dwordx4 v[140:141], off
	s_waitcnt lgkmcnt(8)
	s_barrier
	s_waitcnt lgkmcnt(0)
	s_waitcnt lgkmcnt(0)
	v_mfma_f32_16x16x32_bf16 v[126:129], v[148:151], v[164:167], v[126:129]
	v_mfma_f32_16x16x32_bf16 v[122:125], v[156:159], v[164:167], v[122:125]
	v_mfma_f32_16x16x32_bf16 v[114:117], v[148:151], v[172:175], v[114:117]
	v_mfma_f32_16x16x32_bf16 v[106:109], v[156:159], v[172:175], v[106:109]
	v_mfma_f32_16x16x32_bf16 v[98:101], v[148:151], v[180:183], v[98:101]
	v_mfma_f32_16x16x32_bf16 v[90:93], v[156:159], v[180:183], v[90:93]
	v_mfma_f32_16x16x32_bf16 v[82:85], v[148:151], v[188:191], v[82:85]
	v_mfma_f32_16x16x32_bf16 v[74:77], v[156:159], v[188:191], v[74:77]
	v_mfma_f32_16x16x32_bf16 v[126:129], v[152:155], v[168:171], v[126:129]
	v_mfma_f32_16x16x32_bf16 v[122:125], v[160:163], v[168:171], v[122:125]
	v_mfma_f32_16x16x32_bf16 v[114:117], v[152:155], v[176:179], v[114:117]
	v_mfma_f32_16x16x32_bf16 v[106:109], v[160:163], v[176:179], v[106:109]
	v_mfma_f32_16x16x32_bf16 v[98:101], v[152:155], v[184:187], v[98:101]
	v_mfma_f32_16x16x32_bf16 v[90:93], v[160:163], v[184:187], v[90:93]
	v_mfma_f32_16x16x32_bf16 v[82:85], v[152:155], v[192:195], v[82:85]
	v_mfma_f32_16x16x32_bf16 v[74:77], v[160:163], v[192:195], v[74:77]
	s_barrier
	s_add_i32 s52, 0, 0x14000
	v_add_u32_e32 v140, s52, v143
	s_add_i32 s49, s49, s7
	ds_read_b128 v[208:211], v140
	ds_read_b128 v[212:215], v140 offset:1024
	ds_read_b128 v[216:219], v140 offset:2048
	ds_read_b128 v[220:223], v140 offset:3072
	v_lshl_add_u64 v[140:141], s[42:43], 0, v[130:131]
	s_mov_b32 m0, s49
	s_nop 0
	global_load_lds_dwordx4 v[140:141], off
	v_lshl_add_u64 v[140:141], s[42:43], 0, v[134:135]
	s_add_i32 m0, s49, 0x2000
	s_nop 0
	global_load_lds_dwordx4 v[140:141], off
	s_barrier
	s_waitcnt lgkmcnt(0)
	s_waitcnt lgkmcnt(0)
	v_mfma_f32_16x16x32_bf16 v[118:121], v[208:211], v[164:167], v[118:121]
	v_mfma_f32_16x16x32_bf16 v[110:113], v[216:219], v[164:167], v[110:113]
	v_mfma_f32_16x16x32_bf16 v[102:105], v[208:211], v[172:175], v[102:105]
	v_mfma_f32_16x16x32_bf16 v[94:97], v[216:219], v[172:175], v[94:97]
	v_mfma_f32_16x16x32_bf16 v[86:89], v[208:211], v[180:183], v[86:89]
	v_mfma_f32_16x16x32_bf16 v[78:81], v[216:219], v[180:183], v[78:81]
	v_mfma_f32_16x16x32_bf16 v[70:73], v[208:211], v[188:191], v[70:73]
	v_mfma_f32_16x16x32_bf16 v[66:69], v[216:219], v[188:191], v[66:69]
	v_mfma_f32_16x16x32_bf16 v[118:121], v[212:215], v[168:171], v[118:121]
	v_mfma_f32_16x16x32_bf16 v[110:113], v[220:223], v[168:171], v[110:113]
	v_mfma_f32_16x16x32_bf16 v[102:105], v[212:215], v[176:179], v[102:105]
	v_mfma_f32_16x16x32_bf16 v[94:97], v[220:223], v[176:179], v[94:97]
	v_mfma_f32_16x16x32_bf16 v[86:89], v[212:215], v[184:187], v[86:89]
	v_mfma_f32_16x16x32_bf16 v[78:81], v[220:223], v[184:187], v[78:81]
	v_mfma_f32_16x16x32_bf16 v[70:73], v[212:215], v[192:195], v[70:73]
	v_mfma_f32_16x16x32_bf16 v[66:69], v[220:223], v[192:195], v[66:69]
	s_mov_b32 m0, s11
	v_lshl_add_u64 v[140:141], s[44:45], 0, v[32:33]
	s_barrier
	ds_read_b128 v[164:167], v146 offset:16384
	ds_read_b128 v[168:171], v146 offset:17408
	ds_read_b128 v[172:175], v146 offset:18432
	ds_read_b128 v[176:179], v146 offset:19456
	ds_read_b128 v[180:183], v146 offset:20480
	ds_read_b128 v[184:187], v146 offset:21504
	ds_read_b128 v[188:191], v146 offset:22528
	ds_read_b128 v[192:195], v146 offset:23552
	global_load_lds_dwordx4 v[140:141], off
	v_lshl_add_u64 v[198:199], s[44:45], 0, v[132:133]
	s_mov_b32 m0, s17
	s_nop 0
	global_load_lds_dwordx4 v[198:199], off
	s_barrier
	s_waitcnt lgkmcnt(0)
	s_waitcnt lgkmcnt(0)
	v_mfma_f32_16x16x32_bf16 v[62:65], v[148:151], v[164:167], v[62:65]
	v_mfma_f32_16x16x32_bf16 v[58:61], v[156:159], v[164:167], v[58:61]
	v_mfma_f32_16x16x32_bf16 v[54:57], v[148:151], v[172:175], v[54:57]
	v_mfma_f32_16x16x32_bf16 v[46:49], v[156:159], v[172:175], v[46:49]
	v_mfma_f32_16x16x32_bf16 v[38:41], v[148:151], v[180:183], v[38:41]
	v_mfma_f32_16x16x32_bf16 v[28:31], v[156:159], v[180:183], v[28:31]
	v_mfma_f32_16x16x32_bf16 v[20:23], v[148:151], v[188:191], v[20:23]
	v_mfma_f32_16x16x32_bf16 v[12:15], v[156:159], v[188:191], v[12:15]
	v_mfma_f32_16x16x32_bf16 v[62:65], v[152:155], v[168:171], v[62:65]
	v_mfma_f32_16x16x32_bf16 v[58:61], v[160:163], v[168:171], v[58:61]
	v_mfma_f32_16x16x32_bf16 v[54:57], v[152:155], v[176:179], v[54:57]
	v_mfma_f32_16x16x32_bf16 v[46:49], v[160:163], v[176:179], v[46:49]
	v_mfma_f32_16x16x32_bf16 v[38:41], v[152:155], v[184:187], v[38:41]
	v_mfma_f32_16x16x32_bf16 v[28:31], v[160:163], v[184:187], v[28:31]
	v_mfma_f32_16x16x32_bf16 v[20:23], v[152:155], v[192:195], v[20:23]
	v_mfma_f32_16x16x32_bf16 v[12:15], v[160:163], v[192:195], v[12:15]
	s_barrier
; #define PG8_STAGE(bufoff, gbase, voff) do { _Pragma("unroll") for (int _i = 0; _i < 2; ++_i) \
;     __builtin_amdgcn_global_load_lds((const unsigned*)((const char*)(gbase) + (voff)[_i]), (LAS unsigned*)(lds + (bufoff) + ldsw + _i * 8192), 16, 0, 0); } while (0)
; #define PG8_LDA(dst, b, h) do { _Pragma("unroll") for (int m = 0; m < 4; ++m) _Pragma("unroll") for (int k = 0; k < 2; ++k) dst[m][k] = *(const LAS bf16x8*)(lds + PG8_SA(b, h) + aoff + m * 2048 + k * 1024); } while (0)
; #define PG8_LDB(dst, b, h) do { _Pragma("unroll") for (int n = 0; n < 2; ++n) _Pragma("unroll") for (int k = 0; k < 2; ++k) dst[n][k] = *(const LAS bf16x8*)(lds + PG8_SB(b, h) + boff + n * 2048 + k * 1024); } while (0)
; #define PG8_MMA(ai, bj, At, Bt) do { __builtin_amdgcn_s_setprio(1); _Pragma("unroll") for (int m = 0; m < 4; ++m) _Pragma("unroll") for (int n = 0; n < 2; ++n) _Pragma("unroll") for (int k = 0; k < 2; ++k) \
;     acc[ai][bj][m][n] = __builtin_amdgcn_mfma_f32_16x16x32_bf16(Bt[n][k], At[m][k], acc[ai][bj][m][n], 0, 0, 0); __builtin_amdgcn_s_setprio(0); } while (0)
; #define PG8_WAIT_V(n) asm volatile("s_waitcnt vmcnt(" #n ")" ::: "memory")
; #define PG8_WAIT_L(n) asm volatile("s_waitcnt lgkmcnt(" #n ")" ::: "memory")
; #define PG8_BAR __builtin_amdgcn_s_barrier()
; #define PG8_SCHED __builtin_amdgcn_sched_barrier(0)
; template <class Epi, class Sched, bool ABLK = false>
; __device__ __forceinline__ void gemm_phase(LAS unsigned char* lds, const Gemm g, const Sched& S, const Epi& E) {
;     ...
;       PG8_STAGE(PG8_SB(0, 1), b2 + hstepB, voffB);
;       PG8_WAIT_V(6); PG8_BAR; PG8_MMA(1, 1, At, B1); PG8_BAR;
;       PG8_LDB(B0, 1, 0); PG8_SCHED; PG8_LDA(At, 1, 0); PG8_STAGE(PG8_SA(0, 1), a2 + hstep, voffA);
;       PG8_WAIT_L(8); PG8_BAR; PG8_WAIT_L(0); PG8_MMA(0, 0, At, B0); PG8_BAR; PG8_SCHED;
;       PG8_LDB(B1, 1, 1); PG8_STAGE(PG8_SB(1, 0), b3, voffB);
;       PG8_BAR; PG8_WAIT_L(0); PG8_MMA(0, 1, At, B1); PG8_BAR;
;       PG8_LDA(At, 1, 1); PG8_STAGE(PG8_SA(1, 0), a3, voffA);
	s_add_u32 s50, s42, 0x4000
	s_addc_u32 s51, s43, 0
	s_add_i32 s49, s52, s7
	v_lshl_add_u64 v[148:149], s[50:51], 0, v[130:131]
	s_mov_b32 m0, s49
	s_nop 0
	global_load_lds_dwordx4 v[148:149], off
	v_lshl_add_u64 v[148:149], s[50:51], 0, v[134:135]
	s_add_i32 m0, s49, 0x2000
	s_nop 0
	global_load_lds_dwordx4 v[148:149], off
	s_waitcnt vmcnt(6)
	s_barrier
	v_mfma_f32_16x16x32_bf16 v[50:53], v[208:211], v[164:167], v[50:53]
	v_mfma_f32_16x16x32_bf16 v[42:45], v[216:219], v[164:167], v[42:45]
	v_mfma_f32_16x16x32_bf16 v[34:37], v[208:211], v[172:175], v[34:37]
	v_mfma_f32_16x16x32_bf16 v[24:27], v[216:219], v[172:175], v[24:27]
	v_mfma_f32_16x16x32_bf16 v[16:19], v[208:211], v[180:183], v[16:19]
	v_mfma_f32_16x16x32_bf16 v[8:11], v[216:219], v[180:183], v[8:11]
	v_mfma_f32_16x16x32_bf16 v[4:7], v[208:211], v[188:191], v[4:7]
	v_mfma_f32_16x16x32_bf16 v[0:3], v[216:219], v[188:191], v[0:3]
	v_mfma_f32_16x16x32_bf16 v[50:53], v[212:215], v[168:171], v[50:53]
	v_mfma_f32_16x16x32_bf16 v[42:45], v[220:223], v[168:171], v[42:45]
	v_mfma_f32_16x16x32_bf16 v[34:37], v[212:215], v[176:179], v[34:37]
	v_mfma_f32_16x16x32_bf16 v[24:27], v[220:223], v[176:179], v[24:27]
	v_mfma_f32_16x16x32_bf16 v[16:19], v[212:215], v[184:187], v[16:19]
	v_mfma_f32_16x16x32_bf16 v[8:11], v[220:223], v[184:187], v[8:11]
	v_mfma_f32_16x16x32_bf16 v[4:7], v[212:215], v[192:195], v[4:7]
	v_mfma_f32_16x16x32_bf16 v[0:3], v[220:223], v[192:195], v[0:3]
	s_add_i32 s49, 0, 0x18000
	v_add_u32_e32 v147, s49, v143
	s_barrier
	ds_read_b128 v[148:151], v147
	ds_read_b128 v[152:155], v147 offset:1024
	ds_read_b128 v[156:159], v147 offset:2048
	ds_read_b128 v[160:163], v147 offset:3072
	s_add_u32 s44, s44, 0x80000
	s_addc_u32 s45, s45, 0
	s_mov_b32 m0, s23
	v_lshl_add_u64 v[208:209], s[44:45], 0, v[32:33]
	ds_read_b128 v[164:167], v146 offset:32768
	ds_read_b128 v[168:171], v146 offset:33792
	ds_read_b128 v[172:175], v146 offset:34816
	ds_read_b128 v[176:179], v146 offset:35840
	ds_read_b128 v[180:183], v146 offset:36864
	ds_read_b128 v[184:187], v146 offset:37888
	ds_read_b128 v[188:191], v146 offset:38912
	ds_read_b128 v[192:195], v146 offset:39936
	global_load_lds_dwordx4 v[208:209], off
	v_lshl_add_u64 v[208:209], s[44:45], 0, v[132:133]
	s_mov_b32 m0, s25
	s_nop 0
	global_load_lds_dwordx4 v[208:209], off
	s_waitcnt lgkmcnt(8)
	s_barrier
	s_waitcnt lgkmcnt(0)
	s_waitcnt lgkmcnt(0)
	v_mfma_f32_16x16x32_bf16 v[126:129], v[148:151], v[164:167], v[126:129]
	v_mfma_f32_16x16x32_bf16 v[122:125], v[156:159], v[164:167], v[122:125]
	v_mfma_f32_16x16x32_bf16 v[114:117], v[148:151], v[172:175], v[114:117]
	v_mfma_f32_16x16x32_bf16 v[106:109], v[156:159], v[172:175], v[106:109]
	v_mfma_f32_16x16x32_bf16 v[98:101], v[148:151], v[180:183], v[98:101]
	v_mfma_f32_16x16x32_bf16 v[90:93], v[156:159], v[180:183], v[90:93]
	v_mfma_f32_16x16x32_bf16 v[82:85], v[148:151], v[188:191], v[82:85]
	v_mfma_f32_16x16x32_bf16 v[74:77], v[156:159], v[188:191], v[74:77]
	v_mfma_f32_16x16x32_bf16 v[126:129], v[152:155], v[168:171], v[126:129]
	v_mfma_f32_16x16x32_bf16 v[122:125], v[160:163], v[168:171], v[122:125]
	v_mfma_f32_16x16x32_bf16 v[114:117], v[152:155], v[176:179], v[114:117]
	v_mfma_f32_16x16x32_bf16 v[106:109], v[160:163], v[176:179], v[106:109]
	v_mfma_f32_16x16x32_bf16 v[98:101], v[152:155], v[184:187], v[98:101]
	v_mfma_f32_16x16x32_bf16 v[90:93], v[160:163], v[184:187], v[90:93]
	v_mfma_f32_16x16x32_bf16 v[82:85], v[152:155], v[192:195], v[82:85]
	v_mfma_f32_16x16x32_bf16 v[74:77], v[160:163], v[192:195], v[74:77]
	s_barrier
	s_add_i32 s50, 0, 0x1c000
	s_add_u32 s44, s42, 0x8000
	s_addc_u32 s45, s43, 0
	s_add_i32 s49, s49, s7
	v_add_u32_e32 v147, s50, v143
	v_lshl_add_u64 v[224:225], s[44:45], 0, v[130:131]
	s_mov_b32 m0, s49
	ds_read_b128 v[208:211], v147
	ds_read_b128 v[212:215], v147 offset:1024
	ds_read_b128 v[216:219], v147 offset:2048
	ds_read_b128 v[220:223], v147 offset:3072
	global_load_lds_dwordx4 v[224:225], off
	v_lshl_add_u64 v[224:225], s[44:45], 0, v[134:135]
	s_add_i32 m0, s49, 0x2000
	s_nop 0
	global_load_lds_dwordx4 v[224:225], off
	s_barrier
	s_waitcnt lgkmcnt(0)
	s_waitcnt lgkmcnt(0)
	v_mfma_f32_16x16x32_bf16 v[118:121], v[208:211], v[164:167], v[118:121]
	v_mfma_f32_16x16x32_bf16 v[110:113], v[216:219], v[164:167], v[110:113]
	v_mfma_f32_16x16x32_bf16 v[102:105], v[208:211], v[172:175], v[102:105]
	v_mfma_f32_16x16x32_bf16 v[94:97], v[216:219], v[172:175], v[94:97]
	v_mfma_f32_16x16x32_bf16 v[86:89], v[208:211], v[180:183], v[86:89]
	v_mfma_f32_16x16x32_bf16 v[78:81], v[216:219], v[180:183], v[78:81]
	v_mfma_f32_16x16x32_bf16 v[70:73], v[208:211], v[188:191], v[70:73]
	v_mfma_f32_16x16x32_bf16 v[66:69], v[216:219], v[188:191], v[66:69]
	v_mfma_f32_16x16x32_bf16 v[118:121], v[212:215], v[168:171], v[118:121]
	v_mfma_f32_16x16x32_bf16 v[110:113], v[220:223], v[168:171], v[110:113]
	v_mfma_f32_16x16x32_bf16 v[102:105], v[212:215], v[176:179], v[102:105]
	v_mfma_f32_16x16x32_bf16 v[94:97], v[220:223], v[176:179], v[94:97]
	v_mfma_f32_16x16x32_bf16 v[86:89], v[212:215], v[184:187], v[86:89]
	v_mfma_f32_16x16x32_bf16 v[78:81], v[220:223], v[184:187], v[78:81]
	v_mfma_f32_16x16x32_bf16 v[70:73], v[212:215], v[192:195], v[70:73]
	v_mfma_f32_16x16x32_bf16 v[66:69], v[220:223], v[192:195], v[66:69]
	s_mov_b32 m0, s31
	v_lshl_add_u64 v[140:141], v[140:141], 0, s[54:55]
	s_barrier
	ds_read_b128 v[164:167], v146 offset:49152
	ds_read_b128 v[168:171], v146 offset:50176
	ds_read_b128 v[172:175], v146 offset:51200
	ds_read_b128 v[176:179], v146 offset:52224
	ds_read_b128 v[180:183], v146 offset:53248
	ds_read_b128 v[184:187], v146 offset:54272
	ds_read_b128 v[188:191], v146 offset:55296
	ds_read_b128 v[192:195], v146 offset:56320
	global_load_lds_dwordx4 v[140:141], off
	v_lshl_add_u64 v[140:141], v[198:199], 0, s[54:55]
	s_mov_b32 m0, s56
	s_nop 0
	global_load_lds_dwordx4 v[140:141], off
	s_barrier
; #define PG8_STAGE(bufoff, gbase, voff) do { _Pragma("unroll") for (int _i = 0; _i < 2; ++_i) \
;     __builtin_amdgcn_global_load_lds((const unsigned*)((const char*)(gbase) + (voff)[_i]), (LAS unsigned*)(lds + (bufoff) + ldsw + _i * 8192), 16, 0, 0); } while (0)
; #define PG8_MMA(ai, bj, At, Bt) do { __builtin_amdgcn_s_setprio(1); _Pragma("unroll") for (int m = 0; m < 4; ++m) _Pragma("unroll") for (int n = 0; n < 2; ++n) _Pragma("unroll") for (int k = 0; k < 2; ++k) \
;     acc[ai][bj][m][n] = __builtin_amdgcn_mfma_f32_16x16x32_bf16(Bt[n][k], At[m][k], acc[ai][bj][m][n], 0, 0, 0); __builtin_amdgcn_s_setprio(0); } while (0)
; #define PG8_WAIT_V(n) asm volatile("s_waitcnt vmcnt(" #n ")" ::: "memory")
; #define PG8_WAIT_L(n) asm volatile("s_waitcnt lgkmcnt(" #n ")" ::: "memory")
; #define PG8_BAR __builtin_amdgcn_s_barrier()
; #define PG8_SCHED __builtin_amdgcn_sched_barrier(0)
; template <class Epi, class Sched, bool ABLK = false>
; __device__ __forceinline__ void gemm_phase(LAS unsigned char* lds, const Gemm g, const Sched& S, const Epi& E) {
;     ...
;       PG8_BAR; PG8_WAIT_L(0); PG8_MMA(1, 0, At, B0); PG8_BAR; PG8_SCHED;
;       PG8_STAGE(PG8_SB(1, 1), b3 + hstepB, voffB);
;       PG8_WAIT_V(6); PG8_BAR; PG8_MMA(1, 1, At, B1); PG8_BAR;
;     }
	s_waitcnt lgkmcnt(0)
	s_waitcnt lgkmcnt(0)
	v_mfma_f32_16x16x32_bf16 v[62:65], v[148:151], v[164:167], v[62:65]
	v_mfma_f32_16x16x32_bf16 v[58:61], v[156:159], v[164:167], v[58:61]
	v_mfma_f32_16x16x32_bf16 v[54:57], v[148:151], v[172:175], v[54:57]
	v_mfma_f32_16x16x32_bf16 v[46:49], v[156:159], v[172:175], v[46:49]
	v_mfma_f32_16x16x32_bf16 v[38:41], v[148:151], v[180:183], v[38:41]
	v_mfma_f32_16x16x32_bf16 v[28:31], v[156:159], v[180:183], v[28:31]
	v_mfma_f32_16x16x32_bf16 v[20:23], v[148:151], v[188:191], v[20:23]
	v_mfma_f32_16x16x32_bf16 v[12:15], v[156:159], v[188:191], v[12:15]
	v_mfma_f32_16x16x32_bf16 v[62:65], v[152:155], v[168:171], v[62:65]
	v_mfma_f32_16x16x32_bf16 v[58:61], v[160:163], v[168:171], v[58:61]
	v_mfma_f32_16x16x32_bf16 v[54:57], v[152:155], v[176:179], v[54:57]
	v_mfma_f32_16x16x32_bf16 v[46:49], v[160:163], v[176:179], v[46:49]
	v_mfma_f32_16x16x32_bf16 v[38:41], v[152:155], v[184:187], v[38:41]
	v_mfma_f32_16x16x32_bf16 v[28:31], v[160:163], v[184:187], v[28:31]
	v_mfma_f32_16x16x32_bf16 v[20:23], v[152:155], v[192:195], v[20:23]
	v_mfma_f32_16x16x32_bf16 v[12:15], v[160:163], v[192:195], v[12:15]
	s_barrier
	s_add_u32 s42, s42, 0xc000
	s_addc_u32 s43, s43, 0
	s_add_i32 s44, s50, s7
	v_lshl_add_u64 v[140:141], s[42:43], 0, v[130:131]
	s_mov_b32 m0, s44
	s_nop 0
	global_load_lds_dwordx4 v[140:141], off
	v_lshl_add_u64 v[140:141], s[42:43], 0, v[134:135]
	s_add_i32 m0, s44, 0x2000
	s_nop 0
	global_load_lds_dwordx4 v[140:141], off
	s_waitcnt vmcnt(6)
	s_barrier
	v_mfma_f32_16x16x32_bf16 v[50:53], v[208:211], v[164:167], v[50:53]
	v_mfma_f32_16x16x32_bf16 v[42:45], v[216:219], v[164:167], v[42:45]
	v_mfma_f32_16x16x32_bf16 v[34:37], v[208:211], v[172:175], v[34:37]
	v_mfma_f32_16x16x32_bf16 v[24:27], v[216:219], v[172:175], v[24:27]
	v_mfma_f32_16x16x32_bf16 v[16:19], v[208:211], v[180:183], v[16:19]
	v_mfma_f32_16x16x32_bf16 v[8:11], v[216:219], v[180:183], v[8:11]
	v_mfma_f32_16x16x32_bf16 v[4:7], v[208:211], v[188:191], v[4:7]
	v_mfma_f32_16x16x32_bf16 v[0:3], v[216:219], v[188:191], v[0:3]
	v_mfma_f32_16x16x32_bf16 v[50:53], v[212:215], v[168:171], v[50:53]
	v_mfma_f32_16x16x32_bf16 v[42:45], v[220:223], v[168:171], v[42:45]
	v_mfma_f32_16x16x32_bf16 v[34:37], v[212:215], v[176:179], v[34:37]
	v_mfma_f32_16x16x32_bf16 v[24:27], v[220:223], v[176:179], v[24:27]
	v_mfma_f32_16x16x32_bf16 v[16:19], v[212:215], v[184:187], v[16:19]
	v_mfma_f32_16x16x32_bf16 v[8:11], v[220:223], v[184:187], v[8:11]
	v_mfma_f32_16x16x32_bf16 v[4:7], v[212:215], v[192:195], v[4:7]
	v_mfma_f32_16x16x32_bf16 v[0:3], v[220:223], v[192:195], v[0:3]
	s_add_i32 s48, s48, 2
	s_add_u32 s46, s46, 0x10000
	s_addc_u32 s47, s47, 0
	s_add_u32 s38, s38, 0x100
	s_addc_u32 s39, s39, 0
	s_cmp_gt_u32 s48, 29
	s_barrier
	s_cbranch_scc0 .LBB0_178
; __device__ __forceinline__ unsigned cvt_pk_bf16(float lo, float hi) { unsigned r; asm volatile("v_cvt_pk_bf16_f32 %0, %1, %2" : "=v"(r) : "v"(lo), "v"(hi)); return r; }
; #define PG8_WAIT_V(n) asm volatile("s_waitcnt vmcnt(" #n ")" ::: "memory")
; #define PG8_BAR __builtin_amdgcn_s_barrier()
;   __device__ __forceinline__ float2 operator()(int i) const { const float2 wv = unpk2(Wd[i]); return half ? cmul(wv, twid((float)(i & (L - 1)) * invTurn)) : wv; }
; template <class Epi, class Sched, bool ABLK = false>
; __device__ __forceinline__ void gemm_phase(LAS unsigned char* lds, const Gemm g, const Sched& S, const Epi& E) {
;     ...
;     if (!has_next) break;
; #pragma unroll
;     for (int a = 0; a < 2; ++a)
; #pragma unroll
;       for (int b = 0; b < 2; ++b)
; #pragma unroll
;         for (int m = 0; m < 4; ++m)
; #pragma unroll
;           for (int n = 0; n < 2; ++n) acc[a][b][m][n] = (f32x4){0.f, 0.f, 0.f, 0.f};
;     cur = nxt; cA = nA; cB = nB; ++ui;
;   }
;   PG8_WAIT_V(0);
;   if (wr == 0) PG8_BAR;
;   PG8_BAR;
;   __device__ __forceinline__ void operator()(const f32x4 (&acc)[2][2][4][2], const Unit& u, int wr, int wc, int fr, int fq) const {
;     const int row0 = u.pm * BM + wr * 64 + fr, col0 = u.pn * BM + wc * 32 + 8 * fq;
; #pragma unroll
;     for (int ai = 0; ai < 2; ++ai)
; #pragma unroll
;       for (int m = 0; m < 4; ++m) { bf16_t* rowp = O + (size_t)(row0 + ai * HALF + m * 16) * ldc + col0;
; #pragma unroll
;         for (int bj = 0; bj < 2; ++bj) { const f32x4 v0 = acc[ai][bj][m][0], v1 = acc[ai][bj][m][1];
;           u32x4 w; w.x = cvt_pk_bf16(v0[0], v0[1]); w.y = cvt_pk_bf16(v0[2], v0[3]); w.z = cvt_pk_bf16(v1[0], v1[1]); w.w = cvt_pk_bf16(v1[2], v1[3]);
;           *(u32x4*)(rowp + bj * HALF) = w; } }
;   }
	v_lshl_add_u32 v148, s24, 8, v142
	v_lshl_or_b32 v140, s22, 8, v145
	v_ashrrev_i32_e32 v149, 31, v148
	v_readlane_b32 s38, v251, 14
	v_ashrrev_i32_e32 v141, 31, v140
	v_lshlrev_b64 v[150:151], 12, v[148:149]
	v_readlane_b32 s39, v251, 15
	v_lshlrev_b64 v[152:153], 1, v[140:141]
	v_cvt_pk_bf16_f32 v126, v126, v127
	v_cvt_pk_bf16_f32 v127, v128, v129
	v_cvt_pk_bf16_f32 v128, v122, v123
	v_cvt_pk_bf16_f32 v129, v124, v125
	s_nop 0
	v_lshl_add_u64 v[150:151], s[38:39], 0, v[150:151]
	v_lshl_add_u64 v[140:141], v[150:151], 0, v[152:153]
	global_store_dwordx4 v[140:141], v[126:129], off
	v_cvt_pk_bf16_f32 v118, v118, v119
	v_cvt_pk_bf16_f32 v119, v120, v121
	v_cvt_pk_bf16_f32 v120, v110, v111
	v_or_b32_e32 v110, 16, v148
	v_ashrrev_i32_e32 v111, 31, v110
	v_lshlrev_b64 v[110:111], 12, v[110:111]
	v_lshl_add_u64 v[110:111], s[38:39], 0, v[110:111]
	v_cvt_pk_bf16_f32 v121, v112, v113
	global_store_dwordx4 v[140:141], v[118:121], off offset:256
	s_mov_b32 s15, 0x80000
	s_mov_b32 s22, s14
	v_lshl_add_u64 v[118:119], v[110:111], 0, v[152:153]
	v_cvt_pk_bf16_f32 v110, v114, v115
	v_cvt_pk_bf16_f32 v111, v116, v117
	v_cvt_pk_bf16_f32 v112, v106, v107
	v_cvt_pk_bf16_f32 v113, v108, v109
	global_store_dwordx4 v[118:119], v[110:113], off
	v_cvt_pk_bf16_f32 v102, v102, v103
	v_cvt_pk_bf16_f32 v103, v104, v105
	v_cvt_pk_bf16_f32 v104, v94, v95
	v_or_b32_e32 v94, 32, v148
	v_ashrrev_i32_e32 v95, 31, v94
	v_lshlrev_b64 v[94:95], 12, v[94:95]
	v_lshl_add_u64 v[94:95], s[38:39], 0, v[94:95]
	v_cvt_pk_bf16_f32 v105, v96, v97
	global_store_dwordx4 v[118:119], v[102:105], off offset:256
	s_mov_b32 s24, s20
	s_mov_b64 s[42:43], s[28:29]
	v_lshl_add_u64 v[102:103], v[94:95], 0, v[152:153]
	v_cvt_pk_bf16_f32 v94, v98, v99
	v_cvt_pk_bf16_f32 v95, v100, v101
	v_cvt_pk_bf16_f32 v96, v90, v91
	v_cvt_pk_bf16_f32 v97, v92, v93
	global_store_dwordx4 v[102:103], v[94:97], off
	v_cvt_pk_bf16_f32 v86, v86, v87
	v_cvt_pk_bf16_f32 v87, v88, v89
	v_cvt_pk_bf16_f32 v88, v78, v79
	v_or_b32_e32 v78, 48, v148
	v_ashrrev_i32_e32 v79, 31, v78
	v_lshlrev_b64 v[78:79], 12, v[78:79]
	v_lshl_add_u64 v[78:79], s[38:39], 0, v[78:79]
	v_cvt_pk_bf16_f32 v89, v80, v81
	global_store_dwordx4 v[102:103], v[86:89], off offset:256
	s_mov_b64 s[38:39], 0x80000
	s_nop 0
	v_lshl_add_u64 v[86:87], v[78:79], 0, v[152:153]
	v_cvt_pk_bf16_f32 v78, v82, v83
	v_cvt_pk_bf16_f32 v79, v84, v85
	v_cvt_pk_bf16_f32 v80, v74, v75
	v_cvt_pk_bf16_f32 v81, v76, v77
	global_store_dwordx4 v[86:87], v[78:81], off
	v_cvt_pk_bf16_f32 v70, v70, v71
	v_cvt_pk_bf16_f32 v71, v72, v73
	v_cvt_pk_bf16_f32 v72, v66, v67
	v_cvt_pk_bf16_f32 v73, v68, v69
	global_store_dwordx4 v[86:87], v[70:73], off offset:256
	v_cvt_pk_bf16_f32 v62, v62, v63
	v_cvt_pk_bf16_f32 v63, v64, v65
	v_cvt_pk_bf16_f32 v64, v58, v59
	v_add_co_u32_e32 v58, vcc, s15, v140
	v_lshl_add_u64 v[66:67], v[140:141], 0, s[38:39]
	s_nop 0
	v_addc_co_u32_e32 v59, vcc, 0, v141, vcc
	s_mov_b32 s15, 0x90000
	v_cvt_pk_bf16_f32 v65, v60, v61
	global_store_dwordx4 v[58:59], v[62:65], off
	v_cvt_pk_bf16_f32 v50, v50, v51
	v_cvt_pk_bf16_f32 v51, v52, v53
	v_cvt_pk_bf16_f32 v52, v42, v43
	v_cvt_pk_bf16_f32 v53, v44, v45
	global_store_dwordx4 v[66:67], v[50:53], off offset:256
	s_mov_b64 s[38:39], 0x90000
	v_cvt_pk_bf16_f32 v42, v54, v55
	v_cvt_pk_bf16_f32 v43, v56, v57
	v_cvt_pk_bf16_f32 v44, v46, v47
	v_add_co_u32_e32 v46, vcc, s15, v140
	v_lshl_add_u64 v[50:51], v[140:141], 0, s[38:39]
	s_nop 0
	v_addc_co_u32_e32 v47, vcc, 0, v141, vcc
	s_mov_b32 s15, 0xa0000
	v_cvt_pk_bf16_f32 v45, v48, v49
	global_store_dwordx4 v[46:47], v[42:45], off
	v_cvt_pk_bf16_f32 v34, v34, v35
	v_cvt_pk_bf16_f32 v35, v36, v37
	v_cvt_pk_bf16_f32 v36, v24, v25
	v_cvt_pk_bf16_f32 v37, v26, v27
	global_store_dwordx4 v[50:51], v[34:37], off offset:256
	s_mov_b64 s[38:39], 0xa0000
	v_cvt_pk_bf16_f32 v24, v38, v39
	v_cvt_pk_bf16_f32 v25, v40, v41
	v_cvt_pk_bf16_f32 v26, v28, v29
	v_add_co_u32_e32 v28, vcc, s15, v140
	v_lshl_add_u64 v[34:35], v[140:141], 0, s[38:39]
	s_nop 0
	v_addc_co_u32_e32 v29, vcc, 0, v141, vcc
	s_mov_b32 s15, 0xb0000
	v_cvt_pk_bf16_f32 v27, v30, v31
	global_store_dwordx4 v[28:29], v[24:27], off
	v_cvt_pk_bf16_f32 v16, v16, v17
	v_cvt_pk_bf16_f32 v17, v18, v19
	v_cvt_pk_bf16_f32 v18, v8, v9
	v_cvt_pk_bf16_f32 v19, v10, v11
	global_store_dwordx4 v[34:35], v[16:19], off offset:256
	v_cvt_pk_bf16_f32 v8, v20, v21
	v_cvt_pk_bf16_f32 v9, v22, v23
	v_cvt_pk_bf16_f32 v10, v12, v13
	v_add_co_u32_e32 v12, vcc, s15, v140
	s_mov_b64 s[38:39], 0xb0000
	s_nop 0
	v_addc_co_u32_e32 v13, vcc, 0, v141, vcc
	v_lshl_add_u64 v[16:17], v[140:141], 0, s[38:39]
	s_and_b64 vcc, exec, s[26:27]
	s_mov_b64 s[38:39], s[36:37]
	v_cvt_pk_bf16_f32 v11, v14, v15
	global_store_dwordx4 v[12:13], v[8:11], off
	v_cvt_pk_bf16_f32 v4, v4, v5
	v_cvt_pk_bf16_f32 v5, v6, v7
	v_cvt_pk_bf16_f32 v6, v0, v1
	v_cvt_pk_bf16_f32 v7, v2, v3
	global_store_dwordx4 v[16:17], v[4:7], off offset:256
	s_cbranch_vccz .LBB0_143
	s_waitcnt vmcnt(0)
	s_cmpk_gt_u32 s5, 0xff
	v_mov_b32_e32 v131, v197
	s_cbranch_scc1 .LBB0_182
	s_barrier

; #define PG8_STAGE(bufoff, gbase, voff) do { _Pragma("unroll") for (int _i = 0; _i < 2; ++_i) \
;     __builtin_amdgcn_global_load_lds((const unsigned*)((const char*)(gbase) + (voff)[_i]), (LAS unsigned*)(lds + (bufoff) + ldsw + _i * 8192), 16, 0, 0); } while (0)
; #define PG8_LDA(dst, b, h) do { _Pragma("unroll") for (int m = 0; m < 4; ++m) _Pragma("unroll") for (int k = 0; k < 2; ++k) dst[m][k] = *(const LAS bf16x8*)(lds + PG8_SA(b, h) + aoff + m * 2048 + k * 1024); } while (0)
; #define PG8_LDB(dst, b, h) do { _Pragma("unroll") for (int n = 0; n < 2; ++n) _Pragma("unroll") for (int k = 0; k < 2; ++k) dst[n][k] = *(const LAS bf16x8*)(lds + PG8_SB(b, h) + boff + n * 2048 + k * 1024); } while (0)
; #define PG8_MMA(ai, bj, At, Bt) do { __builtin_amdgcn_s_setprio(1); _Pragma("unroll") for (int m = 0; m < 4; ++m) _Pragma("unroll") for (int n = 0; n < 2; ++n) _Pragma("unroll") for (int k = 0; k < 2; ++k) \
;     acc[ai][bj][m][n] = __builtin_amdgcn_mfma_f32_16x16x32_bf16(Bt[n][k], At[m][k], acc[ai][bj][m][n], 0, 0, 0); __builtin_amdgcn_s_setprio(0); } while (0)
; #define PG8_WAIT_L(n) asm volatile("s_waitcnt lgkmcnt(" #n ")" ::: "memory")
; #define PG8_BAR __builtin_amdgcn_s_barrier()
; #define PG8_SCHED __builtin_amdgcn_sched_barrier(0)
; template <class Epi, class Sched, bool ABLK = false>
; __device__ __forceinline__ void gemm_phase(LAS unsigned char* lds, const Gemm g, const Sched& S, const Epi& E) {
;     ...
;     for (int t = 0; t < nt; t += 2) {
;       const bool last = (t == nt - 2);
;       const char* a1 = cA + (size_t)(t + 1) * kstep;
;       const char* a2 = last ? nA : cA + (size_t)(t + 2) * kstep; const char* b2 = last ? nB : cB + (size_t)(t + 2) * kstepB;
;       const char* a3 = a2 + kstep; const char* b3 = b2 + kstepB;
;       PG8_LDB(B0, 0, 0); PG8_SCHED; PG8_LDA(At, 0, 0); PG8_STAGE(PG8_SA(1, 1), a1 + hstep, voffA);
;       PG8_WAIT_L(8); PG8_BAR; PG8_WAIT_L(0); PG8_MMA(0, 0, At, B0); PG8_BAR; PG8_SCHED;
;       PG8_LDB(B1, 0, 1); PG8_STAGE(PG8_SB(0, 0), b2, voffB);
;       PG8_BAR; PG8_WAIT_L(0); PG8_MMA(0, 1, At, B1); PG8_BAR;
;       PG8_LDA(At, 0, 1); PG8_STAGE(PG8_SA(0, 0), a2, voffA);
;       PG8_BAR; PG8_WAIT_L(0); PG8_MMA(1, 0, At, B0); PG8_BAR; PG8_SCHED;
.LBB0_256:
	s_add_u32 s42, s38, 0xfff80080
	s_addc_u32 s43, s39, -1
	s_add_i32 s49, 0, 0x10000
	v_add_u32_e32 v130, s49, v181
	ds_read_b128 v[106:109], v130
	ds_read_b128 v[110:113], v130 offset:1024
	ds_read_b128 v[126:129], v130 offset:2048
	ds_read_b128 v[130:133], v130 offset:3072
	s_cmp_eq_u32 s48, 28
	s_cselect_b32 s45, s27, s43
	s_cselect_b32 s44, s26, s42
	s_cselect_b32 s43, s21, s47
	s_cselect_b32 s42, s23, s46
	v_lshl_add_u64 v[178:179], s[38:39], 0, v[170:171]
	s_add_i32 m0, s11, 0xc000
	ds_read_b128 v[138:141], v184
	ds_read_b128 v[142:145], v184 offset:1024
	ds_read_b128 v[154:157], v184 offset:2048
	ds_read_b128 v[158:161], v184 offset:3072
	ds_read_b128 v[174:177], v184 offset:4096
	ds_read_b128 v[186:189], v184 offset:5120
	ds_read_b128 v[190:193], v184 offset:6144
	ds_read_b128 v[208:211], v184 offset:7168
	global_load_lds_dwordx4 v[178:179], off
	v_lshl_add_u64 v[178:179], s[38:39], 0, v[172:173]
	s_add_i32 m0, s11, 0xe000
	s_nop 0
	global_load_lds_dwordx4 v[178:179], off
	s_waitcnt lgkmcnt(8)
	s_barrier
	s_waitcnt lgkmcnt(0)
	s_waitcnt lgkmcnt(0)
	v_mfma_f32_16x16x32_bf16 v[150:153], v[106:109], v[138:141], v[150:153]
	v_mfma_f32_16x16x32_bf16 v[134:137], v[126:129], v[138:141], v[134:137]
	v_mfma_f32_16x16x32_bf16 v[118:121], v[106:109], v[154:157], v[118:121]
	v_mfma_f32_16x16x32_bf16 v[102:105], v[126:129], v[154:157], v[102:105]
	v_mfma_f32_16x16x32_bf16 v[94:97], v[106:109], v[174:177], v[94:97]
	v_mfma_f32_16x16x32_bf16 v[86:89], v[126:129], v[174:177], v[86:89]
	v_mfma_f32_16x16x32_bf16 v[78:81], v[106:109], v[190:193], v[78:81]
	v_mfma_f32_16x16x32_bf16 v[70:73], v[126:129], v[190:193], v[70:73]
	v_mfma_f32_16x16x32_bf16 v[150:153], v[110:113], v[142:145], v[150:153]
	v_mfma_f32_16x16x32_bf16 v[134:137], v[130:133], v[142:145], v[134:137]
	v_mfma_f32_16x16x32_bf16 v[118:121], v[110:113], v[158:161], v[118:121]
	v_mfma_f32_16x16x32_bf16 v[102:105], v[130:133], v[158:161], v[102:105]
	v_mfma_f32_16x16x32_bf16 v[94:97], v[110:113], v[186:189], v[94:97]
	v_mfma_f32_16x16x32_bf16 v[86:89], v[130:133], v[186:189], v[86:89]
	v_mfma_f32_16x16x32_bf16 v[78:81], v[110:113], v[208:211], v[78:81]
	v_mfma_f32_16x16x32_bf16 v[70:73], v[130:133], v[208:211], v[70:73]
	s_barrier
	s_add_i32 s52, 0, 0x14000
	v_add_u32_e32 v178, s52, v181
	s_add_i32 s49, s49, s7
	ds_read_b128 v[212:215], v178
	ds_read_b128 v[216:219], v178 offset:1024
	ds_read_b128 v[220:223], v178 offset:2048
	ds_read_b128 v[224:227], v178 offset:3072
	v_lshl_add_u64 v[178:179], s[42:43], 0, v[162:163]
	s_mov_b32 m0, s49
	s_nop 0
	global_load_lds_dwordx4 v[178:179], off
	v_lshl_add_u64 v[178:179], s[42:43], 0, v[166:167]
	s_add_i32 m0, s49, 0x2000
	s_nop 0
	global_load_lds_dwordx4 v[178:179], off
	s_barrier
	s_waitcnt lgkmcnt(0)
	s_waitcnt lgkmcnt(0)
	v_mfma_f32_16x16x32_bf16 v[146:149], v[212:215], v[138:141], v[146:149]
	v_mfma_f32_16x16x32_bf16 v[122:125], v[220:223], v[138:141], v[122:125]
	v_mfma_f32_16x16x32_bf16 v[114:117], v[212:215], v[154:157], v[114:117]
	v_mfma_f32_16x16x32_bf16 v[98:101], v[220:223], v[154:157], v[98:101]
	v_mfma_f32_16x16x32_bf16 v[90:93], v[212:215], v[174:177], v[90:93]
	v_mfma_f32_16x16x32_bf16 v[82:85], v[220:223], v[174:177], v[82:85]
	v_mfma_f32_16x16x32_bf16 v[74:77], v[212:215], v[190:193], v[74:77]
	v_mfma_f32_16x16x32_bf16 v[66:69], v[220:223], v[190:193], v[66:69]
	v_mfma_f32_16x16x32_bf16 v[146:149], v[216:219], v[142:145], v[146:149]
	v_mfma_f32_16x16x32_bf16 v[122:125], v[224:227], v[142:145], v[122:125]
	v_mfma_f32_16x16x32_bf16 v[114:117], v[216:219], v[158:161], v[114:117]
	v_mfma_f32_16x16x32_bf16 v[98:101], v[224:227], v[158:161], v[98:101]
	v_mfma_f32_16x16x32_bf16 v[90:93], v[216:219], v[186:189], v[90:93]
	v_mfma_f32_16x16x32_bf16 v[82:85], v[224:227], v[186:189], v[82:85]
	v_mfma_f32_16x16x32_bf16 v[74:77], v[216:219], v[208:211], v[74:77]
	v_mfma_f32_16x16x32_bf16 v[66:69], v[224:227], v[208:211], v[66:69]
	s_mov_b32 m0, s11
	v_lshl_add_u64 v[178:179], s[44:45], 0, v[32:33]
	s_barrier
	ds_read_b128 v[138:141], v184 offset:16384
	ds_read_b128 v[142:145], v184 offset:17408
	ds_read_b128 v[154:157], v184 offset:18432
	ds_read_b128 v[158:161], v184 offset:19456
	ds_read_b128 v[174:177], v184 offset:20480
	ds_read_b128 v[186:189], v184 offset:21504
	ds_read_b128 v[190:193], v184 offset:22528
	ds_read_b128 v[208:211], v184 offset:23552
	global_load_lds_dwordx4 v[178:179], off
	v_lshl_add_u64 v[194:195], s[44:45], 0, v[164:165]
	s_mov_b32 m0, s15
	s_nop 0
	global_load_lds_dwordx4 v[194:195], off
	s_barrier
	s_waitcnt lgkmcnt(0)
	s_waitcnt lgkmcnt(0)
	v_mfma_f32_16x16x32_bf16 v[62:65], v[106:109], v[138:141], v[62:65]
	v_mfma_f32_16x16x32_bf16 v[54:57], v[126:129], v[138:141], v[54:57]
	v_mfma_f32_16x16x32_bf16 v[46:49], v[106:109], v[154:157], v[46:49]
	v_mfma_f32_16x16x32_bf16 v[38:41], v[126:129], v[154:157], v[38:41]
	v_mfma_f32_16x16x32_bf16 v[28:31], v[106:109], v[174:177], v[28:31]
	v_mfma_f32_16x16x32_bf16 v[20:23], v[126:129], v[174:177], v[20:23]
	v_mfma_f32_16x16x32_bf16 v[12:15], v[106:109], v[190:193], v[12:15]
	v_mfma_f32_16x16x32_bf16 v[4:7], v[126:129], v[190:193], v[4:7]
	v_mfma_f32_16x16x32_bf16 v[62:65], v[110:113], v[142:145], v[62:65]
	v_mfma_f32_16x16x32_bf16 v[54:57], v[130:133], v[142:145], v[54:57]
	v_mfma_f32_16x16x32_bf16 v[46:49], v[110:113], v[158:161], v[46:49]
	v_mfma_f32_16x16x32_bf16 v[38:41], v[130:133], v[158:161], v[38:41]
	v_mfma_f32_16x16x32_bf16 v[28:31], v[110:113], v[186:189], v[28:31]
	v_mfma_f32_16x16x32_bf16 v[20:23], v[130:133], v[186:189], v[20:23]
	v_mfma_f32_16x16x32_bf16 v[12:15], v[110:113], v[208:211], v[12:15]
	v_mfma_f32_16x16x32_bf16 v[4:7], v[130:133], v[208:211], v[4:7]
	s_barrier
; #define PG8_STAGE(bufoff, gbase, voff) do { _Pragma("unroll") for (int _i = 0; _i < 2; ++_i) \
;     __builtin_amdgcn_global_load_lds((const unsigned*)((const char*)(gbase) + (voff)[_i]), (LAS unsigned*)(lds + (bufoff) + ldsw + _i * 8192), 16, 0, 0); } while (0)
; #define PG8_LDA(dst, b, h) do { _Pragma("unroll") for (int m = 0; m < 4; ++m) _Pragma("unroll") for (int k = 0; k < 2; ++k) dst[m][k] = *(const LAS bf16x8*)(lds + PG8_SA(b, h) + aoff + m * 2048 + k * 1024); } while (0)
; #define PG8_LDB(dst, b, h) do { _Pragma("unroll") for (int n = 0; n < 2; ++n) _Pragma("unroll") for (int k = 0; k < 2; ++k) dst[n][k] = *(const LAS bf16x8*)(lds + PG8_SB(b, h) + boff + n * 2048 + k * 1024); } while (0)
; #define PG8_MMA(ai, bj, At, Bt) do { __builtin_amdgcn_s_setprio(1); _Pragma("unroll") for (int m = 0; m < 4; ++m) _Pragma("unroll") for (int n = 0; n < 2; ++n) _Pragma("unroll") for (int k = 0; k < 2; ++k) \
;     acc[ai][bj][m][n] = __builtin_amdgcn_mfma_f32_16x16x32_bf16(Bt[n][k], At[m][k], acc[ai][bj][m][n], 0, 0, 0); __builtin_amdgcn_s_setprio(0); } while (0)
; #define PG8_WAIT_V(n) asm volatile("s_waitcnt vmcnt(" #n ")" ::: "memory")
; #define PG8_WAIT_L(n) asm volatile("s_waitcnt lgkmcnt(" #n ")" ::: "memory")
; #define PG8_BAR __builtin_amdgcn_s_barrier()
; #define PG8_SCHED __builtin_amdgcn_sched_barrier(0)
; template <class Epi, class Sched, bool ABLK = false>
; __device__ __forceinline__ void gemm_phase(LAS unsigned char* lds, const Gemm g, const Sched& S, const Epi& E) {
;     ...
;       PG8_STAGE(PG8_SB(0, 1), b2 + hstepB, voffB);
;       PG8_WAIT_V(6); PG8_BAR; PG8_MMA(1, 1, At, B1); PG8_BAR;
;       PG8_LDB(B0, 1, 0); PG8_SCHED; PG8_LDA(At, 1, 0); PG8_STAGE(PG8_SA(0, 1), a2 + hstep, voffA);
;       PG8_WAIT_L(8); PG8_BAR; PG8_WAIT_L(0); PG8_MMA(0, 0, At, B0); PG8_BAR; PG8_SCHED;
;       PG8_LDB(B1, 1, 1); PG8_STAGE(PG8_SB(1, 0), b3, voffB);
;       PG8_BAR; PG8_WAIT_L(0); PG8_MMA(0, 1, At, B1); PG8_BAR;
;       PG8_LDA(At, 1, 1); PG8_STAGE(PG8_SA(1, 0), a3, voffA);
	s_add_u32 s50, s42, 0x4000
	s_addc_u32 s51, s43, 0
	s_add_i32 s49, s52, s7
	v_lshl_add_u64 v[106:107], s[50:51], 0, v[162:163]
	s_mov_b32 m0, s49
	s_nop 0
	global_load_lds_dwordx4 v[106:107], off
	v_lshl_add_u64 v[106:107], s[50:51], 0, v[166:167]
	s_add_i32 m0, s49, 0x2000
	s_nop 0
	global_load_lds_dwordx4 v[106:107], off
	s_waitcnt vmcnt(6)
	s_barrier
	v_mfma_f32_16x16x32_bf16 v[58:61], v[212:215], v[138:141], v[58:61]
	v_mfma_f32_16x16x32_bf16 v[50:53], v[220:223], v[138:141], v[50:53]
	v_mfma_f32_16x16x32_bf16 v[42:45], v[212:215], v[154:157], v[42:45]
	v_mfma_f32_16x16x32_bf16 v[34:37], v[220:223], v[154:157], v[34:37]
	v_mfma_f32_16x16x32_bf16 v[24:27], v[212:215], v[174:177], v[24:27]
	v_mfma_f32_16x16x32_bf16 v[16:19], v[220:223], v[174:177], v[16:19]
	v_mfma_f32_16x16x32_bf16 v[8:11], v[212:215], v[190:193], v[8:11]
	v_mfma_f32_16x16x32_bf16 v[0:3], v[220:223], v[190:193], v[0:3]
	v_mfma_f32_16x16x32_bf16 v[58:61], v[216:219], v[142:145], v[58:61]
	v_mfma_f32_16x16x32_bf16 v[50:53], v[224:227], v[142:145], v[50:53]
	v_mfma_f32_16x16x32_bf16 v[42:45], v[216:219], v[158:161], v[42:45]
	v_mfma_f32_16x16x32_bf16 v[34:37], v[224:227], v[158:161], v[34:37]
	v_mfma_f32_16x16x32_bf16 v[24:27], v[216:219], v[186:189], v[24:27]
	v_mfma_f32_16x16x32_bf16 v[16:19], v[224:227], v[186:189], v[16:19]
	v_mfma_f32_16x16x32_bf16 v[8:11], v[216:219], v[208:211], v[8:11]
	v_mfma_f32_16x16x32_bf16 v[0:3], v[224:227], v[208:211], v[0:3]
	s_add_i32 s49, 0, 0x18000
	v_add_u32_e32 v130, s49, v181
	s_barrier
	ds_read_b128 v[106:109], v130
	ds_read_b128 v[110:113], v130 offset:1024
	ds_read_b128 v[126:129], v130 offset:2048
	ds_read_b128 v[130:133], v130 offset:3072
	s_add_u32 s44, s44, 0x80000
	s_addc_u32 s45, s45, 0
	s_mov_b32 m0, s17
	v_lshl_add_u64 v[198:199], s[44:45], 0, v[32:33]
	ds_read_b128 v[138:141], v184 offset:32768
	ds_read_b128 v[142:145], v184 offset:33792
	ds_read_b128 v[154:157], v184 offset:34816
	ds_read_b128 v[158:161], v184 offset:35840
	ds_read_b128 v[174:177], v184 offset:36864
	ds_read_b128 v[186:189], v184 offset:37888
	ds_read_b128 v[190:193], v184 offset:38912
	ds_read_b128 v[208:211], v184 offset:39936
	global_load_lds_dwordx4 v[198:199], off
	v_lshl_add_u64 v[198:199], s[44:45], 0, v[164:165]
	s_mov_b32 m0, s31
	s_nop 0
	global_load_lds_dwordx4 v[198:199], off
	s_waitcnt lgkmcnt(8)
	s_barrier
	s_waitcnt lgkmcnt(0)
	s_waitcnt lgkmcnt(0)
	v_mfma_f32_16x16x32_bf16 v[150:153], v[106:109], v[138:141], v[150:153]
	v_mfma_f32_16x16x32_bf16 v[134:137], v[126:129], v[138:141], v[134:137]
	v_mfma_f32_16x16x32_bf16 v[118:121], v[106:109], v[154:157], v[118:121]
	v_mfma_f32_16x16x32_bf16 v[102:105], v[126:129], v[154:157], v[102:105]
	v_mfma_f32_16x16x32_bf16 v[94:97], v[106:109], v[174:177], v[94:97]
	v_mfma_f32_16x16x32_bf16 v[86:89], v[126:129], v[174:177], v[86:89]
	v_mfma_f32_16x16x32_bf16 v[78:81], v[106:109], v[190:193], v[78:81]
	v_mfma_f32_16x16x32_bf16 v[70:73], v[126:129], v[190:193], v[70:73]
	v_mfma_f32_16x16x32_bf16 v[150:153], v[110:113], v[142:145], v[150:153]
	v_mfma_f32_16x16x32_bf16 v[134:137], v[130:133], v[142:145], v[134:137]
	v_mfma_f32_16x16x32_bf16 v[118:121], v[110:113], v[158:161], v[118:121]
	v_mfma_f32_16x16x32_bf16 v[102:105], v[130:133], v[158:161], v[102:105]
	v_mfma_f32_16x16x32_bf16 v[94:97], v[110:113], v[186:189], v[94:97]
	v_mfma_f32_16x16x32_bf16 v[86:89], v[130:133], v[186:189], v[86:89]
	v_mfma_f32_16x16x32_bf16 v[78:81], v[110:113], v[208:211], v[78:81]
	v_mfma_f32_16x16x32_bf16 v[70:73], v[130:133], v[208:211], v[70:73]
	s_barrier
	s_add_i32 s50, 0, 0x1c000
	s_add_u32 s44, s42, 0x8000
	s_addc_u32 s45, s43, 0
	s_add_i32 s49, s49, s7
	v_add_u32_e32 v185, s50, v181
	v_lshl_add_u64 v[198:199], s[44:45], 0, v[162:163]
	s_mov_b32 m0, s49
	ds_read_b128 v[212:215], v185
	ds_read_b128 v[216:219], v185 offset:1024
	ds_read_b128 v[220:223], v185 offset:2048
	ds_read_b128 v[224:227], v185 offset:3072
	global_load_lds_dwordx4 v[198:199], off
	v_lshl_add_u64 v[198:199], s[44:45], 0, v[166:167]
	s_add_i32 m0, s49, 0x2000
	s_nop 0
	global_load_lds_dwordx4 v[198:199], off
	s_barrier
	s_waitcnt lgkmcnt(0)
	s_waitcnt lgkmcnt(0)
	v_mfma_f32_16x16x32_bf16 v[146:149], v[212:215], v[138:141], v[146:149]
	v_mfma_f32_16x16x32_bf16 v[122:125], v[220:223], v[138:141], v[122:125]
	v_mfma_f32_16x16x32_bf16 v[114:117], v[212:215], v[154:157], v[114:117]
	v_mfma_f32_16x16x32_bf16 v[98:101], v[220:223], v[154:157], v[98:101]
	v_mfma_f32_16x16x32_bf16 v[90:93], v[212:215], v[174:177], v[90:93]
	v_mfma_f32_16x16x32_bf16 v[82:85], v[220:223], v[174:177], v[82:85]
	v_mfma_f32_16x16x32_bf16 v[74:77], v[212:215], v[190:193], v[74:77]
	v_mfma_f32_16x16x32_bf16 v[66:69], v[220:223], v[190:193], v[66:69]
	v_mfma_f32_16x16x32_bf16 v[146:149], v[216:219], v[142:145], v[146:149]
	v_mfma_f32_16x16x32_bf16 v[122:125], v[224:227], v[142:145], v[122:125]
	v_mfma_f32_16x16x32_bf16 v[114:117], v[216:219], v[158:161], v[114:117]
	v_mfma_f32_16x16x32_bf16 v[98:101], v[224:227], v[158:161], v[98:101]
	v_mfma_f32_16x16x32_bf16 v[90:93], v[216:219], v[186:189], v[90:93]
	v_mfma_f32_16x16x32_bf16 v[82:85], v[224:227], v[186:189], v[82:85]
	v_mfma_f32_16x16x32_bf16 v[74:77], v[216:219], v[208:211], v[74:77]
	v_mfma_f32_16x16x32_bf16 v[66:69], v[224:227], v[208:211], v[66:69]
	s_mov_b32 m0, s37
	v_lshl_add_u64 v[178:179], v[178:179], 0, s[54:55]
	s_barrier
	ds_read_b128 v[138:141], v184 offset:49152
	ds_read_b128 v[142:145], v184 offset:50176
	ds_read_b128 v[154:157], v184 offset:51200
	ds_read_b128 v[158:161], v184 offset:52224
	ds_read_b128 v[174:177], v184 offset:53248
	ds_read_b128 v[186:189], v184 offset:54272
	ds_read_b128 v[190:193], v184 offset:55296
	ds_read_b128 v[208:211], v184 offset:56320
	global_load_lds_dwordx4 v[178:179], off
	v_lshl_add_u64 v[178:179], v[194:195], 0, s[54:55]
	s_mov_b32 m0, s56
	s_nop 0
	global_load_lds_dwordx4 v[178:179], off
	s_barrier
; __device__ __forceinline__ float bflo(unsigned w) { return __uint_as_float(w << 16); }
; __device__ __forceinline__ float bfhi(unsigned w) { return __uint_as_float(w & 0xffff0000u); }
; __device__ __forceinline__ float sigmoidf_(float x) { return __builtin_amdgcn_rcpf(1.0f + __expf(-x)); }
; #define PG8_STAGE(bufoff, gbase, voff) do { _Pragma("unroll") for (int _i = 0; _i < 2; ++_i) \
;     __builtin_amdgcn_global_load_lds((const unsigned*)((const char*)(gbase) + (voff)[_i]), (LAS unsigned*)(lds + (bufoff) + ldsw + _i * 8192), 16, 0, 0); } while (0)
; #define PG8_WAIT_V(n) asm volatile("s_waitcnt vmcnt(" #n ")" ::: "memory")
; #define PG8_WAIT_L(n) asm volatile("s_waitcnt lgkmcnt(" #n ")" ::: "memory")
; #define PG8_BAR __builtin_amdgcn_s_barrier()
; #define PG8_SCHED __builtin_amdgcn_sched_barrier(0)
; template <class Epi, class Sched, bool ABLK = false>
; __device__ __forceinline__ void gemm_phase(LAS unsigned char* lds, const Gemm g, const Sched& S, const Epi& E) {
;     ...
;       PG8_BAR; PG8_WAIT_L(0); PG8_MMA(1, 0, At, B0); PG8_BAR; PG8_SCHED;
;       PG8_STAGE(PG8_SB(1, 1), b3 + hstepB, voffB);
;       PG8_WAIT_V(6); PG8_BAR; PG8_MMA(1, 1, At, B1); PG8_BAR;
;     }
;   __device__ __forceinline__ void operator()(const f32x4 (&acc)[2][2][4][2], const Unit& u, int wr, int wc, int fr, int fq) const {
;     const int row0 = u.pm * BM + wr * 64 + fr, col0 = u.pn * HALF + wc * 32 + 8 * fq;
; #pragma unroll
;     for (int ai = 0; ai < 2; ++ai) {
;       u32x4 av[4], bv[4];
;       const int wave = wr * 4 + wc, lane = fq * 16 + fr;
; #pragma unroll
;       for (int m = 0; m < 4; ++m) { const size_t idx = ((((size_t)(u.pm * 16 + u.pn) * 2 + ai) * 4 + m) * 8 + wave) * 64 + lane; av[m] = *(const u32x4*)(Aa + idx * 8); bv[m] = *(const u32x4*)(Bb + idx * 8); }
; #pragma unroll
;       for (int m = 0; m < 4; ++m) {
;         const size_t off = (size_t)(row0 + ai * HALF + m * 16) * DM + col0;
;         float o[8];
; #pragma unroll
;         for (int n = 0; n < 2; ++n)
; #pragma unroll
;           for (int j = 0; j < 4; ++j) {
;             const int e = n * 4 + j; const unsigned aw = av[m][e >> 1], bw = bv[m][e >> 1];
;             const float a = (e & 1) ? bfhi(aw) : bflo(aw), b = (e & 1) ? bfhi(bw) : bflo(bw);
;             o[e] = sigmoidf_(acc[ai][0][m][n][j]) * a + sigmoidf_(acc[ai][1][m][n][j]) * b; }
	s_waitcnt lgkmcnt(0)
	s_waitcnt lgkmcnt(0)
	v_mfma_f32_16x16x32_bf16 v[62:65], v[106:109], v[138:141], v[62:65]
	v_mfma_f32_16x16x32_bf16 v[54:57], v[126:129], v[138:141], v[54:57]
	v_mfma_f32_16x16x32_bf16 v[46:49], v[106:109], v[154:157], v[46:49]
	v_mfma_f32_16x16x32_bf16 v[38:41], v[126:129], v[154:157], v[38:41]
	v_mfma_f32_16x16x32_bf16 v[28:31], v[106:109], v[174:177], v[28:31]
	v_mfma_f32_16x16x32_bf16 v[20:23], v[126:129], v[174:177], v[20:23]
	v_mfma_f32_16x16x32_bf16 v[12:15], v[106:109], v[190:193], v[12:15]
	v_mfma_f32_16x16x32_bf16 v[4:7], v[126:129], v[190:193], v[4:7]
	v_mfma_f32_16x16x32_bf16 v[62:65], v[110:113], v[142:145], v[62:65]
	v_mfma_f32_16x16x32_bf16 v[54:57], v[130:133], v[142:145], v[54:57]
	v_mfma_f32_16x16x32_bf16 v[46:49], v[110:113], v[158:161], v[46:49]
	v_mfma_f32_16x16x32_bf16 v[38:41], v[130:133], v[158:161], v[38:41]
	v_mfma_f32_16x16x32_bf16 v[28:31], v[110:113], v[186:189], v[28:31]
	v_mfma_f32_16x16x32_bf16 v[20:23], v[130:133], v[186:189], v[20:23]
	v_mfma_f32_16x16x32_bf16 v[12:15], v[110:113], v[208:211], v[12:15]
	v_mfma_f32_16x16x32_bf16 v[4:7], v[130:133], v[208:211], v[4:7]
	s_barrier
	s_add_u32 s42, s42, 0xc000
	s_addc_u32 s43, s43, 0
	s_add_i32 s44, s50, s7
	v_lshl_add_u64 v[106:107], s[42:43], 0, v[162:163]
	s_mov_b32 m0, s44
	s_nop 0
	global_load_lds_dwordx4 v[106:107], off
	v_lshl_add_u64 v[106:107], s[42:43], 0, v[166:167]
	s_add_i32 m0, s44, 0x2000
	s_nop 0
	global_load_lds_dwordx4 v[106:107], off
	s_waitcnt vmcnt(6)
	s_barrier
	v_mfma_f32_16x16x32_bf16 v[58:61], v[212:215], v[138:141], v[58:61]
	v_mfma_f32_16x16x32_bf16 v[50:53], v[220:223], v[138:141], v[50:53]
	v_mfma_f32_16x16x32_bf16 v[42:45], v[212:215], v[154:157], v[42:45]
	v_mfma_f32_16x16x32_bf16 v[34:37], v[220:223], v[154:157], v[34:37]
	v_mfma_f32_16x16x32_bf16 v[24:27], v[212:215], v[174:177], v[24:27]
	v_mfma_f32_16x16x32_bf16 v[16:19], v[220:223], v[174:177], v[16:19]
	v_mfma_f32_16x16x32_bf16 v[8:11], v[212:215], v[190:193], v[8:11]
	v_mfma_f32_16x16x32_bf16 v[0:3], v[220:223], v[190:193], v[0:3]
	v_mfma_f32_16x16x32_bf16 v[58:61], v[216:219], v[142:145], v[58:61]
	v_mfma_f32_16x16x32_bf16 v[50:53], v[224:227], v[142:145], v[50:53]
	v_mfma_f32_16x16x32_bf16 v[42:45], v[216:219], v[158:161], v[42:45]
	v_mfma_f32_16x16x32_bf16 v[34:37], v[224:227], v[158:161], v[34:37]
	v_mfma_f32_16x16x32_bf16 v[24:27], v[216:219], v[186:189], v[24:27]
	v_mfma_f32_16x16x32_bf16 v[16:19], v[224:227], v[186:189], v[16:19]
	v_mfma_f32_16x16x32_bf16 v[8:11], v[216:219], v[208:211], v[8:11]
	v_mfma_f32_16x16x32_bf16 v[0:3], v[224:227], v[208:211], v[0:3]
	s_add_i32 s48, s48, 2
	s_add_u32 s46, s46, 0x10000
	s_addc_u32 s47, s47, 0
	s_add_u32 s38, s38, 0x100
	s_addc_u32 s39, s39, 0
	s_cmp_gt_u32 s48, 29
	s_barrier
	s_cbranch_scc0 .LBB0_256
	s_lshl_b32 s21, s36, 4
	s_add_i32 s38, s21, s14
	s_ashr_i32 s39, s38, 31
	s_lshl_b64 s[38:39], s[38:39], 15
	v_lshl_add_u64 v[106:107], s[38:39], 0, v[168:169]
	v_readlane_b32 s42, v252, 36
	v_lshlrev_b64 v[174:175], 1, v[106:107]
	v_readlane_b32 s43, v252, 37
	v_readlane_b32 s52, v252, 38
	v_readlane_b32 s53, v252, 39
	v_lshl_add_u64 v[106:107], s[42:43], 0, v[174:175]
	global_load_dwordx4 v[154:157], v[106:107], off
	v_lshl_add_u64 v[106:107], s[52:53], 0, v[174:175]
	global_load_dwordx4 v[158:161], v[106:107], off
	v_mul_f32_e32 v150, 0xbfb8aa3b, v150
	v_exp_f32_e32 v150, v150
	s_mov_b64 s[38:39], 0x2000
	v_lshl_add_u64 v[106:107], v[174:175], 0, s[38:39]
	v_lshl_add_u64 v[108:109], s[42:43], 0, v[106:107]
	v_lshl_add_u64 v[106:107], s[52:53], 0, v[106:107]
	v_mul_f32_e32 v146, 0xbfb8aa3b, v146
	global_load_dwordx4 v[138:141], v[108:109], off
	global_load_dwordx4 v[142:145], v[106:107], off
	v_add_f32_e32 v150, 1.0, v150
	v_exp_f32_e32 v146, v146
	v_rcp_f32_e32 v186, v150
	v_mul_f32_e32 v150, 0xbfb8aa3b, v151
	v_mul_f32_e32 v147, 0xbfb8aa3b, v147
	v_exp_f32_e32 v150, v150
	v_exp_f32_e32 v147, v147
	v_add_f32_e32 v146, 1.0, v146
	v_rcp_f32_e32 v187, v146
	v_add_f32_e32 v150, 1.0, v150
	v_add_f32_e32 v147, 1.0, v147
	v_rcp_f32_e32 v150, v150
	v_rcp_f32_e32 v151, v147
	v_mul_f32_e32 v148, 0xbfb8aa3b, v148
	v_exp_f32_e32 v148, v148
	v_mul_f32_e32 v149, 0xbfb8aa3b, v149
	v_exp_f32_e32 v149, v149
	v_mul_f32_e32 v122, 0xbfb8aa3b, v122
	v_add_f32_e32 v148, 1.0, v148
	v_exp_f32_e32 v122, v122
	v_add_f32_e32 v149, 1.0, v149
	v_mul_f32_e32 v134, 0xbfb8aa3b, v134
	v_mul_f32_e32 v123, 0xbfb8aa3b, v123
	v_add_f32_e32 v122, 1.0, v122
	v_exp_f32_e32 v134, v134
	v_exp_f32_e32 v123, v123
	s_mov_b64 s[38:39], 0x4000
	v_lshl_add_u64 v[106:107], v[174:175], 0, s[38:39]
	v_add_f32_e32 v134, 1.0, v134
	v_add_f32_e32 v123, 1.0, v123
	v_rcp_f32_e32 v123, v123
	s_mov_b64 s[38:39], 0x6000
	v_mul_f32_e32 v114, 0xbfb8aa3b, v114
	v_lshl_add_u32 v176, s36, 8, v180
	v_lshl_add_u64 v[108:109], s[42:43], 0, v[106:107]
	v_lshl_add_u64 v[106:107], s[52:53], 0, v[106:107]
	v_lshl_add_u64 v[110:111], v[174:175], 0, s[38:39]
	v_exp_f32_e32 v114, v114
	v_lshl_or_b32 v178, s14, 7, v182
	global_load_dwordx4 v[126:129], v[108:109], off
	global_load_dwordx4 v[130:133], v[106:107], off
	v_lshl_add_u64 v[106:107], s[42:43], 0, v[110:111]
	v_lshl_add_u64 v[110:111], s[52:53], 0, v[110:111]
	v_ashrrev_i32_e32 v177, 31, v176
	v_readlane_b32 s44, v255, 25
	v_ashrrev_i32_e32 v179, 31, v178
	global_load_dwordx4 v[106:109], v[106:107], off
	v_readlane_b32 s46, v255, 27
	global_load_dwordx4 v[110:113], v[110:111], off
	v_readlane_b32 s47, v255, 28
	v_add_f32_e32 v114, 1.0, v114
	v_mul_f32_e32 v118, 0xbfb8aa3b, v118
	v_mul_f32_e32 v115, 0xbfb8aa3b, v115
	v_exp_f32_e32 v118, v118
	v_exp_f32_e32 v115, v115
	v_mul_f32_e32 v98, 0xbfb8aa3b, v98
	v_exp_f32_e32 v98, v98
	v_add_f32_e32 v118, 1.0, v118
	v_add_f32_e32 v115, 1.0, v115
	v_rcp_f32_e32 v115, v115
	v_add_f32_e32 v98, 1.0, v98
	v_mul_f32_e32 v102, 0xbfb8aa3b, v102
	v_mul_f32_e32 v99, 0xbfb8aa3b, v99
	v_exp_f32_e32 v102, v102
	v_exp_f32_e32 v99, v99
	v_mul_f32_e32 v90, 0xbfb8aa3b, v90
	v_exp_f32_e32 v90, v90
	v_add_f32_e32 v102, 1.0, v102
	s_waitcnt vmcnt(0)
; __device__ __forceinline__ unsigned cvt_pk_bf16(float lo, float hi) { unsigned r; asm volatile("v_cvt_pk_bf16_f32 %0, %1, %2" : "=v"(r) : "v"(lo), "v"(hi)); return r; }
; __device__ __forceinline__ float bflo(unsigned w) { return __uint_as_float(w << 16); }
; __device__ __forceinline__ float bfhi(unsigned w) { return __uint_as_float(w & 0xffff0000u); }
; __device__ __forceinline__ float sigmoidf_(float x) { return __builtin_amdgcn_rcpf(1.0f + __expf(-x)); }
;   __device__ __forceinline__ void operator()(const f32x4 (&acc)[2][2][4][2], const Unit& u, int wr, int wc, int fr, int fq) const {
;     ...
;       for (int m = 0; m < 4; ++m) {
;         const size_t off = (size_t)(row0 + ai * HALF + m * 16) * DM + col0;
;         float o[8];
; #pragma unroll
;         for (int n = 0; n < 2; ++n)
; #pragma unroll
;           for (int j = 0; j < 4; ++j) {
;             const int e = n * 4 + j; const unsigned aw = av[m][e >> 1], bw = bv[m][e >> 1];
;             const float a = (e & 1) ? bfhi(aw) : bflo(aw), b = (e & 1) ? bfhi(bw) : bflo(bw);
;             o[e] = sigmoidf_(acc[ai][0][m][n][j]) * a + sigmoidf_(acc[ai][1][m][n][j]) * b; }
;         u32x4 w; w.x = cvt_pk_bf16(o[0], o[1]); w.y = cvt_pk_bf16(o[2], o[3]); w.z = cvt_pk_bf16(o[4], o[5]); w.w = cvt_pk_bf16(o[6], o[7]);
;         *(u32x4*)(O + off) = w; }
	v_lshlrev_b32_e32 v188, 16, v154
	v_add_f32_e32 v99, 1.0, v99
	v_lshlrev_b32_e32 v189, 16, v158
	v_pk_mul_f32 v[186:187], v[186:187], v[188:189]
	v_rcp_f32_e32 v99, v99
	v_add_f32_e32 v146, v186, v187
	v_and_b32_e32 v187, 0xffff0000, v158
	v_and_b32_e32 v186, 0xffff0000, v154
	v_pk_mul_f32 v[150:151], v[150:151], v[186:187]
	v_lshlrev_b32_e32 v187, 16, v159
	v_add_f32_e32 v147, v150, v151
	v_mul_f32_e32 v150, 0xbfb8aa3b, v152
	v_exp_f32_e32 v150, v150
	v_rcp_f32_e32 v151, v148
	v_lshlrev_b32_e32 v186, 16, v155
	v_and_b32_e32 v152, 0xffff0000, v155
	v_add_f32_e32 v150, 1.0, v150
	v_rcp_f32_e32 v150, v150
	v_add_f32_e32 v90, 1.0, v90
	v_mul_f32_e32 v94, 0xbfb8aa3b, v94
	v_mul_f32_e32 v91, 0xbfb8aa3b, v91
	v_pk_mul_f32 v[150:151], v[150:151], v[186:187]
	v_exp_f32_e32 v94, v94
	v_add_f32_e32 v148, v150, v151
	v_mul_f32_e32 v150, 0xbfb8aa3b, v153
	v_exp_f32_e32 v150, v150
	v_rcp_f32_e32 v151, v149
	v_and_b32_e32 v153, 0xffff0000, v159
	v_exp_f32_e32 v91, v91
	v_add_f32_e32 v150, 1.0, v150
	v_rcp_f32_e32 v150, v150
	v_add_f32_e32 v94, 1.0, v94
	v_add_f32_e32 v91, 1.0, v91
	v_rcp_f32_e32 v91, v91
	v_pk_mul_f32 v[150:151], v[150:151], v[152:153]
	v_lshlrev_b32_e32 v153, 16, v160
	v_add_f32_e32 v149, v150, v151
	v_rcp_f32_e32 v151, v122
	v_mul_f32_e32 v122, 0xbfb8aa3b, v135
	v_exp_f32_e32 v122, v122
	v_rcp_f32_e32 v150, v134
	v_lshlrev_b32_e32 v152, 16, v156
	v_and_b32_e32 v135, 0xffff0000, v160
	v_add_f32_e32 v122, 1.0, v122
	v_rcp_f32_e32 v122, v122
	v_and_b32_e32 v134, 0xffff0000, v156
	v_pk_mul_f32 v[150:151], v[150:151], v[152:153]
	v_mul_f32_e32 v82, 0xbfb8aa3b, v82
	v_pk_mul_f32 v[122:123], v[122:123], v[134:135]
	v_add_f32_e32 v150, v150, v151
	v_add_f32_e32 v151, v122, v123
	v_mul_f32_e32 v122, 0xbfb8aa3b, v136
	v_mul_f32_e32 v123, 0xbfb8aa3b, v124
	v_exp_f32_e32 v122, v122
	v_exp_f32_e32 v123, v123
	v_lshlrev_b32_e32 v135, 16, v161
	v_lshlrev_b32_e32 v134, 16, v157
	v_add_f32_e32 v122, 1.0, v122
	v_add_f32_e32 v123, 1.0, v123
	v_rcp_f32_e32 v122, v122
	v_rcp_f32_e32 v123, v123
	v_and_b32_e32 v124, 0xffff0000, v157
	v_exp_f32_e32 v82, v82
	v_mul_f32_e32 v86, 0xbfb8aa3b, v86
	v_pk_mul_f32 v[122:123], v[122:123], v[134:135]
	v_cvt_pk_bf16_f32 v134, v146, v147
	v_cvt_pk_bf16_f32 v135, v148, v149
	v_cvt_pk_bf16_f32 v136, v150, v151
	v_lshlrev_b32_e32 v147, 16, v142
	v_add_f32_e32 v152, v122, v123
	v_mul_f32_e32 v122, 0xbfb8aa3b, v137
	v_mul_f32_e32 v123, 0xbfb8aa3b, v125
	v_exp_f32_e32 v122, v122
	v_exp_f32_e32 v123, v123
	v_and_b32_e32 v125, 0xffff0000, v161
	v_lshlrev_b32_e32 v146, 16, v138
	v_add_f32_e32 v122, 1.0, v122
	v_add_f32_e32 v123, 1.0, v123
	v_rcp_f32_e32 v122, v122
	v_rcp_f32_e32 v123, v123
	v_add_f32_e32 v82, 1.0, v82
	v_mul_f32_e32 v83, 0xbfb8aa3b, v83
	v_exp_f32_e32 v86, v86
	v_pk_mul_f32 v[122:123], v[122:123], v[124:125]
	v_lshlrev_b64 v[124:125], 1, v[178:179]
	v_add_f32_e32 v122, v122, v123
	v_cvt_pk_bf16_f32 v137, v152, v122
	v_lshlrev_b64 v[122:123], 12, v[176:177]
	v_lshl_add_u64 v[122:123], s[46:47], 0, v[122:123]
	v_lshl_add_u64 v[122:123], v[122:123], 0, v[124:125]
	global_store_dwordx4 v[122:123], v[134:137], off
	v_exp_f32_e32 v83, v83
	v_add_f32_e32 v86, 1.0, v86
	v_rcp_f32_e32 v137, v114
	v_mul_f32_e32 v114, 0xbfb8aa3b, v119
	v_exp_f32_e32 v114, v114
	v_rcp_f32_e32 v136, v118
	v_and_b32_e32 v119, 0xffff0000, v142
	v_and_b32_e32 v118, 0xffff0000, v138
	v_add_f32_e32 v114, 1.0, v114
	v_rcp_f32_e32 v114, v114
	v_pk_mul_f32 v[136:137], v[136:137], v[146:147]
	v_or_b32_e32 v134, 16, v176
	v_add_f32_e32 v136, v136, v137
	v_pk_mul_f32 v[114:115], v[114:115], v[118:119]
	v_lshlrev_b32_e32 v119, 16, v143
	v_add_f32_e32 v137, v114, v115
	v_mul_f32_e32 v114, 0xbfb8aa3b, v120
	v_mul_f32_e32 v115, 0xbfb8aa3b, v116
	v_exp_f32_e32 v114, v114
	v_exp_f32_e32 v115, v115
	v_lshlrev_b32_e32 v118, 16, v139
	v_and_b32_e32 v116, 0xffff0000, v139
	v_add_f32_e32 v114, 1.0, v114
	v_add_f32_e32 v115, 1.0, v115
	v_rcp_f32_e32 v114, v114
	v_rcp_f32_e32 v115, v115
	v_ashrrev_i32_e32 v135, 31, v134
	v_add_f32_e32 v83, 1.0, v83
	v_rcp_f32_e32 v83, v83
	v_pk_mul_f32 v[114:115], v[114:115], v[118:119]
	v_mul_f32_e32 v74, 0xbfb8aa3b, v74
	v_add_f32_e32 v118, v114, v115
	v_mul_f32_e32 v114, 0xbfb8aa3b, v121
	v_mul_f32_e32 v115, 0xbfb8aa3b, v117
	v_exp_f32_e32 v114, v114
	v_exp_f32_e32 v115, v115
	v_and_b32_e32 v117, 0xffff0000, v143
	v_exp_f32_e32 v74, v74
	v_add_f32_e32 v114, 1.0, v114
	v_add_f32_e32 v115, 1.0, v115
	v_rcp_f32_e32 v114, v114
	v_rcp_f32_e32 v115, v115
	v_add_f32_e32 v74, 1.0, v74
	v_mul_f32_e32 v78, 0xbfb8aa3b, v78
	v_mul_f32_e32 v75, 0xbfb8aa3b, v75
	v_pk_mul_f32 v[114:115], v[114:115], v[116:117]
	v_lshlrev_b32_e32 v117, 16, v144
	v_add_f32_e32 v119, v114, v115
	v_rcp_f32_e32 v115, v98
	v_mul_f32_e32 v98, 0xbfb8aa3b, v103
	v_exp_f32_e32 v98, v98
	v_rcp_f32_e32 v114, v102
	v_lshlrev_b32_e32 v116, 16, v140
	v_and_b32_e32 v103, 0xffff0000, v144
	v_add_f32_e32 v98, 1.0, v98
	v_rcp_f32_e32 v98, v98
	v_and_b32_e32 v102, 0xffff0000, v140
	v_pk_mul_f32 v[114:115], v[114:115], v[116:117]
	v_exp_f32_e32 v78, v78
	v_pk_mul_f32 v[98:99], v[98:99], v[102:103]
	v_add_f32_e32 v114, v114, v115
	v_add_f32_e32 v115, v98, v99
	v_mul_f32_e32 v98, 0xbfb8aa3b, v104
	v_mul_f32_e32 v99, 0xbfb8aa3b, v100
	v_exp_f32_e32 v98, v98
	v_exp_f32_e32 v99, v99
	v_lshlrev_b32_e32 v103, 16, v145
	v_lshlrev_b32_e32 v102, 16, v141
	v_add_f32_e32 v98, 1.0, v98
	v_add_f32_e32 v99, 1.0, v99
	v_rcp_f32_e32 v98, v98
	v_rcp_f32_e32 v99, v99
	v_and_b32_e32 v100, 0xffff0000, v141
	v_exp_f32_e32 v75, v75
	v_add_f32_e32 v78, 1.0, v78
	v_pk_mul_f32 v[98:99], v[98:99], v[102:103]
	v_mul_f32_e32 v66, 0xbfb8aa3b, v66
	v_add_f32_e32 v102, v98, v99
	v_mul_f32_e32 v98, 0xbfb8aa3b, v105
; __device__ __forceinline__ unsigned cvt_pk_bf16(float lo, float hi) { unsigned r; asm volatile("v_cvt_pk_bf16_f32 %0, %1, %2" : "=v"(r) : "v"(lo), "v"(hi)); return r; }
; __device__ __forceinline__ float bflo(unsigned w) { return __uint_as_float(w << 16); }
; __device__ __forceinline__ float bfhi(unsigned w) { return __uint_as_float(w & 0xffff0000u); }
; __device__ __forceinline__ float sigmoidf_(float x) { return __builtin_amdgcn_rcpf(1.0f + __expf(-x)); }
;   __device__ __forceinline__ void operator()(const f32x4 (&acc)[2][2][4][2], const Unit& u, int wr, int wc, int fr, int fq) const {
;     ...
;       for (int m = 0; m < 4; ++m) {
;         const size_t off = (size_t)(row0 + ai * HALF + m * 16) * DM + col0;
;         float o[8];
; #pragma unroll
;         for (int n = 0; n < 2; ++n)
; #pragma unroll
;           for (int j = 0; j < 4; ++j) {
;             const int e = n * 4 + j; const unsigned aw = av[m][e >> 1], bw = bv[m][e >> 1];
;             const float a = (e & 1) ? bfhi(aw) : bflo(aw), b = (e & 1) ? bfhi(bw) : bflo(bw);
;             o[e] = sigmoidf_(acc[ai][0][m][n][j]) * a + sigmoidf_(acc[ai][1][m][n][j]) * b; }
;         u32x4 w; w.x = cvt_pk_bf16(o[0], o[1]); w.y = cvt_pk_bf16(o[2], o[3]); w.z = cvt_pk_bf16(o[4], o[5]); w.w = cvt_pk_bf16(o[6], o[7]);
;         *(u32x4*)(O + off) = w; }
	v_mul_f32_e32 v99, 0xbfb8aa3b, v101
	v_exp_f32_e32 v98, v98
	v_exp_f32_e32 v99, v99
	v_and_b32_e32 v101, 0xffff0000, v145
	v_add_f32_e32 v75, 1.0, v75
	v_add_f32_e32 v98, 1.0, v98
	v_add_f32_e32 v99, 1.0, v99
	v_rcp_f32_e32 v98, v98
	v_rcp_f32_e32 v99, v99
	v_rcp_f32_e32 v75, v75
	v_exp_f32_e32 v66, v66
	v_mul_f32_e32 v70, 0xbfb8aa3b, v70
	v_pk_mul_f32 v[98:99], v[98:99], v[100:101]
	v_mul_f32_e32 v67, 0xbfb8aa3b, v67
	v_add_f32_e32 v101, v98, v99
	v_cvt_pk_bf16_f32 v98, v136, v137
	v_cvt_pk_bf16_f32 v99, v118, v119
	v_cvt_pk_bf16_f32 v100, v114, v115
	v_cvt_pk_bf16_f32 v101, v102, v101
	v_lshlrev_b64 v[102:103], 12, v[134:135]
	v_lshl_add_u64 v[102:103], s[46:47], 0, v[102:103]
	v_lshl_add_u64 v[102:103], v[102:103], 0, v[124:125]
	global_store_dwordx4 v[102:103], v[98:101], off
	v_lshlrev_b32_e32 v103, 16, v130
	v_lshlrev_b32_e32 v102, 16, v126
	v_rcp_f32_e32 v101, v90
	v_mul_f32_e32 v90, 0xbfb8aa3b, v95
	v_exp_f32_e32 v90, v90
	v_rcp_f32_e32 v100, v94
	v_and_b32_e32 v95, 0xffff0000, v130
	v_and_b32_e32 v94, 0xffff0000, v126
	v_add_f32_e32 v90, 1.0, v90
	v_rcp_f32_e32 v90, v90
	v_pk_mul_f32 v[100:101], v[100:101], v[102:103]
	v_or_b32_e32 v98, 32, v176
	v_add_f32_e32 v100, v100, v101
	v_pk_mul_f32 v[90:91], v[90:91], v[94:95]
	v_lshlrev_b32_e32 v95, 16, v131
	v_add_f32_e32 v101, v90, v91
	v_mul_f32_e32 v90, 0xbfb8aa3b, v96
	v_mul_f32_e32 v91, 0xbfb8aa3b, v92
	v_exp_f32_e32 v90, v90
	v_exp_f32_e32 v91, v91
	v_lshlrev_b32_e32 v94, 16, v127
	v_and_b32_e32 v92, 0xffff0000, v127
	v_add_f32_e32 v90, 1.0, v90
	v_add_f32_e32 v91, 1.0, v91
	v_rcp_f32_e32 v90, v90
	v_rcp_f32_e32 v91, v91
	v_ashrrev_i32_e32 v99, 31, v98
	v_add_f32_e32 v66, 1.0, v66
	v_exp_f32_e32 v70, v70
	v_pk_mul_f32 v[90:91], v[90:91], v[94:95]
	v_exp_f32_e32 v67, v67
	v_add_f32_e32 v94, v90, v91
	v_mul_f32_e32 v90, 0xbfb8aa3b, v97
	v_mul_f32_e32 v91, 0xbfb8aa3b, v93
	v_exp_f32_e32 v90, v90
	v_exp_f32_e32 v91, v91
	v_and_b32_e32 v93, 0xffff0000, v131
	v_add_f32_e32 v70, 1.0, v70
	v_add_f32_e32 v90, 1.0, v90
	v_add_f32_e32 v91, 1.0, v91
	v_rcp_f32_e32 v90, v90
	v_rcp_f32_e32 v91, v91
	v_add_f32_e32 v67, 1.0, v67
	v_rcp_f32_e32 v67, v67
	s_mov_b64 s[38:39], 0x8000
	v_pk_mul_f32 v[90:91], v[90:91], v[92:93]
	v_lshlrev_b32_e32 v93, 16, v132
	v_add_f32_e32 v95, v90, v91
	v_rcp_f32_e32 v91, v82
	v_mul_f32_e32 v82, 0xbfb8aa3b, v87
	v_exp_f32_e32 v82, v82
	v_rcp_f32_e32 v90, v86
	v_lshlrev_b32_e32 v92, 16, v128
	v_and_b32_e32 v87, 0xffff0000, v132
	v_add_f32_e32 v82, 1.0, v82
	v_rcp_f32_e32 v82, v82
	v_and_b32_e32 v86, 0xffff0000, v128
	v_pk_mul_f32 v[90:91], v[90:91], v[92:93]
	v_mul_f32_e32 v58, 0xbfb8aa3b, v58
	v_pk_mul_f32 v[82:83], v[82:83], v[86:87]
	v_add_f32_e32 v90, v90, v91
	v_add_f32_e32 v91, v82, v83
	v_mul_f32_e32 v82, 0xbfb8aa3b, v88
	v_mul_f32_e32 v83, 0xbfb8aa3b, v84
	v_exp_f32_e32 v82, v82
	v_exp_f32_e32 v83, v83
	v_lshlrev_b32_e32 v87, 16, v133
	v_lshlrev_b32_e32 v86, 16, v129
	v_add_f32_e32 v82, 1.0, v82
	v_add_f32_e32 v83, 1.0, v83
	v_rcp_f32_e32 v82, v82
	v_rcp_f32_e32 v83, v83
	v_and_b32_e32 v84, 0xffff0000, v129
	v_exp_f32_e32 v58, v58
	v_mul_f32_e32 v59, 0xbfb8aa3b, v59
	v_pk_mul_f32 v[82:83], v[82:83], v[86:87]
	v_exp_f32_e32 v59, v59
	v_add_f32_e32 v86, v82, v83
	v_mul_f32_e32 v82, 0xbfb8aa3b, v89
	v_mul_f32_e32 v83, 0xbfb8aa3b, v85
	v_exp_f32_e32 v82, v82
	v_exp_f32_e32 v83, v83
	v_and_b32_e32 v85, 0xffff0000, v133
	v_add_f32_e32 v58, 1.0, v58
	v_add_f32_e32 v82, 1.0, v82
	v_add_f32_e32 v83, 1.0, v83
	v_rcp_f32_e32 v82, v82
	v_rcp_f32_e32 v83, v83
	v_mul_f32_e32 v62, 0xbfb8aa3b, v62
	v_exp_f32_e32 v62, v62
	v_add_f32_e32 v59, 1.0, v59
	v_pk_mul_f32 v[82:83], v[82:83], v[84:85]
	v_rcp_f32_e32 v59, v59
	v_add_f32_e32 v85, v82, v83
	v_cvt_pk_bf16_f32 v82, v100, v101
	v_cvt_pk_bf16_f32 v83, v94, v95
	v_cvt_pk_bf16_f32 v84, v90, v91
	v_cvt_pk_bf16_f32 v85, v86, v85
	v_lshlrev_b64 v[86:87], 12, v[98:99]
	v_lshl_add_u64 v[86:87], s[46:47], 0, v[86:87]
	v_lshl_add_u64 v[86:87], v[86:87], 0, v[124:125]
	global_store_dwordx4 v[86:87], v[82:85], off
	v_lshlrev_b32_e32 v87, 16, v110
	v_lshlrev_b32_e32 v86, 16, v106
	v_rcp_f32_e32 v85, v74
	v_mul_f32_e32 v74, 0xbfb8aa3b, v79
	v_exp_f32_e32 v74, v74
	v_rcp_f32_e32 v84, v78
	v_and_b32_e32 v79, 0xffff0000, v110
	v_and_b32_e32 v78, 0xffff0000, v106
	v_add_f32_e32 v74, 1.0, v74
	v_rcp_f32_e32 v74, v74
	v_pk_mul_f32 v[84:85], v[84:85], v[86:87]
	v_or_b32_e32 v82, 48, v176
	v_add_f32_e32 v84, v84, v85
	v_pk_mul_f32 v[74:75], v[74:75], v[78:79]
	v_lshlrev_b32_e32 v79, 16, v111
	v_add_f32_e32 v85, v74, v75
	v_mul_f32_e32 v74, 0xbfb8aa3b, v80
	v_mul_f32_e32 v75, 0xbfb8aa3b, v76
	v_exp_f32_e32 v74, v74
	v_exp_f32_e32 v75, v75
	v_lshlrev_b32_e32 v78, 16, v107
	v_and_b32_e32 v76, 0xffff0000, v107
	v_add_f32_e32 v74, 1.0, v74
	v_add_f32_e32 v75, 1.0, v75
	v_rcp_f32_e32 v74, v74
	v_rcp_f32_e32 v75, v75
	v_ashrrev_i32_e32 v83, 31, v82
	v_rcp_f32_e32 v99, v58
	v_mul_f32_e32 v58, 0xbfb8aa3b, v63
	v_pk_mul_f32 v[74:75], v[74:75], v[78:79]
	v_exp_f32_e32 v58, v58
	v_add_f32_e32 v78, v74, v75
	v_mul_f32_e32 v74, 0xbfb8aa3b, v81
	v_mul_f32_e32 v75, 0xbfb8aa3b, v77
	v_exp_f32_e32 v74, v74
	v_exp_f32_e32 v75, v75
	v_and_b32_e32 v77, 0xffff0000, v111
	v_add_f32_e32 v58, 1.0, v58
	v_add_f32_e32 v74, 1.0, v74
	v_add_f32_e32 v75, 1.0, v75
	v_rcp_f32_e32 v74, v74
	v_rcp_f32_e32 v75, v75
	v_rcp_f32_e32 v58, v58
	v_add_f32_e32 v62, 1.0, v62
	v_rcp_f32_e32 v98, v62
	v_pk_mul_f32 v[74:75], v[74:75], v[76:77]
	v_lshlrev_b32_e32 v77, 16, v112
	v_add_f32_e32 v79, v74, v75
	v_rcp_f32_e32 v75, v66
	v_mul_f32_e32 v66, 0xbfb8aa3b, v71
	v_exp_f32_e32 v66, v66
	v_rcp_f32_e32 v74, v70
	v_lshlrev_b32_e32 v76, 16, v108
	v_and_b32_e32 v71, 0xffff0000, v112
; __device__ __forceinline__ unsigned cvt_pk_bf16(float lo, float hi) { unsigned r; asm volatile("v_cvt_pk_bf16_f32 %0, %1, %2" : "=v"(r) : "v"(lo), "v"(hi)); return r; }
; __device__ __forceinline__ float bflo(unsigned w) { return __uint_as_float(w << 16); }
; __device__ __forceinline__ float bfhi(unsigned w) { return __uint_as_float(w & 0xffff0000u); }
; __device__ __forceinline__ float sigmoidf_(float x) { return __builtin_amdgcn_rcpf(1.0f + __expf(-x)); }
;   __device__ __forceinline__ void operator()(const f32x4 (&acc)[2][2][4][2], const Unit& u, int wr, int wc, int fr, int fq) const {
;     ...
;       for (int m = 0; m < 4; ++m) { const size_t idx = ((((size_t)(u.pm * 16 + u.pn) * 2 + ai) * 4 + m) * 8 + wave) * 64 + lane; av[m] = *(const u32x4*)(Aa + idx * 8); bv[m] = *(const u32x4*)(Bb + idx * 8); }
; #pragma unroll
;       for (int m = 0; m < 4; ++m) {
;         const size_t off = (size_t)(row0 + ai * HALF + m * 16) * DM + col0;
;         float o[8];
; #pragma unroll
;         for (int n = 0; n < 2; ++n)
; #pragma unroll
;           for (int j = 0; j < 4; ++j) {
;             const int e = n * 4 + j; const unsigned aw = av[m][e >> 1], bw = bv[m][e >> 1];
;             const float a = (e & 1) ? bfhi(aw) : bflo(aw), b = (e & 1) ? bfhi(bw) : bflo(bw);
;             o[e] = sigmoidf_(acc[ai][0][m][n][j]) * a + sigmoidf_(acc[ai][1][m][n][j]) * b; }
;         u32x4 w; w.x = cvt_pk_bf16(o[0], o[1]); w.y = cvt_pk_bf16(o[2], o[3]); w.z = cvt_pk_bf16(o[4], o[5]); w.w = cvt_pk_bf16(o[6], o[7]);
;         *(u32x4*)(O + off) = w; }
	v_add_f32_e32 v66, 1.0, v66
	v_rcp_f32_e32 v66, v66
	v_and_b32_e32 v70, 0xffff0000, v108
	v_pk_mul_f32 v[74:75], v[74:75], v[76:77]
	v_mul_f32_e32 v50, 0xbfb8aa3b, v50
	v_pk_mul_f32 v[66:67], v[66:67], v[70:71]
	v_add_f32_e32 v74, v74, v75
	v_add_f32_e32 v75, v66, v67
	v_mul_f32_e32 v66, 0xbfb8aa3b, v72
	v_mul_f32_e32 v67, 0xbfb8aa3b, v68
	v_exp_f32_e32 v66, v66
	v_exp_f32_e32 v67, v67
	v_lshlrev_b32_e32 v71, 16, v113
	v_lshlrev_b32_e32 v70, 16, v109
	v_add_f32_e32 v66, 1.0, v66
	v_add_f32_e32 v67, 1.0, v67
	v_rcp_f32_e32 v66, v66
	v_rcp_f32_e32 v67, v67
	v_and_b32_e32 v68, 0xffff0000, v109
	v_exp_f32_e32 v50, v50
	v_mul_f32_e32 v54, 0xbfb8aa3b, v54
	v_pk_mul_f32 v[66:67], v[66:67], v[70:71]
	v_mul_f32_e32 v51, 0xbfb8aa3b, v51
	v_add_f32_e32 v70, v66, v67
	v_mul_f32_e32 v66, 0xbfb8aa3b, v73
	v_mul_f32_e32 v67, 0xbfb8aa3b, v69
	v_exp_f32_e32 v66, v66
	v_exp_f32_e32 v67, v67
	v_and_b32_e32 v69, 0xffff0000, v113
	v_add_f32_e32 v50, 1.0, v50
	v_add_f32_e32 v66, 1.0, v66
	v_add_f32_e32 v67, 1.0, v67
	v_rcp_f32_e32 v66, v66
	v_rcp_f32_e32 v67, v67
	v_exp_f32_e32 v54, v54
	v_exp_f32_e32 v51, v51
	v_mul_f32_e32 v42, 0xbfb8aa3b, v42
	v_pk_mul_f32 v[66:67], v[66:67], v[68:69]
	v_add_f32_e32 v54, 1.0, v54
	v_add_f32_e32 v69, v66, v67
	v_cvt_pk_bf16_f32 v66, v84, v85
	v_cvt_pk_bf16_f32 v67, v78, v79
	v_cvt_pk_bf16_f32 v68, v74, v75
	v_cvt_pk_bf16_f32 v69, v70, v69
	v_lshlrev_b64 v[70:71], 12, v[82:83]
	v_lshl_add_u64 v[70:71], s[46:47], 0, v[70:71]
	v_lshl_add_u64 v[70:71], v[70:71], 0, v[124:125]
	global_store_dwordx4 v[70:71], v[66:69], off
	v_add_f32_e32 v51, 1.0, v51
	v_rcp_f32_e32 v51, v51
	v_lshl_add_u64 v[66:67], v[174:175], 0, s[38:39]
	v_lshl_add_u64 v[68:69], s[42:43], 0, v[66:67]
	v_lshl_add_u64 v[66:67], s[52:53], 0, v[66:67]
	global_load_dwordx4 v[90:93], v[68:69], off
	global_load_dwordx4 v[94:97], v[66:67], off
	s_mov_b64 s[38:39], 0xa000
	v_lshl_add_u64 v[66:67], v[174:175], 0, s[38:39]
	v_lshl_add_u64 v[68:69], s[42:43], 0, v[66:67]
	v_lshl_add_u64 v[66:67], s[52:53], 0, v[66:67]
	global_load_dwordx4 v[82:85], v[68:69], off
	global_load_dwordx4 v[86:89], v[66:67], off
	s_mov_b64 s[38:39], 0xc000
	v_lshl_add_u64 v[66:67], v[174:175], 0, s[38:39]
	s_mov_b64 s[38:39], 0xe000
	v_exp_f32_e32 v42, v42
	v_lshl_add_u64 v[68:69], s[42:43], 0, v[66:67]
	v_lshl_add_u64 v[66:67], s[52:53], 0, v[66:67]
	v_lshl_add_u64 v[70:71], v[174:175], 0, s[38:39]
	global_load_dwordx4 v[74:77], v[68:69], off
	global_load_dwordx4 v[78:81], v[66:67], off
	v_lshl_add_u64 v[66:67], s[42:43], 0, v[70:71]
	v_lshl_add_u64 v[70:71], s[52:53], 0, v[70:71]
	s_mov_b32 s14, 0x80000
	global_load_dwordx4 v[66:69], v[66:67], off
	v_add_f32_e32 v42, 1.0, v42
	global_load_dwordx4 v[70:73], v[70:71], off
	v_mul_f32_e32 v46, 0xbfb8aa3b, v46
	v_mul_f32_e32 v43, 0xbfb8aa3b, v43
	v_exp_f32_e32 v46, v46
	v_exp_f32_e32 v43, v43
	v_mul_f32_e32 v34, 0xbfb8aa3b, v34
	v_exp_f32_e32 v34, v34
	v_add_f32_e32 v46, 1.0, v46
	v_add_f32_e32 v43, 1.0, v43
	v_rcp_f32_e32 v43, v43
	v_add_f32_e32 v34, 1.0, v34
	v_mul_f32_e32 v38, 0xbfb8aa3b, v38
	v_mul_f32_e32 v35, 0xbfb8aa3b, v35
	v_exp_f32_e32 v38, v38
	v_exp_f32_e32 v35, v35
	v_mul_f32_e32 v24, 0xbfb8aa3b, v24
	v_exp_f32_e32 v24, v24
	v_add_f32_e32 v38, 1.0, v38
	v_add_f32_e32 v35, 1.0, v35
	v_rcp_f32_e32 v35, v35
	v_add_f32_e32 v24, 1.0, v24
	v_mul_f32_e32 v28, 0xbfb8aa3b, v28
	v_mul_f32_e32 v25, 0xbfb8aa3b, v25
	v_exp_f32_e32 v28, v28
	v_exp_f32_e32 v25, v25
	v_mul_f32_e32 v16, 0xbfb8aa3b, v16
	v_exp_f32_e32 v16, v16
	v_add_f32_e32 v28, 1.0, v28
	v_add_f32_e32 v25, 1.0, v25
	v_rcp_f32_e32 v25, v25
	v_add_f32_e32 v16, 1.0, v16
	v_mul_f32_e32 v20, 0xbfb8aa3b, v20
	v_mul_f32_e32 v17, 0xbfb8aa3b, v17
	v_exp_f32_e32 v20, v20
	v_exp_f32_e32 v17, v17
	v_mul_f32_e32 v8, 0xbfb8aa3b, v8
	v_exp_f32_e32 v8, v8
	v_add_f32_e32 v20, 1.0, v20
	v_add_f32_e32 v17, 1.0, v17
	v_rcp_f32_e32 v17, v17
	v_add_f32_e32 v8, 1.0, v8
	v_mul_f32_e32 v12, 0xbfb8aa3b, v12
	v_mul_f32_e32 v9, 0xbfb8aa3b, v9
	v_exp_f32_e32 v12, v12
	v_exp_f32_e32 v9, v9
	v_mul_f32_e32 v0, 0xbfb8aa3b, v0
	v_exp_f32_e32 v0, v0
	v_add_f32_e32 v12, 1.0, v12
	v_add_f32_e32 v9, 1.0, v9
	v_rcp_f32_e32 v9, v9
	v_add_f32_e32 v0, 1.0, v0
	v_mul_f32_e32 v4, 0xbfb8aa3b, v4
	v_mul_f32_e32 v1, 0xbfb8aa3b, v1
	v_exp_f32_e32 v4, v4
	v_exp_f32_e32 v1, v1
	s_mov_b32 s36, s22
	s_mov_b64 s[38:39], s[28:29]
	v_add_f32_e32 v4, 1.0, v4
	s_waitcnt vmcnt(0)
; __device__ __forceinline__ unsigned cvt_pk_bf16(float lo, float hi) { unsigned r; asm volatile("v_cvt_pk_bf16_f32 %0, %1, %2" : "=v"(r) : "v"(lo), "v"(hi)); return r; }
; __device__ __forceinline__ float bflo(unsigned w) { return __uint_as_float(w << 16); }
; __device__ __forceinline__ float bfhi(unsigned w) { return __uint_as_float(w & 0xffff0000u); }
; __device__ __forceinline__ float sigmoidf_(float x) { return __builtin_amdgcn_rcpf(1.0f + __expf(-x)); }
;   __device__ __forceinline__ void operator()(const f32x4 (&acc)[2][2][4][2], const Unit& u, int wr, int wc, int fr, int fq) const {
;     ...
;       for (int m = 0; m < 4; ++m) {
;         const size_t off = (size_t)(row0 + ai * HALF + m * 16) * DM + col0;
;         float o[8];
; #pragma unroll
;         for (int n = 0; n < 2; ++n)
; #pragma unroll
;           for (int j = 0; j < 4; ++j) {
;             const int e = n * 4 + j; const unsigned aw = av[m][e >> 1], bw = bv[m][e >> 1];
;             const float a = (e & 1) ? bfhi(aw) : bflo(aw), b = (e & 1) ? bfhi(bw) : bflo(bw);
;             o[e] = sigmoidf_(acc[ai][0][m][n][j]) * a + sigmoidf_(acc[ai][1][m][n][j]) * b; }
;         u32x4 w; w.x = cvt_pk_bf16(o[0], o[1]); w.y = cvt_pk_bf16(o[2], o[3]); w.z = cvt_pk_bf16(o[4], o[5]); w.w = cvt_pk_bf16(o[6], o[7]);
;         *(u32x4*)(O + off) = w; }
	v_and_b32_e32 v62, 0xffff0000, v90
	v_and_b32_e32 v63, 0xffff0000, v94
	v_pk_mul_f32 v[58:59], v[58:59], v[62:63]
	v_lshlrev_b32_e32 v100, 16, v90
	v_add_f32_e32 v90, v58, v59
	v_mul_f32_e32 v58, 0xbfb8aa3b, v64
	v_mul_f32_e32 v59, 0xbfb8aa3b, v60
	v_exp_f32_e32 v58, v58
	v_exp_f32_e32 v59, v59
	v_lshlrev_b32_e32 v63, 16, v95
	v_lshlrev_b32_e32 v62, 16, v91
	v_add_f32_e32 v58, 1.0, v58
	v_add_f32_e32 v59, 1.0, v59
	v_rcp_f32_e32 v58, v58
	v_rcp_f32_e32 v59, v59
	v_and_b32_e32 v60, 0xffff0000, v91
	v_lshlrev_b32_e32 v101, 16, v94
	v_pk_mul_f32 v[98:99], v[98:99], v[100:101]
	v_pk_mul_f32 v[58:59], v[58:59], v[62:63]
	v_add_f32_e32 v98, v98, v99
	v_add_f32_e32 v62, v58, v59
	v_mul_f32_e32 v58, 0xbfb8aa3b, v65
	v_mul_f32_e32 v59, 0xbfb8aa3b, v61
	v_exp_f32_e32 v58, v58
	v_exp_f32_e32 v59, v59
	v_and_b32_e32 v61, 0xffff0000, v95
	v_add_f32_e32 v1, 1.0, v1
	v_add_f32_e32 v58, 1.0, v58
	v_add_f32_e32 v59, 1.0, v59
	v_rcp_f32_e32 v58, v58
	v_rcp_f32_e32 v59, v59
	v_rcp_f32_e32 v1, v1
	s_mov_b64 s[42:43], s[26:27]
	v_readlane_b32 s45, v255, 26
	v_pk_mul_f32 v[58:59], v[58:59], v[60:61]
	v_lshlrev_b32_e32 v61, 16, v96
	v_add_f32_e32 v63, v58, v59
	v_rcp_f32_e32 v59, v50
	v_mul_f32_e32 v50, 0xbfb8aa3b, v55
	v_exp_f32_e32 v50, v50
	v_rcp_f32_e32 v58, v54
	v_lshlrev_b32_e32 v60, 16, v92
	v_and_b32_e32 v55, 0xffff0000, v96
	v_add_f32_e32 v50, 1.0, v50
	v_rcp_f32_e32 v50, v50
	v_and_b32_e32 v54, 0xffff0000, v92
	v_pk_mul_f32 v[58:59], v[58:59], v[60:61]
	v_readlane_b32 s48, v255, 29
	v_pk_mul_f32 v[50:51], v[50:51], v[54:55]
	v_add_f32_e32 v58, v58, v59
	v_add_f32_e32 v59, v50, v51
	v_mul_f32_e32 v50, 0xbfb8aa3b, v56
	v_mul_f32_e32 v51, 0xbfb8aa3b, v52
	v_exp_f32_e32 v50, v50
	v_exp_f32_e32 v51, v51
	v_lshlrev_b32_e32 v55, 16, v97
	v_lshlrev_b32_e32 v54, 16, v93
	v_add_f32_e32 v50, 1.0, v50
	v_add_f32_e32 v51, 1.0, v51
	v_rcp_f32_e32 v50, v50
	v_rcp_f32_e32 v51, v51
	v_and_b32_e32 v52, 0xffff0000, v93
	v_readlane_b32 s49, v255, 30
	v_readlane_b32 s50, v255, 31
	v_pk_mul_f32 v[50:51], v[50:51], v[54:55]
	v_readlane_b32 s51, v255, 32
	v_add_f32_e32 v54, v50, v51
	v_mul_f32_e32 v50, 0xbfb8aa3b, v57
	v_mul_f32_e32 v51, 0xbfb8aa3b, v53
	v_exp_f32_e32 v50, v50
	v_exp_f32_e32 v51, v51
	v_and_b32_e32 v53, 0xffff0000, v97
	v_add_f32_e32 v50, 1.0, v50
	v_add_f32_e32 v51, 1.0, v51
	v_rcp_f32_e32 v50, v50
	v_rcp_f32_e32 v51, v51
	s_nop 0
	v_pk_mul_f32 v[50:51], v[50:51], v[52:53]
	s_nop 0
	v_add_f32_e32 v53, v50, v51
	v_cvt_pk_bf16_f32 v50, v98, v90
	v_cvt_pk_bf16_f32 v51, v62, v63
	v_cvt_pk_bf16_f32 v52, v58, v59
	v_cvt_pk_bf16_f32 v53, v54, v53
	v_add_co_u32_e32 v54, vcc, s14, v122
	s_mov_b32 s14, 0x90000
	s_nop 0
	v_addc_co_u32_e32 v55, vcc, 0, v123, vcc
	global_store_dwordx4 v[54:55], v[50:53], off
	s_nop 1
	v_rcp_f32_e32 v51, v42
	v_mul_f32_e32 v42, 0xbfb8aa3b, v47
	v_exp_f32_e32 v42, v42
	v_rcp_f32_e32 v50, v46
	v_lshlrev_b32_e32 v53, 16, v86
	v_lshlrev_b32_e32 v52, 16, v82
	v_add_f32_e32 v42, 1.0, v42
	v_rcp_f32_e32 v42, v42
	v_and_b32_e32 v47, 0xffff0000, v86
	v_and_b32_e32 v46, 0xffff0000, v82
	v_pk_mul_f32 v[50:51], v[50:51], v[52:53]
	v_pk_mul_f32 v[42:43], v[42:43], v[46:47]
	v_add_f32_e32 v50, v50, v51
	v_add_f32_e32 v51, v42, v43
	v_mul_f32_e32 v42, 0xbfb8aa3b, v48
	v_mul_f32_e32 v43, 0xbfb8aa3b, v44
	v_exp_f32_e32 v42, v42
	v_exp_f32_e32 v43, v43
	v_lshlrev_b32_e32 v47, 16, v87
	v_lshlrev_b32_e32 v46, 16, v83
	v_add_f32_e32 v42, 1.0, v42
	v_add_f32_e32 v43, 1.0, v43
	v_rcp_f32_e32 v42, v42
	v_rcp_f32_e32 v43, v43
	v_and_b32_e32 v44, 0xffff0000, v83
	v_pk_mul_f32 v[42:43], v[42:43], v[46:47]
	s_nop 0
	v_add_f32_e32 v46, v42, v43
	v_mul_f32_e32 v42, 0xbfb8aa3b, v49
	v_mul_f32_e32 v43, 0xbfb8aa3b, v45
	v_exp_f32_e32 v42, v42
	v_exp_f32_e32 v43, v43
	v_and_b32_e32 v45, 0xffff0000, v87
	v_add_f32_e32 v42, 1.0, v42
	v_add_f32_e32 v43, 1.0, v43
	v_rcp_f32_e32 v42, v42
	v_rcp_f32_e32 v43, v43
	s_nop 0
	v_pk_mul_f32 v[42:43], v[42:43], v[44:45]
	s_nop 0
	v_add_f32_e32 v47, v42, v43
	v_rcp_f32_e32 v43, v34
	v_mul_f32_e32 v34, 0xbfb8aa3b, v39
	v_exp_f32_e32 v34, v34
	v_rcp_f32_e32 v42, v38
	v_lshlrev_b32_e32 v45, 16, v88
	v_lshlrev_b32_e32 v44, 16, v84
	v_add_f32_e32 v34, 1.0, v34
	v_rcp_f32_e32 v34, v34
	v_and_b32_e32 v39, 0xffff0000, v88
	v_and_b32_e32 v38, 0xffff0000, v84
	v_pk_mul_f32 v[42:43], v[42:43], v[44:45]
	v_pk_mul_f32 v[34:35], v[34:35], v[38:39]
	v_add_f32_e32 v42, v42, v43
	v_add_f32_e32 v43, v34, v35
	v_mul_f32_e32 v34, 0xbfb8aa3b, v40
	v_mul_f32_e32 v35, 0xbfb8aa3b, v36
	v_exp_f32_e32 v34, v34
	v_exp_f32_e32 v35, v35
	v_lshlrev_b32_e32 v39, 16, v89
	v_lshlrev_b32_e32 v38, 16, v85
	v_add_f32_e32 v34, 1.0, v34
	v_add_f32_e32 v35, 1.0, v35
	v_rcp_f32_e32 v34, v34
	v_rcp_f32_e32 v35, v35
	v_and_b32_e32 v36, 0xffff0000, v85
	v_pk_mul_f32 v[34:35], v[34:35], v[38:39]
	s_nop 0
	v_add_f32_e32 v38, v34, v35
	v_mul_f32_e32 v34, 0xbfb8aa3b, v41
	v_mul_f32_e32 v35, 0xbfb8aa3b, v37
	v_exp_f32_e32 v34, v34
	v_exp_f32_e32 v35, v35
	v_and_b32_e32 v37, 0xffff0000, v89
	v_add_f32_e32 v34, 1.0, v34
	v_add_f32_e32 v35, 1.0, v35
	v_rcp_f32_e32 v34, v34
	v_rcp_f32_e32 v35, v35
	s_nop 0
	v_pk_mul_f32 v[34:35], v[34:35], v[36:37]
	s_nop 0
	v_add_f32_e32 v37, v34, v35
	v_cvt_pk_bf16_f32 v34, v50, v51
	v_cvt_pk_bf16_f32 v35, v46, v47
	v_cvt_pk_bf16_f32 v36, v42, v43
	v_cvt_pk_bf16_f32 v37, v38, v37
	v_add_co_u32_e32 v38, vcc, s14, v122
	s_mov_b32 s14, 0xa0000
	s_nop 0
	v_addc_co_u32_e32 v39, vcc, 0, v123, vcc
	global_store_dwordx4 v[38:39], v[34:37], off
; __device__ __forceinline__ unsigned cvt_pk_bf16(float lo, float hi) { unsigned r; asm volatile("v_cvt_pk_bf16_f32 %0, %1, %2" : "=v"(r) : "v"(lo), "v"(hi)); return r; }
; __device__ __forceinline__ float bflo(unsigned w) { return __uint_as_float(w << 16); }
; __device__ __forceinline__ float bfhi(unsigned w) { return __uint_as_float(w & 0xffff0000u); }
; __device__ __forceinline__ float sigmoidf_(float x) { return __builtin_amdgcn_rcpf(1.0f + __expf(-x)); }
; #define PG8_WAIT_V(n) asm volatile("s_waitcnt vmcnt(" #n ")" ::: "memory")
; #define PG8_BAR __builtin_amdgcn_s_barrier()
; template <class Epi, class Sched, bool ABLK = false>
; __device__ __forceinline__ void gemm_phase(LAS unsigned char* lds, const Gemm g, const Sched& S, const Epi& E) {
;     ...
;     cur = nxt; cA = nA; cB = nB; ++ui;
;   }
;   PG8_WAIT_V(0);
;   if (wr == 0) PG8_BAR;
;   PG8_BAR;
;   __device__ __forceinline__ void operator()(const f32x4 (&acc)[2][2][4][2], const Unit& u, int wr, int wc, int fr, int fq) const {
;     ...
;       for (int m = 0; m < 4; ++m) {
;         const size_t off = (size_t)(row0 + ai * HALF + m * 16) * DM + col0;
;         float o[8];
; #pragma unroll
;         for (int n = 0; n < 2; ++n)
; #pragma unroll
;           for (int j = 0; j < 4; ++j) {
;             const int e = n * 4 + j; const unsigned aw = av[m][e >> 1], bw = bv[m][e >> 1];
;             const float a = (e & 1) ? bfhi(aw) : bflo(aw), b = (e & 1) ? bfhi(bw) : bflo(bw);
;             o[e] = sigmoidf_(acc[ai][0][m][n][j]) * a + sigmoidf_(acc[ai][1][m][n][j]) * b; }
;         u32x4 w; w.x = cvt_pk_bf16(o[0], o[1]); w.y = cvt_pk_bf16(o[2], o[3]); w.z = cvt_pk_bf16(o[4], o[5]); w.w = cvt_pk_bf16(o[6], o[7]);
;         *(u32x4*)(O + off) = w; }
	s_nop 1
	v_rcp_f32_e32 v35, v24
	v_mul_f32_e32 v24, 0xbfb8aa3b, v29
	v_exp_f32_e32 v24, v24
	v_rcp_f32_e32 v34, v28
	v_lshlrev_b32_e32 v37, 16, v78
	v_lshlrev_b32_e32 v36, 16, v74
	v_add_f32_e32 v24, 1.0, v24
	v_rcp_f32_e32 v24, v24
	v_and_b32_e32 v29, 0xffff0000, v78
	v_and_b32_e32 v28, 0xffff0000, v74
	v_pk_mul_f32 v[34:35], v[34:35], v[36:37]
	v_pk_mul_f32 v[24:25], v[24:25], v[28:29]
	v_add_f32_e32 v34, v34, v35
	v_add_f32_e32 v35, v24, v25
	v_mul_f32_e32 v24, 0xbfb8aa3b, v30
	v_mul_f32_e32 v25, 0xbfb8aa3b, v26
	v_exp_f32_e32 v24, v24
	v_exp_f32_e32 v25, v25
	v_lshlrev_b32_e32 v29, 16, v79
	v_lshlrev_b32_e32 v28, 16, v75
	v_add_f32_e32 v24, 1.0, v24
	v_add_f32_e32 v25, 1.0, v25
	v_rcp_f32_e32 v24, v24
	v_rcp_f32_e32 v25, v25
	v_and_b32_e32 v26, 0xffff0000, v75
	v_pk_mul_f32 v[24:25], v[24:25], v[28:29]
	s_nop 0
	v_add_f32_e32 v28, v24, v25
	v_mul_f32_e32 v24, 0xbfb8aa3b, v31
	v_mul_f32_e32 v25, 0xbfb8aa3b, v27
	v_exp_f32_e32 v24, v24
	v_exp_f32_e32 v25, v25
	v_and_b32_e32 v27, 0xffff0000, v79
	v_add_f32_e32 v24, 1.0, v24
	v_add_f32_e32 v25, 1.0, v25
	v_rcp_f32_e32 v24, v24
	v_rcp_f32_e32 v25, v25
	s_nop 0
	v_pk_mul_f32 v[24:25], v[24:25], v[26:27]
	s_nop 0
	v_add_f32_e32 v29, v24, v25
	v_rcp_f32_e32 v25, v16
	v_mul_f32_e32 v16, 0xbfb8aa3b, v21
	v_exp_f32_e32 v16, v16
	v_rcp_f32_e32 v24, v20
	v_lshlrev_b32_e32 v27, 16, v80
	v_lshlrev_b32_e32 v26, 16, v76
	v_add_f32_e32 v16, 1.0, v16
	v_rcp_f32_e32 v16, v16
	v_and_b32_e32 v21, 0xffff0000, v80
	v_and_b32_e32 v20, 0xffff0000, v76
	v_pk_mul_f32 v[24:25], v[24:25], v[26:27]
	v_pk_mul_f32 v[16:17], v[16:17], v[20:21]
	v_add_f32_e32 v24, v24, v25
	v_add_f32_e32 v25, v16, v17
	v_mul_f32_e32 v16, 0xbfb8aa3b, v22
	v_mul_f32_e32 v17, 0xbfb8aa3b, v18
	v_exp_f32_e32 v16, v16
	v_exp_f32_e32 v17, v17
	v_lshlrev_b32_e32 v21, 16, v81
	v_lshlrev_b32_e32 v20, 16, v77
	v_add_f32_e32 v16, 1.0, v16
	v_add_f32_e32 v17, 1.0, v17
	v_rcp_f32_e32 v16, v16
	v_rcp_f32_e32 v17, v17
	v_and_b32_e32 v18, 0xffff0000, v77
	v_pk_mul_f32 v[16:17], v[16:17], v[20:21]
	s_nop 0
	v_add_f32_e32 v20, v16, v17
	v_mul_f32_e32 v16, 0xbfb8aa3b, v23
	v_mul_f32_e32 v17, 0xbfb8aa3b, v19
	v_exp_f32_e32 v16, v16
	v_exp_f32_e32 v17, v17
	v_and_b32_e32 v19, 0xffff0000, v81
	v_add_f32_e32 v16, 1.0, v16
	v_add_f32_e32 v17, 1.0, v17
	v_rcp_f32_e32 v16, v16
	v_rcp_f32_e32 v17, v17
	s_nop 0
	v_pk_mul_f32 v[16:17], v[16:17], v[18:19]
	s_nop 0
	v_add_f32_e32 v19, v16, v17
	v_cvt_pk_bf16_f32 v16, v34, v35
	v_cvt_pk_bf16_f32 v17, v28, v29
	v_cvt_pk_bf16_f32 v18, v24, v25
	v_cvt_pk_bf16_f32 v19, v20, v19
	v_add_co_u32_e32 v20, vcc, s14, v122
	s_mov_b32 s14, s20
	s_nop 0
	v_addc_co_u32_e32 v21, vcc, 0, v123, vcc
	global_store_dwordx4 v[20:21], v[16:19], off
	s_nop 1
	v_rcp_f32_e32 v17, v8
	v_mul_f32_e32 v8, 0xbfb8aa3b, v13
	v_exp_f32_e32 v8, v8
	v_rcp_f32_e32 v16, v12
	v_lshlrev_b32_e32 v19, 16, v70
	v_lshlrev_b32_e32 v18, 16, v66
	v_add_f32_e32 v8, 1.0, v8
	v_rcp_f32_e32 v8, v8
	v_and_b32_e32 v13, 0xffff0000, v70
	v_and_b32_e32 v12, 0xffff0000, v66
	v_pk_mul_f32 v[16:17], v[16:17], v[18:19]
	v_pk_mul_f32 v[8:9], v[8:9], v[12:13]
	v_add_f32_e32 v16, v16, v17
	v_add_f32_e32 v17, v8, v9
	v_mul_f32_e32 v8, 0xbfb8aa3b, v14
	v_mul_f32_e32 v9, 0xbfb8aa3b, v10
	v_exp_f32_e32 v8, v8
	v_exp_f32_e32 v9, v9
	v_lshlrev_b32_e32 v13, 16, v71
	v_lshlrev_b32_e32 v12, 16, v67
	v_add_f32_e32 v8, 1.0, v8
	v_add_f32_e32 v9, 1.0, v9
	v_rcp_f32_e32 v8, v8
	v_rcp_f32_e32 v9, v9
	v_and_b32_e32 v10, 0xffff0000, v67
	v_pk_mul_f32 v[8:9], v[8:9], v[12:13]
	s_nop 0
	v_add_f32_e32 v12, v8, v9
	v_mul_f32_e32 v8, 0xbfb8aa3b, v15
	v_mul_f32_e32 v9, 0xbfb8aa3b, v11
	v_exp_f32_e32 v8, v8
	v_exp_f32_e32 v9, v9
	v_and_b32_e32 v11, 0xffff0000, v71
	v_add_f32_e32 v8, 1.0, v8
	v_add_f32_e32 v9, 1.0, v9
	v_rcp_f32_e32 v8, v8
	v_rcp_f32_e32 v9, v9
	s_nop 0
	v_pk_mul_f32 v[8:9], v[8:9], v[10:11]
	s_nop 0
	v_add_f32_e32 v13, v8, v9
	v_rcp_f32_e32 v9, v0
	v_mul_f32_e32 v0, 0xbfb8aa3b, v5
	v_exp_f32_e32 v0, v0
	v_rcp_f32_e32 v8, v4
	v_lshlrev_b32_e32 v11, 16, v72
	v_lshlrev_b32_e32 v10, 16, v68
	v_add_f32_e32 v0, 1.0, v0
	v_rcp_f32_e32 v0, v0
	v_and_b32_e32 v5, 0xffff0000, v72
	v_and_b32_e32 v4, 0xffff0000, v68
	v_pk_mul_f32 v[8:9], v[8:9], v[10:11]
	v_pk_mul_f32 v[0:1], v[0:1], v[4:5]
	v_add_f32_e32 v8, v8, v9
	v_add_f32_e32 v9, v0, v1
	v_mul_f32_e32 v0, 0xbfb8aa3b, v6
	v_mul_f32_e32 v1, 0xbfb8aa3b, v2
	v_exp_f32_e32 v0, v0
	v_exp_f32_e32 v1, v1
	v_lshlrev_b32_e32 v5, 16, v73
	v_lshlrev_b32_e32 v4, 16, v69
	v_add_f32_e32 v0, 1.0, v0
	v_add_f32_e32 v1, 1.0, v1
	v_rcp_f32_e32 v0, v0
	v_rcp_f32_e32 v1, v1
	v_and_b32_e32 v2, 0xffff0000, v69
	v_pk_mul_f32 v[0:1], v[0:1], v[4:5]
	s_nop 0
	v_add_f32_e32 v4, v0, v1
	v_mul_f32_e32 v0, 0xbfb8aa3b, v7
	v_mul_f32_e32 v1, 0xbfb8aa3b, v3
	v_exp_f32_e32 v0, v0
	v_exp_f32_e32 v1, v1
	v_and_b32_e32 v3, 0xffff0000, v73
	v_add_f32_e32 v0, 1.0, v0
	v_add_f32_e32 v1, 1.0, v1
	v_rcp_f32_e32 v0, v0
	v_rcp_f32_e32 v1, v1
	s_nop 0
	v_pk_mul_f32 v[0:1], v[0:1], v[2:3]
	s_nop 0
	v_add_f32_e32 v3, v0, v1
	v_cvt_pk_bf16_f32 v0, v16, v17
	v_cvt_pk_bf16_f32 v1, v12, v13
	v_cvt_pk_bf16_f32 v2, v8, v9
	v_cvt_pk_bf16_f32 v3, v4, v3
	v_add_co_u32_e32 v4, vcc, 0xb0000, v122
	s_nop 1
	v_addc_co_u32_e32 v5, vcc, 0, v123, vcc
	s_and_b64 vcc, exec, s[24:25]
	global_store_dwordx4 v[4:5], v[0:3], off
	s_cbranch_vccz .LBB0_221
	s_waitcnt vmcnt(0)
	v_mov_b32_e32 v131, v197
	s_cmpk_gt_u32 s5, 0xff
	s_cbranch_scc1 .LBB0_260
	s_barrier

; #define PG8_STAGE(bufoff, gbase, voff) do { _Pragma("unroll") for (int _i = 0; _i < 2; ++_i) \
;     __builtin_amdgcn_global_load_lds((const unsigned*)((const char*)(gbase) + (voff)[_i]), (LAS unsigned*)(lds + (bufoff) + ldsw + _i * 8192), 16, 0, 0); } while (0)
; #define PG8_LDA(dst, b, h) do { _Pragma("unroll") for (int m = 0; m < 4; ++m) _Pragma("unroll") for (int k = 0; k < 2; ++k) dst[m][k] = *(const LAS bf16x8*)(lds + PG8_SA(b, h) + aoff + m * 2048 + k * 1024); } while (0)
; #define PG8_LDB(dst, b, h) do { _Pragma("unroll") for (int n = 0; n < 2; ++n) _Pragma("unroll") for (int k = 0; k < 2; ++k) dst[n][k] = *(const LAS bf16x8*)(lds + PG8_SB(b, h) + boff + n * 2048 + k * 1024); } while (0)
; #define PG8_MMA(ai, bj, At, Bt) do { __builtin_amdgcn_s_setprio(1); _Pragma("unroll") for (int m = 0; m < 4; ++m) _Pragma("unroll") for (int n = 0; n < 2; ++n) _Pragma("unroll") for (int k = 0; k < 2; ++k) \
;     acc[ai][bj][m][n] = __builtin_amdgcn_mfma_f32_16x16x32_bf16(Bt[n][k], At[m][k], acc[ai][bj][m][n], 0, 0, 0); __builtin_amdgcn_s_setprio(0); } while (0)
; #define PG8_WAIT_V(n) asm volatile("s_waitcnt vmcnt(" #n ")" ::: "memory")
; #define PG8_WAIT_L(n) asm volatile("s_waitcnt lgkmcnt(" #n ")" ::: "memory")
; #define PG8_BAR __builtin_amdgcn_s_barrier()
; template <class Epi, class Sched, bool ABLK = false>
; __device__ __forceinline__ void gemm_phase(LAS unsigned char* lds, const Gemm g, const Sched& S, const Epi& E) {
;     ...
;     for (int t = 0; t < nt; t += 2) {
;       const bool last = (t == nt - 2);
;       const char* a1 = cA + (size_t)(t + 1) * kstep;
;       const char* a2 = last ? nA : cA + (size_t)(t + 2) * kstep; const char* b2 = last ? nB : cB + (size_t)(t + 2) * kstepB;
;       const char* a3 = a2 + kstep; const char* b3 = b2 + kstepB;
;       PG8_LDB(B0, 0, 0); PG8_SCHED; PG8_LDA(At, 0, 0); PG8_STAGE(PG8_SA(1, 1), a1 + hstep, voffA);
;       PG8_WAIT_L(8); PG8_BAR; PG8_WAIT_L(0); PG8_MMA(0, 0, At, B0); PG8_BAR; PG8_SCHED;
;       PG8_LDB(B1, 0, 1); PG8_STAGE(PG8_SB(0, 0), b2, voffB);
;       PG8_BAR; PG8_WAIT_L(0); PG8_MMA(0, 1, At, B1); PG8_BAR;
;       PG8_LDA(At, 0, 1); PG8_STAGE(PG8_SA(0, 0), a2, voffA);
;       PG8_BAR; PG8_WAIT_L(0); PG8_MMA(1, 0, At, B0); PG8_BAR; PG8_SCHED;
;       PG8_STAGE(PG8_SB(0, 1), b2 + hstepB, voffB);
;       PG8_WAIT_V(6); PG8_BAR; PG8_MMA(1, 1, At, B1); PG8_BAR;
.LBB0_334:
	s_add_u32 s42, s38, 0xfffc0080
	s_addc_u32 s43, s39, -1
	s_add_i32 s47, 0, 0x10000
	v_add_u32_e32 v159, s47, v156
	ds_read_b128 v[160:163], v159
	ds_read_b128 v[164:167], v159 offset:1024
	ds_read_b128 v[168:171], v159 offset:2048
	ds_read_b128 v[172:175], v159 offset:3072
	s_cmp_eq_u32 s46, 12
	s_cselect_b32 s45, s29, s43
	s_cselect_b32 s44, s28, s42
	s_cselect_b32 s43, s15, s25
	s_cselect_b32 s42, s21, s23
	v_lshl_add_u64 v[198:199], s[38:39], 0, v[152:153]
	s_add_i32 m0, s11, 0xc000
	ds_read_b128 v[176:179], v158
	ds_read_b128 v[180:183], v158 offset:1024
	ds_read_b128 v[184:187], v158 offset:2048
	ds_read_b128 v[188:191], v158 offset:3072
	ds_read_b128 v[192:195], v158 offset:4096
	ds_read_b128 v[208:211], v158 offset:5120
	ds_read_b128 v[212:215], v158 offset:6144
	ds_read_b128 v[216:219], v158 offset:7168
	global_load_lds_dwordx4 v[198:199], off
	v_lshl_add_u64 v[198:199], s[38:39], 0, v[154:155]
	s_add_i32 m0, s11, 0xe000
	s_nop 0
	global_load_lds_dwordx4 v[198:199], off
	s_waitcnt lgkmcnt(8)
	s_barrier
	s_waitcnt lgkmcnt(0)
	s_waitcnt lgkmcnt(0)
	v_mfma_f32_16x16x32_bf16 v[126:129], v[160:163], v[176:179], v[126:129]
	v_mfma_f32_16x16x32_bf16 v[122:125], v[168:171], v[176:179], v[122:125]
	v_mfma_f32_16x16x32_bf16 v[114:117], v[160:163], v[184:187], v[114:117]
	v_mfma_f32_16x16x32_bf16 v[106:109], v[168:171], v[184:187], v[106:109]
	v_mfma_f32_16x16x32_bf16 v[102:105], v[160:163], v[192:195], v[102:105]
	v_mfma_f32_16x16x32_bf16 v[94:97], v[168:171], v[192:195], v[94:97]
	v_mfma_f32_16x16x32_bf16 v[86:89], v[160:163], v[212:215], v[86:89]
	v_mfma_f32_16x16x32_bf16 v[78:81], v[168:171], v[212:215], v[78:81]
	v_mfma_f32_16x16x32_bf16 v[126:129], v[164:167], v[180:183], v[126:129]
	v_mfma_f32_16x16x32_bf16 v[122:125], v[172:175], v[180:183], v[122:125]
	v_mfma_f32_16x16x32_bf16 v[114:117], v[164:167], v[188:191], v[114:117]
	v_mfma_f32_16x16x32_bf16 v[106:109], v[172:175], v[188:191], v[106:109]
	v_mfma_f32_16x16x32_bf16 v[102:105], v[164:167], v[208:211], v[102:105]
	v_mfma_f32_16x16x32_bf16 v[94:97], v[172:175], v[208:211], v[94:97]
	v_mfma_f32_16x16x32_bf16 v[86:89], v[164:167], v[216:219], v[86:89]
	v_mfma_f32_16x16x32_bf16 v[78:81], v[172:175], v[216:219], v[78:81]
	s_barrier
	s_add_i32 s50, 0, 0x14000
	s_add_i32 s47, s47, s7
	v_add_u32_e32 v159, s50, v156
	v_lshl_add_u64 v[198:199], s[42:43], 0, v[130:131]
	s_mov_b32 m0, s47
	ds_read_b128 v[220:223], v159
	ds_read_b128 v[224:227], v159 offset:1024
	ds_read_b128 v[228:231], v159 offset:2048
	ds_read_b128 v[232:235], v159 offset:3072
	global_load_lds_dwordx4 v[198:199], off
	v_lshl_add_u64 v[198:199], s[42:43], 0, v[134:135]
	s_add_i32 m0, s47, 0x2000
	s_nop 0
	global_load_lds_dwordx4 v[198:199], off
	s_barrier
	s_waitcnt lgkmcnt(0)
	s_waitcnt lgkmcnt(0)
	v_mfma_f32_16x16x32_bf16 v[118:121], v[220:223], v[176:179], v[118:121]
	v_mfma_f32_16x16x32_bf16 v[110:113], v[228:231], v[176:179], v[110:113]
	v_mfma_f32_16x16x32_bf16 v[98:101], v[220:223], v[184:187], v[98:101]
	v_mfma_f32_16x16x32_bf16 v[90:93], v[228:231], v[184:187], v[90:93]
	v_mfma_f32_16x16x32_bf16 v[82:85], v[220:223], v[192:195], v[82:85]
	v_mfma_f32_16x16x32_bf16 v[74:77], v[228:231], v[192:195], v[74:77]
	v_mfma_f32_16x16x32_bf16 v[70:73], v[220:223], v[212:215], v[70:73]
	v_mfma_f32_16x16x32_bf16 v[66:69], v[228:231], v[212:215], v[66:69]
	v_mfma_f32_16x16x32_bf16 v[118:121], v[224:227], v[180:183], v[118:121]
	v_mfma_f32_16x16x32_bf16 v[110:113], v[232:235], v[180:183], v[110:113]
	v_mfma_f32_16x16x32_bf16 v[98:101], v[224:227], v[188:191], v[98:101]
	v_mfma_f32_16x16x32_bf16 v[90:93], v[232:235], v[188:191], v[90:93]
	v_mfma_f32_16x16x32_bf16 v[82:85], v[224:227], v[208:211], v[82:85]
	v_mfma_f32_16x16x32_bf16 v[74:77], v[232:235], v[208:211], v[74:77]
	v_mfma_f32_16x16x32_bf16 v[70:73], v[224:227], v[216:219], v[70:73]
	v_mfma_f32_16x16x32_bf16 v[66:69], v[232:235], v[216:219], v[66:69]
	s_mov_b32 m0, s11
	v_lshl_add_u64 v[198:199], s[44:45], 0, v[32:33]
	s_barrier
	ds_read_b128 v[176:179], v158 offset:16384
	ds_read_b128 v[180:183], v158 offset:17408
	ds_read_b128 v[184:187], v158 offset:18432
	ds_read_b128 v[188:191], v158 offset:19456
	ds_read_b128 v[192:195], v158 offset:20480
	ds_read_b128 v[208:211], v158 offset:21504
	ds_read_b128 v[212:215], v158 offset:22528
	ds_read_b128 v[216:219], v158 offset:23552
	global_load_lds_dwordx4 v[198:199], off
	v_lshl_add_u64 v[236:237], s[44:45], 0, v[132:133]
	s_mov_b32 m0, s17
	s_nop 0
	global_load_lds_dwordx4 v[236:237], off
	s_barrier
	s_waitcnt lgkmcnt(0)
	s_waitcnt lgkmcnt(0)
	v_mfma_f32_16x16x32_bf16 v[62:65], v[160:163], v[176:179], v[62:65]
	v_mfma_f32_16x16x32_bf16 v[58:61], v[168:171], v[176:179], v[58:61]
	v_mfma_f32_16x16x32_bf16 v[54:57], v[160:163], v[184:187], v[54:57]
	v_mfma_f32_16x16x32_bf16 v[46:49], v[168:171], v[184:187], v[46:49]
	v_mfma_f32_16x16x32_bf16 v[38:41], v[160:163], v[192:195], v[38:41]
	v_mfma_f32_16x16x32_bf16 v[28:31], v[168:171], v[192:195], v[28:31]
	v_mfma_f32_16x16x32_bf16 v[20:23], v[160:163], v[212:215], v[20:23]
	v_mfma_f32_16x16x32_bf16 v[12:15], v[168:171], v[212:215], v[12:15]
	v_mfma_f32_16x16x32_bf16 v[62:65], v[164:167], v[180:183], v[62:65]
	v_mfma_f32_16x16x32_bf16 v[58:61], v[172:175], v[180:183], v[58:61]
	v_mfma_f32_16x16x32_bf16 v[54:57], v[164:167], v[188:191], v[54:57]
	v_mfma_f32_16x16x32_bf16 v[46:49], v[172:175], v[188:191], v[46:49]
	v_mfma_f32_16x16x32_bf16 v[38:41], v[164:167], v[208:211], v[38:41]
	v_mfma_f32_16x16x32_bf16 v[28:31], v[172:175], v[208:211], v[28:31]
	v_mfma_f32_16x16x32_bf16 v[20:23], v[164:167], v[216:219], v[20:23]
	v_mfma_f32_16x16x32_bf16 v[12:15], v[172:175], v[216:219], v[12:15]
	s_barrier
; #define PG8_STAGE(bufoff, gbase, voff) do { _Pragma("unroll") for (int _i = 0; _i < 2; ++_i) \
;     __builtin_amdgcn_global_load_lds((const unsigned*)((const char*)(gbase) + (voff)[_i]), (LAS unsigned*)(lds + (bufoff) + ldsw + _i * 8192), 16, 0, 0); } while (0)
; #define PG8_LDA(dst, b, h) do { _Pragma("unroll") for (int m = 0; m < 4; ++m) _Pragma("unroll") for (int k = 0; k < 2; ++k) dst[m][k] = *(const LAS bf16x8*)(lds + PG8_SA(b, h) + aoff + m * 2048 + k * 1024); } while (0)
; #define PG8_LDB(dst, b, h) do { _Pragma("unroll") for (int n = 0; n < 2; ++n) _Pragma("unroll") for (int k = 0; k < 2; ++k) dst[n][k] = *(const LAS bf16x8*)(lds + PG8_SB(b, h) + boff + n * 2048 + k * 1024); } while (0)
; #define PG8_MMA(ai, bj, At, Bt) do { __builtin_amdgcn_s_setprio(1); _Pragma("unroll") for (int m = 0; m < 4; ++m) _Pragma("unroll") for (int n = 0; n < 2; ++n) _Pragma("unroll") for (int k = 0; k < 2; ++k) \
;     acc[ai][bj][m][n] = __builtin_amdgcn_mfma_f32_16x16x32_bf16(Bt[n][k], At[m][k], acc[ai][bj][m][n], 0, 0, 0); __builtin_amdgcn_s_setprio(0); } while (0)
; #define PG8_WAIT_V(n) asm volatile("s_waitcnt vmcnt(" #n ")" ::: "memory")
; #define PG8_WAIT_L(n) asm volatile("s_waitcnt lgkmcnt(" #n ")" ::: "memory")
; #define PG8_BAR __builtin_amdgcn_s_barrier()
; #define PG8_SCHED __builtin_amdgcn_sched_barrier(0)
; template <class Epi, class Sched, bool ABLK = false>
; __device__ __forceinline__ void gemm_phase(LAS unsigned char* lds, const Gemm g, const Sched& S, const Epi& E) {
;     ...
;       PG8_WAIT_V(6); PG8_BAR; PG8_MMA(1, 1, At, B1); PG8_BAR;
;       PG8_LDB(B0, 1, 0); PG8_SCHED; PG8_LDA(At, 1, 0); PG8_STAGE(PG8_SA(0, 1), a2 + hstep, voffA);
;       PG8_WAIT_L(8); PG8_BAR; PG8_WAIT_L(0); PG8_MMA(0, 0, At, B0); PG8_BAR; PG8_SCHED;
;       PG8_LDB(B1, 1, 1); PG8_STAGE(PG8_SB(1, 0), b3, voffB);
;       PG8_BAR; PG8_WAIT_L(0); PG8_MMA(0, 1, At, B1); PG8_BAR;
;       PG8_LDA(At, 1, 1); PG8_STAGE(PG8_SA(1, 0), a3, voffA);
;       PG8_BAR; PG8_WAIT_L(0); PG8_MMA(1, 0, At, B0); PG8_BAR; PG8_SCHED;
	s_add_u32 s48, s42, 0x4000
	s_addc_u32 s49, s43, 0
	s_add_i32 s47, s50, s7
	v_lshl_add_u64 v[160:161], s[48:49], 0, v[130:131]
	s_mov_b32 m0, s47
	s_nop 0
	global_load_lds_dwordx4 v[160:161], off
	v_lshl_add_u64 v[160:161], s[48:49], 0, v[134:135]
	s_add_i32 m0, s47, 0x2000
	s_nop 0
	global_load_lds_dwordx4 v[160:161], off
	s_waitcnt vmcnt(6)
	s_barrier
	v_mfma_f32_16x16x32_bf16 v[50:53], v[220:223], v[176:179], v[50:53]
	v_mfma_f32_16x16x32_bf16 v[42:45], v[228:231], v[176:179], v[42:45]
	v_mfma_f32_16x16x32_bf16 v[34:37], v[220:223], v[184:187], v[34:37]
	v_mfma_f32_16x16x32_bf16 v[24:27], v[228:231], v[184:187], v[24:27]
	v_mfma_f32_16x16x32_bf16 v[16:19], v[220:223], v[192:195], v[16:19]
	v_mfma_f32_16x16x32_bf16 v[8:11], v[228:231], v[192:195], v[8:11]
	v_mfma_f32_16x16x32_bf16 v[4:7], v[220:223], v[212:215], v[4:7]
	v_mfma_f32_16x16x32_bf16 v[0:3], v[228:231], v[212:215], v[0:3]
	v_mfma_f32_16x16x32_bf16 v[50:53], v[224:227], v[180:183], v[50:53]
	v_mfma_f32_16x16x32_bf16 v[42:45], v[232:235], v[180:183], v[42:45]
	v_mfma_f32_16x16x32_bf16 v[34:37], v[224:227], v[188:191], v[34:37]
	v_mfma_f32_16x16x32_bf16 v[24:27], v[232:235], v[188:191], v[24:27]
	v_mfma_f32_16x16x32_bf16 v[16:19], v[224:227], v[208:211], v[16:19]
	v_mfma_f32_16x16x32_bf16 v[8:11], v[232:235], v[208:211], v[8:11]
	v_mfma_f32_16x16x32_bf16 v[4:7], v[224:227], v[216:219], v[4:7]
	v_mfma_f32_16x16x32_bf16 v[0:3], v[232:235], v[216:219], v[0:3]
	s_add_i32 s47, 0, 0x18000
	v_add_u32_e32 v159, s47, v156
	s_barrier
	ds_read_b128 v[160:163], v159
	ds_read_b128 v[164:167], v159 offset:1024
	ds_read_b128 v[168:171], v159 offset:2048
	ds_read_b128 v[172:175], v159 offset:3072
	s_add_u32 s44, s44, 0x40000
	s_addc_u32 s45, s45, 0
	s_mov_b32 m0, s31
	v_lshl_add_u64 v[220:221], s[44:45], 0, v[32:33]
	ds_read_b128 v[176:179], v158 offset:32768
	ds_read_b128 v[180:183], v158 offset:33792
	ds_read_b128 v[184:187], v158 offset:34816
	ds_read_b128 v[188:191], v158 offset:35840
	ds_read_b128 v[192:195], v158 offset:36864
	ds_read_b128 v[208:211], v158 offset:37888
	ds_read_b128 v[212:215], v158 offset:38912
	ds_read_b128 v[216:219], v158 offset:39936
	global_load_lds_dwordx4 v[220:221], off
	v_lshl_add_u64 v[220:221], s[44:45], 0, v[132:133]
	s_mov_b32 m0, s56
	s_nop 0
	global_load_lds_dwordx4 v[220:221], off
	s_waitcnt lgkmcnt(8)
	s_barrier
	s_waitcnt lgkmcnt(0)
	s_waitcnt lgkmcnt(0)
	v_mfma_f32_16x16x32_bf16 v[126:129], v[160:163], v[176:179], v[126:129]
	v_mfma_f32_16x16x32_bf16 v[122:125], v[168:171], v[176:179], v[122:125]
	v_mfma_f32_16x16x32_bf16 v[114:117], v[160:163], v[184:187], v[114:117]
	v_mfma_f32_16x16x32_bf16 v[106:109], v[168:171], v[184:187], v[106:109]
	v_mfma_f32_16x16x32_bf16 v[102:105], v[160:163], v[192:195], v[102:105]
	v_mfma_f32_16x16x32_bf16 v[94:97], v[168:171], v[192:195], v[94:97]
	v_mfma_f32_16x16x32_bf16 v[86:89], v[160:163], v[212:215], v[86:89]
	v_mfma_f32_16x16x32_bf16 v[78:81], v[168:171], v[212:215], v[78:81]
	v_mfma_f32_16x16x32_bf16 v[126:129], v[164:167], v[180:183], v[126:129]
	v_mfma_f32_16x16x32_bf16 v[122:125], v[172:175], v[180:183], v[122:125]
	v_mfma_f32_16x16x32_bf16 v[114:117], v[164:167], v[188:191], v[114:117]
	v_mfma_f32_16x16x32_bf16 v[106:109], v[172:175], v[188:191], v[106:109]
	v_mfma_f32_16x16x32_bf16 v[102:105], v[164:167], v[208:211], v[102:105]
	v_mfma_f32_16x16x32_bf16 v[94:97], v[172:175], v[208:211], v[94:97]
	v_mfma_f32_16x16x32_bf16 v[86:89], v[164:167], v[216:219], v[86:89]
	v_mfma_f32_16x16x32_bf16 v[78:81], v[172:175], v[216:219], v[78:81]
	s_barrier
	s_add_i32 s48, 0, 0x1c000
	s_add_u32 s44, s42, 0x8000
	s_addc_u32 s45, s43, 0
	s_add_i32 s47, s47, s7
	v_add_u32_e32 v159, s48, v156
	v_lshl_add_u64 v[238:239], s[44:45], 0, v[130:131]
	s_mov_b32 m0, s47
	ds_read_b128 v[220:223], v159
	ds_read_b128 v[224:227], v159 offset:1024
	ds_read_b128 v[228:231], v159 offset:2048
	ds_read_b128 v[232:235], v159 offset:3072
	global_load_lds_dwordx4 v[238:239], off
	v_lshl_add_u64 v[238:239], s[44:45], 0, v[134:135]
	s_add_i32 m0, s47, 0x2000
	s_nop 0
	global_load_lds_dwordx4 v[238:239], off
	s_barrier
	s_waitcnt lgkmcnt(0)
	s_waitcnt lgkmcnt(0)
	v_mfma_f32_16x16x32_bf16 v[118:121], v[220:223], v[176:179], v[118:121]
	v_mfma_f32_16x16x32_bf16 v[110:113], v[228:231], v[176:179], v[110:113]
	v_mfma_f32_16x16x32_bf16 v[98:101], v[220:223], v[184:187], v[98:101]
	v_mfma_f32_16x16x32_bf16 v[90:93], v[228:231], v[184:187], v[90:93]
	v_mfma_f32_16x16x32_bf16 v[82:85], v[220:223], v[192:195], v[82:85]
	v_mfma_f32_16x16x32_bf16 v[74:77], v[228:231], v[192:195], v[74:77]
	v_mfma_f32_16x16x32_bf16 v[70:73], v[220:223], v[212:215], v[70:73]
	v_mfma_f32_16x16x32_bf16 v[66:69], v[228:231], v[212:215], v[66:69]
	v_mfma_f32_16x16x32_bf16 v[118:121], v[224:227], v[180:183], v[118:121]
	v_mfma_f32_16x16x32_bf16 v[110:113], v[232:235], v[180:183], v[110:113]
	v_mfma_f32_16x16x32_bf16 v[98:101], v[224:227], v[188:191], v[98:101]
	v_mfma_f32_16x16x32_bf16 v[90:93], v[232:235], v[188:191], v[90:93]
	v_mfma_f32_16x16x32_bf16 v[82:85], v[224:227], v[208:211], v[82:85]
	v_mfma_f32_16x16x32_bf16 v[74:77], v[232:235], v[208:211], v[74:77]
	v_mfma_f32_16x16x32_bf16 v[70:73], v[224:227], v[216:219], v[70:73]
	v_mfma_f32_16x16x32_bf16 v[66:69], v[232:235], v[216:219], v[66:69]
	s_mov_b32 m0, s69
	v_lshl_add_u64 v[198:199], v[198:199], 0, s[52:53]
	s_barrier
	ds_read_b128 v[176:179], v158 offset:49152
	ds_read_b128 v[180:183], v158 offset:50176
	ds_read_b128 v[184:187], v158 offset:51200
	ds_read_b128 v[188:191], v158 offset:52224
	ds_read_b128 v[192:195], v158 offset:53248
	ds_read_b128 v[208:211], v158 offset:54272
	ds_read_b128 v[212:215], v158 offset:55296
	ds_read_b128 v[216:219], v158 offset:56320
	global_load_lds_dwordx4 v[198:199], off
	v_lshl_add_u64 v[198:199], v[236:237], 0, s[52:53]
	s_mov_b32 m0, s77
	s_nop 0
	global_load_lds_dwordx4 v[198:199], off
	s_barrier
; #define PG8_STAGE(bufoff, gbase, voff) do { _Pragma("unroll") for (int _i = 0; _i < 2; ++_i) \
;     __builtin_amdgcn_global_load_lds((const unsigned*)((const char*)(gbase) + (voff)[_i]), (LAS unsigned*)(lds + (bufoff) + ldsw + _i * 8192), 16, 0, 0); } while (0)
; #define PG8_MMA(ai, bj, At, Bt) do { __builtin_amdgcn_s_setprio(1); _Pragma("unroll") for (int m = 0; m < 4; ++m) _Pragma("unroll") for (int n = 0; n < 2; ++n) _Pragma("unroll") for (int k = 0; k < 2; ++k) \
;     acc[ai][bj][m][n] = __builtin_amdgcn_mfma_f32_16x16x32_bf16(Bt[n][k], At[m][k], acc[ai][bj][m][n], 0, 0, 0); __builtin_amdgcn_s_setprio(0); } while (0)
; #define PG8_WAIT_V(n) asm volatile("s_waitcnt vmcnt(" #n ")" ::: "memory")
; #define PG8_WAIT_L(n) asm volatile("s_waitcnt lgkmcnt(" #n ")" ::: "memory")
; #define PG8_BAR __builtin_amdgcn_s_barrier()
; #define PG8_SCHED __builtin_amdgcn_sched_barrier(0)
; template <class Epi, class Sched, bool ABLK = false>
; __device__ __forceinline__ void gemm_phase(LAS unsigned char* lds, const Gemm g, const Sched& S, const Epi& E) {
;     ...
;       PG8_BAR; PG8_WAIT_L(0); PG8_MMA(1, 0, At, B0); PG8_BAR; PG8_SCHED;
;       PG8_STAGE(PG8_SB(1, 1), b3 + hstepB, voffB);
;       PG8_WAIT_V(6); PG8_BAR; PG8_MMA(1, 1, At, B1); PG8_BAR;
;     }
	s_waitcnt lgkmcnt(0)
	s_waitcnt lgkmcnt(0)
	v_mfma_f32_16x16x32_bf16 v[62:65], v[160:163], v[176:179], v[62:65]
	v_mfma_f32_16x16x32_bf16 v[58:61], v[168:171], v[176:179], v[58:61]
	v_mfma_f32_16x16x32_bf16 v[54:57], v[160:163], v[184:187], v[54:57]
	v_mfma_f32_16x16x32_bf16 v[46:49], v[168:171], v[184:187], v[46:49]
	v_mfma_f32_16x16x32_bf16 v[38:41], v[160:163], v[192:195], v[38:41]
	v_mfma_f32_16x16x32_bf16 v[28:31], v[168:171], v[192:195], v[28:31]
	v_mfma_f32_16x16x32_bf16 v[20:23], v[160:163], v[212:215], v[20:23]
	v_mfma_f32_16x16x32_bf16 v[12:15], v[168:171], v[212:215], v[12:15]
	v_mfma_f32_16x16x32_bf16 v[62:65], v[164:167], v[180:183], v[62:65]
	v_mfma_f32_16x16x32_bf16 v[58:61], v[172:175], v[180:183], v[58:61]
	v_mfma_f32_16x16x32_bf16 v[54:57], v[164:167], v[188:191], v[54:57]
	v_mfma_f32_16x16x32_bf16 v[46:49], v[172:175], v[188:191], v[46:49]
	v_mfma_f32_16x16x32_bf16 v[38:41], v[164:167], v[208:211], v[38:41]
	v_mfma_f32_16x16x32_bf16 v[28:31], v[172:175], v[208:211], v[28:31]
	v_mfma_f32_16x16x32_bf16 v[20:23], v[164:167], v[216:219], v[20:23]
	v_mfma_f32_16x16x32_bf16 v[12:15], v[172:175], v[216:219], v[12:15]
	s_barrier
	s_add_u32 s42, s42, 0xc000
	s_addc_u32 s43, s43, 0
	s_add_i32 s44, s48, s7
	v_lshl_add_u64 v[160:161], s[42:43], 0, v[130:131]
	s_mov_b32 m0, s44
	s_nop 0
	global_load_lds_dwordx4 v[160:161], off
	v_lshl_add_u64 v[160:161], s[42:43], 0, v[134:135]
	s_add_i32 m0, s44, 0x2000
	s_nop 0
	global_load_lds_dwordx4 v[160:161], off
	s_waitcnt vmcnt(6)
	s_barrier
	v_mfma_f32_16x16x32_bf16 v[50:53], v[220:223], v[176:179], v[50:53]
	v_mfma_f32_16x16x32_bf16 v[42:45], v[228:231], v[176:179], v[42:45]
	v_mfma_f32_16x16x32_bf16 v[34:37], v[220:223], v[184:187], v[34:37]
	v_mfma_f32_16x16x32_bf16 v[24:27], v[228:231], v[184:187], v[24:27]
	v_mfma_f32_16x16x32_bf16 v[16:19], v[220:223], v[192:195], v[16:19]
	v_mfma_f32_16x16x32_bf16 v[8:11], v[228:231], v[192:195], v[8:11]
	v_mfma_f32_16x16x32_bf16 v[4:7], v[220:223], v[212:215], v[4:7]
	v_mfma_f32_16x16x32_bf16 v[0:3], v[228:231], v[212:215], v[0:3]
	v_mfma_f32_16x16x32_bf16 v[50:53], v[224:227], v[180:183], v[50:53]
	v_mfma_f32_16x16x32_bf16 v[42:45], v[232:235], v[180:183], v[42:45]
	v_mfma_f32_16x16x32_bf16 v[34:37], v[224:227], v[188:191], v[34:37]
	v_mfma_f32_16x16x32_bf16 v[24:27], v[232:235], v[188:191], v[24:27]
	v_mfma_f32_16x16x32_bf16 v[16:19], v[224:227], v[208:211], v[16:19]
	v_mfma_f32_16x16x32_bf16 v[8:11], v[232:235], v[208:211], v[8:11]
	v_mfma_f32_16x16x32_bf16 v[4:7], v[224:227], v[216:219], v[4:7]
	v_mfma_f32_16x16x32_bf16 v[0:3], v[232:235], v[216:219], v[0:3]
	s_add_i32 s46, s46, 2
	s_add_u32 s23, s23, 0x10000
	s_addc_u32 s25, s25, 0
	s_add_u32 s38, s38, 0x100
	s_addc_u32 s39, s39, 0
	s_cmp_gt_u32 s46, 13
	s_barrier
	s_cbranch_scc0 .LBB0_334
; __device__ __forceinline__ unsigned cvt_pk_bf16(float lo, float hi) { unsigned r; asm volatile("v_cvt_pk_bf16_f32 %0, %1, %2" : "=v"(r) : "v"(lo), "v"(hi)); return r; }
; #define PG8_WAIT_V(n) asm volatile("s_waitcnt vmcnt(" #n ")" ::: "memory")
; #define PG8_BAR __builtin_amdgcn_s_barrier()
;   __device__ __forceinline__ float2 operator()(int i) const { const float2 wv = unpk2(Wd[i]); return half ? cmul(wv, twid((float)(i & (L - 1)) * invTurn)) : wv; }
; template <class Epi, class Sched, bool ABLK = false>
; __device__ __forceinline__ void gemm_phase(LAS unsigned char* lds, const Gemm g, const Sched& S, const Epi& E) {
;     ...
;     cur = nxt; cA = nA; cB = nB; ++ui;
;   }
;   PG8_WAIT_V(0);
;   if (wr == 0) PG8_BAR;
;   PG8_BAR;
;   __device__ __forceinline__ void operator()(const f32x4 (&acc)[2][2][4][2], const Unit& u, int wr, int wc, int fr, int fq) const {
;     const int wave = wr * 4 + wc, lane = fq * 16 + fr;
; #pragma unroll
;     for (int ai = 0; ai < 2; ++ai)
; #pragma unroll
;       for (int m = 0; m < 4; ++m)
; #pragma unroll
;         for (int bj = 0; bj < 2; ++bj) { const f32x4 v0 = acc[ai][bj][m][0], v1 = acc[ai][bj][m][1];
;           u32x4 w; w.x = cvt_pk_bf16(v0[0], v0[1]); w.y = cvt_pk_bf16(v0[2], v0[3]); w.z = cvt_pk_bf16(v1[0], v1[1]); w.w = cvt_pk_bf16(v1[2], v1[3]);
;           const size_t idx = ((((size_t)(u.pm * 16 + 2 * u.pn + bj) * 2 + ai) * 4 + m) * 8 + wave) * 64 + lane;
;           *(u32x4*)(O + idx * 8) = w; }
;   }
	s_lshl_b32 s15, s24, 4
	s_lshl_b32 s21, s22, 1
	s_add_i32 s24, s15, s21
	s_ashr_i32 s25, s24, 31
	s_lshl_b64 s[22:23], s[24:25], 12
	v_readlane_b32 s38, v252, 36
	s_or_b32 s24, s24, 1
	v_cvt_pk_bf16_f32 v126, v126, v127
	v_cvt_pk_bf16_f32 v127, v128, v129
	v_cvt_pk_bf16_f32 v128, v122, v123
	v_lshl_add_u64 v[122:123], s[22:23], 0, v[136:137]
	v_readlane_b32 s39, v252, 37
	s_ashr_i32 s25, s24, 31
	s_lshl_b64 s[24:25], s[24:25], 12
	v_lshl_add_u64 v[122:123], v[122:123], 4, s[38:39]
	v_cvt_pk_bf16_f32 v129, v124, v125
	global_store_dwordx4 v[122:123], v[126:129], off
	v_cvt_pk_bf16_f32 v118, v118, v119
	v_cvt_pk_bf16_f32 v119, v120, v121
	v_cvt_pk_bf16_f32 v120, v110, v111
	v_lshl_add_u64 v[110:111], s[24:25], 0, v[136:137]
	v_lshl_add_u64 v[110:111], v[110:111], 4, s[38:39]
	v_cvt_pk_bf16_f32 v121, v112, v113
	global_store_dwordx4 v[110:111], v[118:121], off
	v_cvt_pk_bf16_f32 v110, v114, v115
	v_cvt_pk_bf16_f32 v111, v116, v117
	v_cvt_pk_bf16_f32 v112, v106, v107
	v_lshl_add_u64 v[106:107], s[22:23], 0, v[138:139]
	v_lshl_add_u64 v[106:107], v[106:107], 4, s[38:39]
	v_cvt_pk_bf16_f32 v113, v108, v109
	global_store_dwordx4 v[106:107], v[110:113], off
	v_cvt_pk_bf16_f32 v98, v98, v99
	v_cvt_pk_bf16_f32 v99, v100, v101
	v_cvt_pk_bf16_f32 v100, v90, v91
	v_lshl_add_u64 v[90:91], s[24:25], 0, v[138:139]
	v_lshl_add_u64 v[90:91], v[90:91], 4, s[38:39]
	v_cvt_pk_bf16_f32 v101, v92, v93
	global_store_dwordx4 v[90:91], v[98:101], off
	v_cvt_pk_bf16_f32 v90, v102, v103
	v_cvt_pk_bf16_f32 v91, v104, v105
	v_cvt_pk_bf16_f32 v92, v94, v95
	v_lshl_add_u64 v[94:95], s[22:23], 0, v[140:141]
	v_lshl_add_u64 v[94:95], v[94:95], 4, s[38:39]
	v_cvt_pk_bf16_f32 v93, v96, v97
	global_store_dwordx4 v[94:95], v[90:93], off
	v_cvt_pk_bf16_f32 v82, v82, v83
	v_cvt_pk_bf16_f32 v83, v84, v85
	v_cvt_pk_bf16_f32 v84, v74, v75
	v_lshl_add_u64 v[74:75], s[24:25], 0, v[140:141]
	v_lshl_add_u64 v[74:75], v[74:75], 4, s[38:39]
	v_cvt_pk_bf16_f32 v85, v76, v77
	global_store_dwordx4 v[74:75], v[82:85], off
	v_cvt_pk_bf16_f32 v74, v86, v87
	v_cvt_pk_bf16_f32 v75, v88, v89
	v_cvt_pk_bf16_f32 v76, v78, v79
	v_lshl_add_u64 v[78:79], s[22:23], 0, v[142:143]
	v_lshl_add_u64 v[78:79], v[78:79], 4, s[38:39]
	v_cvt_pk_bf16_f32 v77, v80, v81
	global_store_dwordx4 v[78:79], v[74:77], off
	v_cvt_pk_bf16_f32 v70, v70, v71
	v_cvt_pk_bf16_f32 v71, v72, v73
	v_cvt_pk_bf16_f32 v72, v66, v67
	v_lshl_add_u64 v[66:67], s[24:25], 0, v[142:143]
	v_lshl_add_u64 v[66:67], v[66:67], 4, s[38:39]
	v_cvt_pk_bf16_f32 v73, v68, v69
	global_store_dwordx4 v[66:67], v[70:73], off
	v_cvt_pk_bf16_f32 v62, v62, v63
	v_cvt_pk_bf16_f32 v63, v64, v65
	v_cvt_pk_bf16_f32 v64, v58, v59
	v_lshl_add_u64 v[58:59], s[22:23], 0, v[144:145]
	v_lshl_add_u64 v[58:59], v[58:59], 4, s[38:39]
	v_cvt_pk_bf16_f32 v65, v60, v61
	global_store_dwordx4 v[58:59], v[62:65], off
	v_cvt_pk_bf16_f32 v50, v50, v51
	v_cvt_pk_bf16_f32 v51, v52, v53
	v_cvt_pk_bf16_f32 v52, v42, v43
	v_lshl_add_u64 v[42:43], s[24:25], 0, v[144:145]
	v_lshl_add_u64 v[42:43], v[42:43], 4, s[38:39]
	v_cvt_pk_bf16_f32 v53, v44, v45
	global_store_dwordx4 v[42:43], v[50:53], off
	v_cvt_pk_bf16_f32 v42, v54, v55
	v_cvt_pk_bf16_f32 v43, v56, v57
	v_cvt_pk_bf16_f32 v44, v46, v47
	v_lshl_add_u64 v[46:47], s[22:23], 0, v[146:147]
	v_lshl_add_u64 v[46:47], v[46:47], 4, s[38:39]
	v_cvt_pk_bf16_f32 v45, v48, v49
	global_store_dwordx4 v[46:47], v[42:45], off
	v_cvt_pk_bf16_f32 v34, v34, v35
	v_cvt_pk_bf16_f32 v35, v36, v37
	v_cvt_pk_bf16_f32 v36, v24, v25
	v_lshl_add_u64 v[24:25], s[24:25], 0, v[146:147]
	v_lshl_add_u64 v[24:25], v[24:25], 4, s[38:39]
	v_cvt_pk_bf16_f32 v37, v26, v27
	global_store_dwordx4 v[24:25], v[34:37], off
	v_cvt_pk_bf16_f32 v24, v38, v39
	v_cvt_pk_bf16_f32 v25, v40, v41
	v_cvt_pk_bf16_f32 v26, v28, v29
	v_lshl_add_u64 v[28:29], s[22:23], 0, v[148:149]
	v_lshl_add_u64 v[28:29], v[28:29], 4, s[38:39]
	v_cvt_pk_bf16_f32 v27, v30, v31
	global_store_dwordx4 v[28:29], v[24:27], off
	v_cvt_pk_bf16_f32 v16, v16, v17
	v_cvt_pk_bf16_f32 v17, v18, v19
	v_cvt_pk_bf16_f32 v18, v8, v9
	v_lshl_add_u64 v[8:9], s[24:25], 0, v[148:149]
	v_lshl_add_u64 v[8:9], v[8:9], 4, s[38:39]
	v_cvt_pk_bf16_f32 v19, v10, v11
	global_store_dwordx4 v[8:9], v[16:19], off
	v_cvt_pk_bf16_f32 v8, v20, v21
	v_cvt_pk_bf16_f32 v9, v22, v23
	v_cvt_pk_bf16_f32 v10, v12, v13
	v_lshl_add_u64 v[12:13], s[22:23], 0, v[150:151]
	v_lshl_add_u64 v[12:13], v[12:13], 4, s[38:39]
	v_cvt_pk_bf16_f32 v11, v14, v15
	global_store_dwordx4 v[12:13], v[8:11], off
	v_cvt_pk_bf16_f32 v4, v4, v5
	v_cvt_pk_bf16_f32 v5, v6, v7
	v_cvt_pk_bf16_f32 v6, v0, v1
	v_lshl_add_u64 v[0:1], s[24:25], 0, v[150:151]
	v_lshl_add_u64 v[0:1], v[0:1], 4, s[38:39]
	s_and_b64 vcc, exec, s[26:27]
	s_mov_b32 s22, s14
	s_mov_b32 s24, s20
	s_mov_b64 s[38:39], s[36:37]
	s_mov_b64 s[42:43], s[28:29]
	v_cvt_pk_bf16_f32 v7, v2, v3
	global_store_dwordx4 v[0:1], v[4:7], off
	s_cbranch_vccz .LBB0_299
	s_waitcnt vmcnt(0)
	s_cmpk_gt_u32 s5, 0xff
	s_mov_b32 s77, s13
	v_mov_b32_e32 v131, v197
	s_cbranch_scc1 .LBB0_338
	s_barrier

; #define PG8_STAGE(bufoff, gbase, voff) do { _Pragma("unroll") for (int _i = 0; _i < 2; ++_i) \
;     __builtin_amdgcn_global_load_lds((const unsigned*)((const char*)(gbase) + (voff)[_i]), (LAS unsigned*)(lds + (bufoff) + ldsw + _i * 8192), 16, 0, 0); } while (0)
; #define PG8_LDA(dst, b, h) do { _Pragma("unroll") for (int m = 0; m < 4; ++m) _Pragma("unroll") for (int k = 0; k < 2; ++k) dst[m][k] = *(const LAS bf16x8*)(lds + PG8_SA(b, h) + aoff + m * 2048 + k * 1024); } while (0)
; #define PG8_LDB(dst, b, h) do { _Pragma("unroll") for (int n = 0; n < 2; ++n) _Pragma("unroll") for (int k = 0; k < 2; ++k) dst[n][k] = *(const LAS bf16x8*)(lds + PG8_SB(b, h) + boff + n * 2048 + k * 1024); } while (0)
; #define PG8_MMA(ai, bj, At, Bt) do { __builtin_amdgcn_s_setprio(1); _Pragma("unroll") for (int m = 0; m < 4; ++m) _Pragma("unroll") for (int n = 0; n < 2; ++n) _Pragma("unroll") for (int k = 0; k < 2; ++k) \
;     acc[ai][bj][m][n] = __builtin_amdgcn_mfma_f32_16x16x32_bf16(Bt[n][k], At[m][k], acc[ai][bj][m][n], 0, 0, 0); __builtin_amdgcn_s_setprio(0); } while (0)
; #define PG8_WAIT_V(n) asm volatile("s_waitcnt vmcnt(" #n ")" ::: "memory")
; #define PG8_WAIT_L(n) asm volatile("s_waitcnt lgkmcnt(" #n ")" ::: "memory")
; #define PG8_BAR __builtin_amdgcn_s_barrier()
; template <class Epi, class Sched, bool ABLK = false>
; __device__ __forceinline__ void gemm_phase(LAS unsigned char* lds, const Gemm g, const Sched& S, const Epi& E) {
;     ...
;     for (int t = 0; t < nt; t += 2) {
;       const bool last = (t == nt - 2);
;       const char* a1 = cA + (size_t)(t + 1) * kstep;
;       const char* a2 = last ? nA : cA + (size_t)(t + 2) * kstep; const char* b2 = last ? nB : cB + (size_t)(t + 2) * kstepB;
;       const char* a3 = a2 + kstep; const char* b3 = b2 + kstepB;
;       PG8_LDB(B0, 0, 0); PG8_SCHED; PG8_LDA(At, 0, 0); PG8_STAGE(PG8_SA(1, 1), a1 + hstep, voffA);
;       PG8_WAIT_L(8); PG8_BAR; PG8_WAIT_L(0); PG8_MMA(0, 0, At, B0); PG8_BAR; PG8_SCHED;
;       PG8_LDB(B1, 0, 1); PG8_STAGE(PG8_SB(0, 0), b2, voffB);
;       PG8_BAR; PG8_WAIT_L(0); PG8_MMA(0, 1, At, B1); PG8_BAR;
;       PG8_LDA(At, 0, 1); PG8_STAGE(PG8_SA(0, 0), a2, voffA);
;       PG8_BAR; PG8_WAIT_L(0); PG8_MMA(1, 0, At, B0); PG8_BAR; PG8_SCHED;
;       PG8_STAGE(PG8_SB(0, 1), b2 + hstepB, voffB);
;       PG8_WAIT_V(6); PG8_BAR; PG8_MMA(1, 1, At, B1); PG8_BAR;
.LBB0_410:
	s_add_u32 s42, s38, 0xfffe0080
	s_addc_u32 s43, s39, -1
	s_add_i32 s47, 0, 0x10000
	v_add_u32_e32 v159, s47, v156
	ds_read_b128 v[160:163], v159
	ds_read_b128 v[164:167], v159 offset:1024
	ds_read_b128 v[168:171], v159 offset:2048
	ds_read_b128 v[172:175], v159 offset:3072
	s_cmp_eq_u32 s46, 4
	s_cselect_b32 s45, s29, s43
	s_cselect_b32 s44, s28, s42
	s_cselect_b32 s43, s15, s25
	s_cselect_b32 s42, s21, s23
	v_lshl_add_u64 v[198:199], s[38:39], 0, v[152:153]
	s_add_i32 m0, s11, 0xc000
	ds_read_b128 v[176:179], v158
	ds_read_b128 v[180:183], v158 offset:1024
	ds_read_b128 v[184:187], v158 offset:2048
	ds_read_b128 v[188:191], v158 offset:3072
	ds_read_b128 v[192:195], v158 offset:4096
	ds_read_b128 v[208:211], v158 offset:5120
	ds_read_b128 v[212:215], v158 offset:6144
	ds_read_b128 v[216:219], v158 offset:7168
	global_load_lds_dwordx4 v[198:199], off
	v_lshl_add_u64 v[198:199], s[38:39], 0, v[154:155]
	s_add_i32 m0, s11, 0xe000
	s_nop 0
	global_load_lds_dwordx4 v[198:199], off
	s_waitcnt lgkmcnt(8)
	s_barrier
	s_waitcnt lgkmcnt(0)
	s_waitcnt lgkmcnt(0)
	v_mfma_f32_16x16x32_bf16 v[126:129], v[160:163], v[176:179], v[126:129]
	v_mfma_f32_16x16x32_bf16 v[122:125], v[168:171], v[176:179], v[122:125]
	v_mfma_f32_16x16x32_bf16 v[114:117], v[160:163], v[184:187], v[114:117]
	v_mfma_f32_16x16x32_bf16 v[106:109], v[168:171], v[184:187], v[106:109]
	v_mfma_f32_16x16x32_bf16 v[102:105], v[160:163], v[192:195], v[102:105]
	v_mfma_f32_16x16x32_bf16 v[94:97], v[168:171], v[192:195], v[94:97]
	v_mfma_f32_16x16x32_bf16 v[86:89], v[160:163], v[212:215], v[86:89]
	v_mfma_f32_16x16x32_bf16 v[78:81], v[168:171], v[212:215], v[78:81]
	v_mfma_f32_16x16x32_bf16 v[126:129], v[164:167], v[180:183], v[126:129]
	v_mfma_f32_16x16x32_bf16 v[122:125], v[172:175], v[180:183], v[122:125]
	v_mfma_f32_16x16x32_bf16 v[114:117], v[164:167], v[188:191], v[114:117]
	v_mfma_f32_16x16x32_bf16 v[106:109], v[172:175], v[188:191], v[106:109]
	v_mfma_f32_16x16x32_bf16 v[102:105], v[164:167], v[208:211], v[102:105]
	v_mfma_f32_16x16x32_bf16 v[94:97], v[172:175], v[208:211], v[94:97]
	v_mfma_f32_16x16x32_bf16 v[86:89], v[164:167], v[216:219], v[86:89]
	v_mfma_f32_16x16x32_bf16 v[78:81], v[172:175], v[216:219], v[78:81]
	s_barrier
	s_add_i32 s50, 0, 0x14000
	s_add_i32 s47, s47, s7
	v_add_u32_e32 v159, s50, v156
	v_lshl_add_u64 v[198:199], s[42:43], 0, v[130:131]
	s_mov_b32 m0, s47
	ds_read_b128 v[220:223], v159
	ds_read_b128 v[224:227], v159 offset:1024
	ds_read_b128 v[228:231], v159 offset:2048
	ds_read_b128 v[232:235], v159 offset:3072
	global_load_lds_dwordx4 v[198:199], off
	v_lshl_add_u64 v[198:199], s[42:43], 0, v[134:135]
	s_add_i32 m0, s47, 0x2000
	s_nop 0
	global_load_lds_dwordx4 v[198:199], off
	s_barrier
	s_waitcnt lgkmcnt(0)
	s_waitcnt lgkmcnt(0)
	v_mfma_f32_16x16x32_bf16 v[118:121], v[220:223], v[176:179], v[118:121]
	v_mfma_f32_16x16x32_bf16 v[110:113], v[228:231], v[176:179], v[110:113]
	v_mfma_f32_16x16x32_bf16 v[98:101], v[220:223], v[184:187], v[98:101]
	v_mfma_f32_16x16x32_bf16 v[90:93], v[228:231], v[184:187], v[90:93]
	v_mfma_f32_16x16x32_bf16 v[82:85], v[220:223], v[192:195], v[82:85]
	v_mfma_f32_16x16x32_bf16 v[74:77], v[228:231], v[192:195], v[74:77]
	v_mfma_f32_16x16x32_bf16 v[70:73], v[220:223], v[212:215], v[70:73]
	v_mfma_f32_16x16x32_bf16 v[66:69], v[228:231], v[212:215], v[66:69]
	v_mfma_f32_16x16x32_bf16 v[118:121], v[224:227], v[180:183], v[118:121]
	v_mfma_f32_16x16x32_bf16 v[110:113], v[232:235], v[180:183], v[110:113]
	v_mfma_f32_16x16x32_bf16 v[98:101], v[224:227], v[188:191], v[98:101]
	v_mfma_f32_16x16x32_bf16 v[90:93], v[232:235], v[188:191], v[90:93]
	v_mfma_f32_16x16x32_bf16 v[82:85], v[224:227], v[208:211], v[82:85]
	v_mfma_f32_16x16x32_bf16 v[74:77], v[232:235], v[208:211], v[74:77]
	v_mfma_f32_16x16x32_bf16 v[70:73], v[224:227], v[216:219], v[70:73]
	v_mfma_f32_16x16x32_bf16 v[66:69], v[232:235], v[216:219], v[66:69]
	s_mov_b32 m0, s11
	v_lshl_add_u64 v[198:199], s[44:45], 0, v[32:33]
	s_barrier
	ds_read_b128 v[176:179], v158 offset:16384
	ds_read_b128 v[180:183], v158 offset:17408
	ds_read_b128 v[184:187], v158 offset:18432
	ds_read_b128 v[188:191], v158 offset:19456
	ds_read_b128 v[192:195], v158 offset:20480
	ds_read_b128 v[208:211], v158 offset:21504
	ds_read_b128 v[212:215], v158 offset:22528
	ds_read_b128 v[216:219], v158 offset:23552
	global_load_lds_dwordx4 v[198:199], off
	v_lshl_add_u64 v[236:237], s[44:45], 0, v[132:133]
	s_mov_b32 m0, s17
	s_nop 0
	global_load_lds_dwordx4 v[236:237], off
	s_barrier
	s_waitcnt lgkmcnt(0)
	s_waitcnt lgkmcnt(0)
	v_mfma_f32_16x16x32_bf16 v[62:65], v[160:163], v[176:179], v[62:65]
	v_mfma_f32_16x16x32_bf16 v[58:61], v[168:171], v[176:179], v[58:61]
	v_mfma_f32_16x16x32_bf16 v[54:57], v[160:163], v[184:187], v[54:57]
	v_mfma_f32_16x16x32_bf16 v[46:49], v[168:171], v[184:187], v[46:49]
	v_mfma_f32_16x16x32_bf16 v[38:41], v[160:163], v[192:195], v[38:41]
	v_mfma_f32_16x16x32_bf16 v[28:31], v[168:171], v[192:195], v[28:31]
	v_mfma_f32_16x16x32_bf16 v[20:23], v[160:163], v[212:215], v[20:23]
	v_mfma_f32_16x16x32_bf16 v[12:15], v[168:171], v[212:215], v[12:15]
	v_mfma_f32_16x16x32_bf16 v[62:65], v[164:167], v[180:183], v[62:65]
	v_mfma_f32_16x16x32_bf16 v[58:61], v[172:175], v[180:183], v[58:61]
	v_mfma_f32_16x16x32_bf16 v[54:57], v[164:167], v[188:191], v[54:57]
	v_mfma_f32_16x16x32_bf16 v[46:49], v[172:175], v[188:191], v[46:49]
	v_mfma_f32_16x16x32_bf16 v[38:41], v[164:167], v[208:211], v[38:41]
	v_mfma_f32_16x16x32_bf16 v[28:31], v[172:175], v[208:211], v[28:31]
	v_mfma_f32_16x16x32_bf16 v[20:23], v[164:167], v[216:219], v[20:23]
	v_mfma_f32_16x16x32_bf16 v[12:15], v[172:175], v[216:219], v[12:15]
	s_barrier
; #define PG8_STAGE(bufoff, gbase, voff) do { _Pragma("unroll") for (int _i = 0; _i < 2; ++_i) \
;     __builtin_amdgcn_global_load_lds((const unsigned*)((const char*)(gbase) + (voff)[_i]), (LAS unsigned*)(lds + (bufoff) + ldsw + _i * 8192), 16, 0, 0); } while (0)
; #define PG8_LDA(dst, b, h) do { _Pragma("unroll") for (int m = 0; m < 4; ++m) _Pragma("unroll") for (int k = 0; k < 2; ++k) dst[m][k] = *(const LAS bf16x8*)(lds + PG8_SA(b, h) + aoff + m * 2048 + k * 1024); } while (0)
; #define PG8_LDB(dst, b, h) do { _Pragma("unroll") for (int n = 0; n < 2; ++n) _Pragma("unroll") for (int k = 0; k < 2; ++k) dst[n][k] = *(const LAS bf16x8*)(lds + PG8_SB(b, h) + boff + n * 2048 + k * 1024); } while (0)
; #define PG8_MMA(ai, bj, At, Bt) do { __builtin_amdgcn_s_setprio(1); _Pragma("unroll") for (int m = 0; m < 4; ++m) _Pragma("unroll") for (int n = 0; n < 2; ++n) _Pragma("unroll") for (int k = 0; k < 2; ++k) \
;     acc[ai][bj][m][n] = __builtin_amdgcn_mfma_f32_16x16x32_bf16(Bt[n][k], At[m][k], acc[ai][bj][m][n], 0, 0, 0); __builtin_amdgcn_s_setprio(0); } while (0)
; #define PG8_WAIT_V(n) asm volatile("s_waitcnt vmcnt(" #n ")" ::: "memory")
; #define PG8_WAIT_L(n) asm volatile("s_waitcnt lgkmcnt(" #n ")" ::: "memory")
; #define PG8_BAR __builtin_amdgcn_s_barrier()
; #define PG8_SCHED __builtin_amdgcn_sched_barrier(0)
; template <class Epi, class Sched, bool ABLK = false>
; __device__ __forceinline__ void gemm_phase(LAS unsigned char* lds, const Gemm g, const Sched& S, const Epi& E) {
;     ...
;       PG8_WAIT_V(6); PG8_BAR; PG8_MMA(1, 1, At, B1); PG8_BAR;
;       PG8_LDB(B0, 1, 0); PG8_SCHED; PG8_LDA(At, 1, 0); PG8_STAGE(PG8_SA(0, 1), a2 + hstep, voffA);
;       PG8_WAIT_L(8); PG8_BAR; PG8_WAIT_L(0); PG8_MMA(0, 0, At, B0); PG8_BAR; PG8_SCHED;
;       PG8_LDB(B1, 1, 1); PG8_STAGE(PG8_SB(1, 0), b3, voffB);
;       PG8_BAR; PG8_WAIT_L(0); PG8_MMA(0, 1, At, B1); PG8_BAR;
;       PG8_LDA(At, 1, 1); PG8_STAGE(PG8_SA(1, 0), a3, voffA);
;       PG8_BAR; PG8_WAIT_L(0); PG8_MMA(1, 0, At, B0); PG8_BAR; PG8_SCHED;
	s_add_u32 s48, s42, 0x4000
	s_addc_u32 s49, s43, 0
	s_add_i32 s47, s50, s7
	v_lshl_add_u64 v[160:161], s[48:49], 0, v[130:131]
	s_mov_b32 m0, s47
	s_nop 0
	global_load_lds_dwordx4 v[160:161], off
	v_lshl_add_u64 v[160:161], s[48:49], 0, v[134:135]
	s_add_i32 m0, s47, 0x2000
	s_nop 0
	global_load_lds_dwordx4 v[160:161], off
	s_waitcnt vmcnt(6)
	s_barrier
	v_mfma_f32_16x16x32_bf16 v[50:53], v[220:223], v[176:179], v[50:53]
	v_mfma_f32_16x16x32_bf16 v[42:45], v[228:231], v[176:179], v[42:45]
	v_mfma_f32_16x16x32_bf16 v[34:37], v[220:223], v[184:187], v[34:37]
	v_mfma_f32_16x16x32_bf16 v[24:27], v[228:231], v[184:187], v[24:27]
	v_mfma_f32_16x16x32_bf16 v[16:19], v[220:223], v[192:195], v[16:19]
	v_mfma_f32_16x16x32_bf16 v[8:11], v[228:231], v[192:195], v[8:11]
	v_mfma_f32_16x16x32_bf16 v[4:7], v[220:223], v[212:215], v[4:7]
	v_mfma_f32_16x16x32_bf16 v[0:3], v[228:231], v[212:215], v[0:3]
	v_mfma_f32_16x16x32_bf16 v[50:53], v[224:227], v[180:183], v[50:53]
	v_mfma_f32_16x16x32_bf16 v[42:45], v[232:235], v[180:183], v[42:45]
	v_mfma_f32_16x16x32_bf16 v[34:37], v[224:227], v[188:191], v[34:37]
	v_mfma_f32_16x16x32_bf16 v[24:27], v[232:235], v[188:191], v[24:27]
	v_mfma_f32_16x16x32_bf16 v[16:19], v[224:227], v[208:211], v[16:19]
	v_mfma_f32_16x16x32_bf16 v[8:11], v[232:235], v[208:211], v[8:11]
	v_mfma_f32_16x16x32_bf16 v[4:7], v[224:227], v[216:219], v[4:7]
	v_mfma_f32_16x16x32_bf16 v[0:3], v[232:235], v[216:219], v[0:3]
	s_add_i32 s47, 0, 0x18000
	v_add_u32_e32 v159, s47, v156
	s_barrier
	ds_read_b128 v[160:163], v159
	ds_read_b128 v[164:167], v159 offset:1024
	ds_read_b128 v[168:171], v159 offset:2048
	ds_read_b128 v[172:175], v159 offset:3072
	s_add_u32 s44, s44, 0x20000
	s_addc_u32 s45, s45, 0
	s_mov_b32 m0, s31
	v_lshl_add_u64 v[220:221], s[44:45], 0, v[32:33]
	ds_read_b128 v[176:179], v158 offset:32768
	ds_read_b128 v[180:183], v158 offset:33792
	ds_read_b128 v[184:187], v158 offset:34816
	ds_read_b128 v[188:191], v158 offset:35840
	ds_read_b128 v[192:195], v158 offset:36864
	ds_read_b128 v[208:211], v158 offset:37888
	ds_read_b128 v[212:215], v158 offset:38912
	ds_read_b128 v[216:219], v158 offset:39936
	global_load_lds_dwordx4 v[220:221], off
	v_lshl_add_u64 v[220:221], s[44:45], 0, v[132:133]
	s_mov_b32 m0, s56
	s_nop 0
	global_load_lds_dwordx4 v[220:221], off
	s_waitcnt lgkmcnt(8)
	s_barrier
	s_waitcnt lgkmcnt(0)
	s_waitcnt lgkmcnt(0)
	v_mfma_f32_16x16x32_bf16 v[126:129], v[160:163], v[176:179], v[126:129]
	v_mfma_f32_16x16x32_bf16 v[122:125], v[168:171], v[176:179], v[122:125]
	v_mfma_f32_16x16x32_bf16 v[114:117], v[160:163], v[184:187], v[114:117]
	v_mfma_f32_16x16x32_bf16 v[106:109], v[168:171], v[184:187], v[106:109]
	v_mfma_f32_16x16x32_bf16 v[102:105], v[160:163], v[192:195], v[102:105]
	v_mfma_f32_16x16x32_bf16 v[94:97], v[168:171], v[192:195], v[94:97]
	v_mfma_f32_16x16x32_bf16 v[86:89], v[160:163], v[212:215], v[86:89]
	v_mfma_f32_16x16x32_bf16 v[78:81], v[168:171], v[212:215], v[78:81]
	v_mfma_f32_16x16x32_bf16 v[126:129], v[164:167], v[180:183], v[126:129]
	v_mfma_f32_16x16x32_bf16 v[122:125], v[172:175], v[180:183], v[122:125]
	v_mfma_f32_16x16x32_bf16 v[114:117], v[164:167], v[188:191], v[114:117]
	v_mfma_f32_16x16x32_bf16 v[106:109], v[172:175], v[188:191], v[106:109]
	v_mfma_f32_16x16x32_bf16 v[102:105], v[164:167], v[208:211], v[102:105]
	v_mfma_f32_16x16x32_bf16 v[94:97], v[172:175], v[208:211], v[94:97]
	v_mfma_f32_16x16x32_bf16 v[86:89], v[164:167], v[216:219], v[86:89]
	v_mfma_f32_16x16x32_bf16 v[78:81], v[172:175], v[216:219], v[78:81]
	s_barrier
	s_add_i32 s48, 0, 0x1c000
	s_add_u32 s44, s42, 0x8000
	s_addc_u32 s45, s43, 0
	s_add_i32 s47, s47, s7
	v_add_u32_e32 v159, s48, v156
	v_lshl_add_u64 v[238:239], s[44:45], 0, v[130:131]
	s_mov_b32 m0, s47
	ds_read_b128 v[220:223], v159
	ds_read_b128 v[224:227], v159 offset:1024
	ds_read_b128 v[228:231], v159 offset:2048
	ds_read_b128 v[232:235], v159 offset:3072
	global_load_lds_dwordx4 v[238:239], off
	v_lshl_add_u64 v[238:239], s[44:45], 0, v[134:135]
	s_add_i32 m0, s47, 0x2000
	s_nop 0
	global_load_lds_dwordx4 v[238:239], off
	s_barrier
	s_waitcnt lgkmcnt(0)
	s_waitcnt lgkmcnt(0)
	v_mfma_f32_16x16x32_bf16 v[118:121], v[220:223], v[176:179], v[118:121]
	v_mfma_f32_16x16x32_bf16 v[110:113], v[228:231], v[176:179], v[110:113]
	v_mfma_f32_16x16x32_bf16 v[98:101], v[220:223], v[184:187], v[98:101]
	v_mfma_f32_16x16x32_bf16 v[90:93], v[228:231], v[184:187], v[90:93]
	v_mfma_f32_16x16x32_bf16 v[82:85], v[220:223], v[192:195], v[82:85]
	v_mfma_f32_16x16x32_bf16 v[74:77], v[228:231], v[192:195], v[74:77]
	v_mfma_f32_16x16x32_bf16 v[70:73], v[220:223], v[212:215], v[70:73]
	v_mfma_f32_16x16x32_bf16 v[66:69], v[228:231], v[212:215], v[66:69]
	v_mfma_f32_16x16x32_bf16 v[118:121], v[224:227], v[180:183], v[118:121]
	v_mfma_f32_16x16x32_bf16 v[110:113], v[232:235], v[180:183], v[110:113]
	v_mfma_f32_16x16x32_bf16 v[98:101], v[224:227], v[188:191], v[98:101]
	v_mfma_f32_16x16x32_bf16 v[90:93], v[232:235], v[188:191], v[90:93]
	v_mfma_f32_16x16x32_bf16 v[82:85], v[224:227], v[208:211], v[82:85]
	v_mfma_f32_16x16x32_bf16 v[74:77], v[232:235], v[208:211], v[74:77]
	v_mfma_f32_16x16x32_bf16 v[70:73], v[224:227], v[216:219], v[70:73]
	v_mfma_f32_16x16x32_bf16 v[66:69], v[232:235], v[216:219], v[66:69]
	s_mov_b32 m0, s69
	v_lshl_add_u64 v[198:199], v[198:199], 0, s[52:53]
	s_barrier
	ds_read_b128 v[176:179], v158 offset:49152
	ds_read_b128 v[180:183], v158 offset:50176
	ds_read_b128 v[184:187], v158 offset:51200
	ds_read_b128 v[188:191], v158 offset:52224
	ds_read_b128 v[192:195], v158 offset:53248
	ds_read_b128 v[208:211], v158 offset:54272
	ds_read_b128 v[212:215], v158 offset:55296
	ds_read_b128 v[216:219], v158 offset:56320
	global_load_lds_dwordx4 v[198:199], off
	v_lshl_add_u64 v[198:199], v[236:237], 0, s[52:53]
	s_mov_b32 m0, s77
	s_nop 0
	global_load_lds_dwordx4 v[198:199], off
	s_barrier
; #define PG8_STAGE(bufoff, gbase, voff) do { _Pragma("unroll") for (int _i = 0; _i < 2; ++_i) \
;     __builtin_amdgcn_global_load_lds((const unsigned*)((const char*)(gbase) + (voff)[_i]), (LAS unsigned*)(lds + (bufoff) + ldsw + _i * 8192), 16, 0, 0); } while (0)
; #define PG8_MMA(ai, bj, At, Bt) do { __builtin_amdgcn_s_setprio(1); _Pragma("unroll") for (int m = 0; m < 4; ++m) _Pragma("unroll") for (int n = 0; n < 2; ++n) _Pragma("unroll") for (int k = 0; k < 2; ++k) \
;     acc[ai][bj][m][n] = __builtin_amdgcn_mfma_f32_16x16x32_bf16(Bt[n][k], At[m][k], acc[ai][bj][m][n], 0, 0, 0); __builtin_amdgcn_s_setprio(0); } while (0)
; #define PG8_WAIT_V(n) asm volatile("s_waitcnt vmcnt(" #n ")" ::: "memory")
; #define PG8_WAIT_L(n) asm volatile("s_waitcnt lgkmcnt(" #n ")" ::: "memory")
; #define PG8_BAR __builtin_amdgcn_s_barrier()
; #define PG8_SCHED __builtin_amdgcn_sched_barrier(0)
; template <class Epi, class Sched, bool ABLK = false>
; __device__ __forceinline__ void gemm_phase(LAS unsigned char* lds, const Gemm g, const Sched& S, const Epi& E) {
;     ...
;       PG8_BAR; PG8_WAIT_L(0); PG8_MMA(1, 0, At, B0); PG8_BAR; PG8_SCHED;
;       PG8_STAGE(PG8_SB(1, 1), b3 + hstepB, voffB);
;       PG8_WAIT_V(6); PG8_BAR; PG8_MMA(1, 1, At, B1); PG8_BAR;
;     }
	s_waitcnt lgkmcnt(0)
	s_waitcnt lgkmcnt(0)
	v_mfma_f32_16x16x32_bf16 v[62:65], v[160:163], v[176:179], v[62:65]
	v_mfma_f32_16x16x32_bf16 v[58:61], v[168:171], v[176:179], v[58:61]
	v_mfma_f32_16x16x32_bf16 v[54:57], v[160:163], v[184:187], v[54:57]
	v_mfma_f32_16x16x32_bf16 v[46:49], v[168:171], v[184:187], v[46:49]
	v_mfma_f32_16x16x32_bf16 v[38:41], v[160:163], v[192:195], v[38:41]
	v_mfma_f32_16x16x32_bf16 v[28:31], v[168:171], v[192:195], v[28:31]
	v_mfma_f32_16x16x32_bf16 v[20:23], v[160:163], v[212:215], v[20:23]
	v_mfma_f32_16x16x32_bf16 v[12:15], v[168:171], v[212:215], v[12:15]
	v_mfma_f32_16x16x32_bf16 v[62:65], v[164:167], v[180:183], v[62:65]
	v_mfma_f32_16x16x32_bf16 v[58:61], v[172:175], v[180:183], v[58:61]
	v_mfma_f32_16x16x32_bf16 v[54:57], v[164:167], v[188:191], v[54:57]
	v_mfma_f32_16x16x32_bf16 v[46:49], v[172:175], v[188:191], v[46:49]
	v_mfma_f32_16x16x32_bf16 v[38:41], v[164:167], v[208:211], v[38:41]
	v_mfma_f32_16x16x32_bf16 v[28:31], v[172:175], v[208:211], v[28:31]
	v_mfma_f32_16x16x32_bf16 v[20:23], v[164:167], v[216:219], v[20:23]
	v_mfma_f32_16x16x32_bf16 v[12:15], v[172:175], v[216:219], v[12:15]
	s_barrier
	s_add_u32 s42, s42, 0xc000
	s_addc_u32 s43, s43, 0
	s_add_i32 s44, s48, s7
	v_lshl_add_u64 v[160:161], s[42:43], 0, v[130:131]
	s_mov_b32 m0, s44
	s_nop 0
	global_load_lds_dwordx4 v[160:161], off
	v_lshl_add_u64 v[160:161], s[42:43], 0, v[134:135]
	s_add_i32 m0, s44, 0x2000
	s_nop 0
	global_load_lds_dwordx4 v[160:161], off
	s_waitcnt vmcnt(6)
	s_barrier
	v_mfma_f32_16x16x32_bf16 v[50:53], v[220:223], v[176:179], v[50:53]
	v_mfma_f32_16x16x32_bf16 v[42:45], v[228:231], v[176:179], v[42:45]
	v_mfma_f32_16x16x32_bf16 v[34:37], v[220:223], v[184:187], v[34:37]
	v_mfma_f32_16x16x32_bf16 v[24:27], v[228:231], v[184:187], v[24:27]
	v_mfma_f32_16x16x32_bf16 v[16:19], v[220:223], v[192:195], v[16:19]
	v_mfma_f32_16x16x32_bf16 v[8:11], v[228:231], v[192:195], v[8:11]
	v_mfma_f32_16x16x32_bf16 v[4:7], v[220:223], v[212:215], v[4:7]
	v_mfma_f32_16x16x32_bf16 v[0:3], v[228:231], v[212:215], v[0:3]
	v_mfma_f32_16x16x32_bf16 v[50:53], v[224:227], v[180:183], v[50:53]
	v_mfma_f32_16x16x32_bf16 v[42:45], v[232:235], v[180:183], v[42:45]
	v_mfma_f32_16x16x32_bf16 v[34:37], v[224:227], v[188:191], v[34:37]
	v_mfma_f32_16x16x32_bf16 v[24:27], v[232:235], v[188:191], v[24:27]
	v_mfma_f32_16x16x32_bf16 v[16:19], v[224:227], v[208:211], v[16:19]
	v_mfma_f32_16x16x32_bf16 v[8:11], v[232:235], v[208:211], v[8:11]
	v_mfma_f32_16x16x32_bf16 v[4:7], v[224:227], v[216:219], v[4:7]
	v_mfma_f32_16x16x32_bf16 v[0:3], v[232:235], v[216:219], v[0:3]
	s_add_i32 s46, s46, 2
	s_add_u32 s23, s23, 0x10000
	s_addc_u32 s25, s25, 0
	s_add_u32 s38, s38, 0x100
	s_addc_u32 s39, s39, 0
	s_cmp_gt_u32 s46, 5
	s_barrier
	s_cbranch_scc0 .LBB0_410
; __device__ __forceinline__ unsigned cvt_pk_bf16(float lo, float hi) { unsigned r; asm volatile("v_cvt_pk_bf16_f32 %0, %1, %2" : "=v"(r) : "v"(lo), "v"(hi)); return r; }
; #define PG8_WAIT_V(n) asm volatile("s_waitcnt vmcnt(" #n ")" ::: "memory")
; #define PG8_BAR __builtin_amdgcn_s_barrier()
;   __device__ __forceinline__ float2 operator()(int i) const { const float2 wv = unpk2(Wd[i]); return half ? cmul(wv, twid((float)(i & (L - 1)) * invTurn)) : wv; }
; template <class Epi, class Sched, bool ABLK = false>
; __device__ __forceinline__ void gemm_phase(LAS unsigned char* lds, const Gemm g, const Sched& S, const Epi& E) {
;     ...
;     cur = nxt; cA = nA; cB = nB; ++ui;
;   }
;   PG8_WAIT_V(0);
;   if (wr == 0) PG8_BAR;
;   PG8_BAR;
;   __device__ __forceinline__ void operator()(const f32x4 (&acc)[2][2][4][2], const Unit& u, int wr, int wc, int fr, int fq) const {
;     const int wave = wr * 4 + wc, lane = fq * 16 + fr;
; #pragma unroll
;     for (int ai = 0; ai < 2; ++ai)
; #pragma unroll
;       for (int m = 0; m < 4; ++m)
; #pragma unroll
;         for (int bj = 0; bj < 2; ++bj) { const f32x4 v0 = acc[ai][bj][m][0], v1 = acc[ai][bj][m][1];
;           u32x4 w; w.x = cvt_pk_bf16(v0[0], v0[1]); w.y = cvt_pk_bf16(v0[2], v0[3]); w.z = cvt_pk_bf16(v1[0], v1[1]); w.w = cvt_pk_bf16(v1[2], v1[3]);
;           const size_t idx = ((((size_t)(u.pm * 16 + 2 * u.pn + bj) * 2 + ai) * 4 + m) * 8 + wave) * 64 + lane;
;           *(u32x4*)(O + idx * 8) = w; }
;   }
	s_lshl_b32 s15, s24, 4
	s_lshl_b32 s21, s22, 1
	s_add_i32 s24, s15, s21
	s_ashr_i32 s25, s24, 31
	s_lshl_b64 s[22:23], s[24:25], 12
	v_readlane_b32 s38, v252, 38
	s_or_b32 s24, s24, 1
	v_cvt_pk_bf16_f32 v126, v126, v127
	v_cvt_pk_bf16_f32 v127, v128, v129
	v_cvt_pk_bf16_f32 v128, v122, v123
	v_lshl_add_u64 v[122:123], s[22:23], 0, v[136:137]
	v_readlane_b32 s39, v252, 39
	s_ashr_i32 s25, s24, 31
	s_lshl_b64 s[24:25], s[24:25], 12
	v_lshl_add_u64 v[122:123], v[122:123], 4, s[38:39]
	v_cvt_pk_bf16_f32 v129, v124, v125
	global_store_dwordx4 v[122:123], v[126:129], off
	v_cvt_pk_bf16_f32 v118, v118, v119
	v_cvt_pk_bf16_f32 v119, v120, v121
	v_cvt_pk_bf16_f32 v120, v110, v111
	v_lshl_add_u64 v[110:111], s[24:25], 0, v[136:137]
	v_lshl_add_u64 v[110:111], v[110:111], 4, s[38:39]
	v_cvt_pk_bf16_f32 v121, v112, v113
	global_store_dwordx4 v[110:111], v[118:121], off
	v_cvt_pk_bf16_f32 v110, v114, v115
	v_cvt_pk_bf16_f32 v111, v116, v117
	v_cvt_pk_bf16_f32 v112, v106, v107
	v_lshl_add_u64 v[106:107], s[22:23], 0, v[138:139]
	v_lshl_add_u64 v[106:107], v[106:107], 4, s[38:39]
	v_cvt_pk_bf16_f32 v113, v108, v109
	global_store_dwordx4 v[106:107], v[110:113], off
	v_cvt_pk_bf16_f32 v98, v98, v99
	v_cvt_pk_bf16_f32 v99, v100, v101
	v_cvt_pk_bf16_f32 v100, v90, v91
	v_lshl_add_u64 v[90:91], s[24:25], 0, v[138:139]
	v_lshl_add_u64 v[90:91], v[90:91], 4, s[38:39]
	v_cvt_pk_bf16_f32 v101, v92, v93
	global_store_dwordx4 v[90:91], v[98:101], off
	v_cvt_pk_bf16_f32 v90, v102, v103
	v_cvt_pk_bf16_f32 v91, v104, v105
	v_cvt_pk_bf16_f32 v92, v94, v95
	v_lshl_add_u64 v[94:95], s[22:23], 0, v[140:141]
	v_lshl_add_u64 v[94:95], v[94:95], 4, s[38:39]
	v_cvt_pk_bf16_f32 v93, v96, v97
	global_store_dwordx4 v[94:95], v[90:93], off
	v_cvt_pk_bf16_f32 v82, v82, v83
	v_cvt_pk_bf16_f32 v83, v84, v85
	v_cvt_pk_bf16_f32 v84, v74, v75
	v_lshl_add_u64 v[74:75], s[24:25], 0, v[140:141]
	v_lshl_add_u64 v[74:75], v[74:75], 4, s[38:39]
	v_cvt_pk_bf16_f32 v85, v76, v77
	global_store_dwordx4 v[74:75], v[82:85], off
	v_cvt_pk_bf16_f32 v74, v86, v87
	v_cvt_pk_bf16_f32 v75, v88, v89
	v_cvt_pk_bf16_f32 v76, v78, v79
	v_lshl_add_u64 v[78:79], s[22:23], 0, v[142:143]
	v_lshl_add_u64 v[78:79], v[78:79], 4, s[38:39]
	v_cvt_pk_bf16_f32 v77, v80, v81
	global_store_dwordx4 v[78:79], v[74:77], off
	v_cvt_pk_bf16_f32 v70, v70, v71
	v_cvt_pk_bf16_f32 v71, v72, v73
	v_cvt_pk_bf16_f32 v72, v66, v67
	v_lshl_add_u64 v[66:67], s[24:25], 0, v[142:143]
	v_lshl_add_u64 v[66:67], v[66:67], 4, s[38:39]
	v_cvt_pk_bf16_f32 v73, v68, v69
	global_store_dwordx4 v[66:67], v[70:73], off
	v_cvt_pk_bf16_f32 v62, v62, v63
	v_cvt_pk_bf16_f32 v63, v64, v65
	v_cvt_pk_bf16_f32 v64, v58, v59
	v_lshl_add_u64 v[58:59], s[22:23], 0, v[144:145]
	v_lshl_add_u64 v[58:59], v[58:59], 4, s[38:39]
	v_cvt_pk_bf16_f32 v65, v60, v61
	global_store_dwordx4 v[58:59], v[62:65], off
	v_cvt_pk_bf16_f32 v50, v50, v51
	v_cvt_pk_bf16_f32 v51, v52, v53
	v_cvt_pk_bf16_f32 v52, v42, v43
	v_lshl_add_u64 v[42:43], s[24:25], 0, v[144:145]
	v_lshl_add_u64 v[42:43], v[42:43], 4, s[38:39]
	v_cvt_pk_bf16_f32 v53, v44, v45
	global_store_dwordx4 v[42:43], v[50:53], off
	v_cvt_pk_bf16_f32 v42, v54, v55
	v_cvt_pk_bf16_f32 v43, v56, v57
	v_cvt_pk_bf16_f32 v44, v46, v47
	v_lshl_add_u64 v[46:47], s[22:23], 0, v[146:147]
	v_lshl_add_u64 v[46:47], v[46:47], 4, s[38:39]
	v_cvt_pk_bf16_f32 v45, v48, v49
	global_store_dwordx4 v[46:47], v[42:45], off
	v_cvt_pk_bf16_f32 v34, v34, v35
	v_cvt_pk_bf16_f32 v35, v36, v37
	v_cvt_pk_bf16_f32 v36, v24, v25
	v_lshl_add_u64 v[24:25], s[24:25], 0, v[146:147]
	v_lshl_add_u64 v[24:25], v[24:25], 4, s[38:39]
	v_cvt_pk_bf16_f32 v37, v26, v27
	global_store_dwordx4 v[24:25], v[34:37], off
	v_cvt_pk_bf16_f32 v24, v38, v39
	v_cvt_pk_bf16_f32 v25, v40, v41
	v_cvt_pk_bf16_f32 v26, v28, v29
	v_lshl_add_u64 v[28:29], s[22:23], 0, v[148:149]
	v_lshl_add_u64 v[28:29], v[28:29], 4, s[38:39]
	v_cvt_pk_bf16_f32 v27, v30, v31
	global_store_dwordx4 v[28:29], v[24:27], off
	v_cvt_pk_bf16_f32 v16, v16, v17
	v_cvt_pk_bf16_f32 v17, v18, v19
	v_cvt_pk_bf16_f32 v18, v8, v9
	v_lshl_add_u64 v[8:9], s[24:25], 0, v[148:149]
	v_lshl_add_u64 v[8:9], v[8:9], 4, s[38:39]
	v_cvt_pk_bf16_f32 v19, v10, v11
	global_store_dwordx4 v[8:9], v[16:19], off
	v_cvt_pk_bf16_f32 v8, v20, v21
	v_cvt_pk_bf16_f32 v9, v22, v23
	v_cvt_pk_bf16_f32 v10, v12, v13
	v_lshl_add_u64 v[12:13], s[22:23], 0, v[150:151]
	v_lshl_add_u64 v[12:13], v[12:13], 4, s[38:39]
	v_cvt_pk_bf16_f32 v11, v14, v15
	global_store_dwordx4 v[12:13], v[8:11], off
	v_cvt_pk_bf16_f32 v4, v4, v5
	v_cvt_pk_bf16_f32 v5, v6, v7
	v_cvt_pk_bf16_f32 v6, v0, v1
	v_lshl_add_u64 v[0:1], s[24:25], 0, v[150:151]
	v_lshl_add_u64 v[0:1], v[0:1], 4, s[38:39]
	s_and_b64 vcc, exec, s[26:27]
	s_mov_b32 s22, s14
	s_mov_b32 s24, s20
	s_mov_b64 s[38:39], s[36:37]
	s_mov_b64 s[42:43], s[28:29]
	v_cvt_pk_bf16_f32 v7, v2, v3
	global_store_dwordx4 v[0:1], v[4:7], off
	s_cbranch_vccz .LBB0_375
	s_waitcnt vmcnt(0)
	s_cmpk_gt_u32 s5, 0xff
	s_mov_b32 s77, s13
	v_mov_b32_e32 v131, v197
	s_cbranch_scc1 .LBB0_414
	s_barrier

; #define PG8_STAGE(bufoff, gbase, voff) do { _Pragma("unroll") for (int _i = 0; _i < 2; ++_i) \
;     __builtin_amdgcn_global_load_lds((const unsigned*)((const char*)(gbase) + (voff)[_i]), (LAS unsigned*)(lds + (bufoff) + ldsw + _i * 8192), 16, 0, 0); } while (0)
; #define PG8_LDA(dst, b, h) do { _Pragma("unroll") for (int m = 0; m < 4; ++m) _Pragma("unroll") for (int k = 0; k < 2; ++k) dst[m][k] = *(const LAS bf16x8*)(lds + PG8_SA(b, h) + aoff + m * 2048 + k * 1024); } while (0)
; #define PG8_LDB(dst, b, h) do { _Pragma("unroll") for (int n = 0; n < 2; ++n) _Pragma("unroll") for (int k = 0; k < 2; ++k) dst[n][k] = *(const LAS bf16x8*)(lds + PG8_SB(b, h) + boff + n * 2048 + k * 1024); } while (0)
; #define PG8_MMA(ai, bj, At, Bt) do { __builtin_amdgcn_s_setprio(1); _Pragma("unroll") for (int m = 0; m < 4; ++m) _Pragma("unroll") for (int n = 0; n < 2; ++n) _Pragma("unroll") for (int k = 0; k < 2; ++k) \
;     acc[ai][bj][m][n] = __builtin_amdgcn_mfma_f32_16x16x32_bf16(Bt[n][k], At[m][k], acc[ai][bj][m][n], 0, 0, 0); __builtin_amdgcn_s_setprio(0); } while (0)
; #define PG8_WAIT_V(n) asm volatile("s_waitcnt vmcnt(" #n ")" ::: "memory")
; #define PG8_WAIT_L(n) asm volatile("s_waitcnt lgkmcnt(" #n ")" ::: "memory")
; #define PG8_BAR __builtin_amdgcn_s_barrier()
; template <class Epi, class Sched, bool ABLK = false>
; __device__ __forceinline__ void gemm_phase(LAS unsigned char* lds, const Gemm g, const Sched& S, const Epi& E) {
;     ...
;     for (int t = 0; t < nt; t += 2) {
;       const bool last = (t == nt - 2);
;       const char* a1 = cA + (size_t)(t + 1) * kstep;
;       const char* a2 = last ? nA : cA + (size_t)(t + 2) * kstep; const char* b2 = last ? nB : cB + (size_t)(t + 2) * kstepB;
;       const char* a3 = a2 + kstep; const char* b3 = b2 + kstepB;
;       PG8_LDB(B0, 0, 0); PG8_SCHED; PG8_LDA(At, 0, 0); PG8_STAGE(PG8_SA(1, 1), a1 + hstep, voffA);
;       PG8_WAIT_L(8); PG8_BAR; PG8_WAIT_L(0); PG8_MMA(0, 0, At, B0); PG8_BAR; PG8_SCHED;
;       PG8_LDB(B1, 0, 1); PG8_STAGE(PG8_SB(0, 0), b2, voffB);
;       PG8_BAR; PG8_WAIT_L(0); PG8_MMA(0, 1, At, B1); PG8_BAR;
;       PG8_LDA(At, 0, 1); PG8_STAGE(PG8_SA(0, 0), a2, voffA);
;       PG8_BAR; PG8_WAIT_L(0); PG8_MMA(1, 0, At, B0); PG8_BAR; PG8_SCHED;
;       PG8_STAGE(PG8_SB(0, 1), b2 + hstepB, voffB);
;       PG8_WAIT_V(6); PG8_BAR; PG8_MMA(1, 1, At, B1); PG8_BAR;
.LBB0_1185:
	s_add_u32 s44, s14, 0xfff80080
	s_addc_u32 s45, s15, -1
	s_add_i32 s53, 0, 0x10000
	v_add_u32_e32 v12, s53, v212
	ds_read_b128 v[0:3], v12
	ds_read_b128 v[4:7], v12 offset:1024
	ds_read_b128 v[8:11], v12 offset:2048
	ds_read_b128 v[12:15], v12 offset:3072
	s_cmp_eq_u32 s52, 28
	s_cselect_b32 s49, s39, s45
	s_cselect_b32 s48, s38, s44
	s_cselect_b32 s45, s23, s51
	s_cselect_b32 s44, s25, s50
	v_lshl_add_u64 v[194:195], s[14:15], 0, v[190:191]
	s_add_i32 m0, s11, 0xc000
	ds_read_b128 v[16:19], v218
	ds_read_b128 v[20:23], v218 offset:1024
	ds_read_b128 v[24:27], v218 offset:2048
	ds_read_b128 v[28:31], v218 offset:3072
	ds_read_b128 v[162:165], v218 offset:4096
	ds_read_b128 v[166:169], v218 offset:5120
	ds_read_b128 v[170:173], v218 offset:6144
	ds_read_b128 v[174:177], v218 offset:7168
	global_load_lds_dwordx4 v[194:195], off
	v_lshl_add_u64 v[194:195], s[14:15], 0, v[192:193]
	s_add_i32 m0, s11, 0xe000
	s_nop 0
	global_load_lds_dwordx4 v[194:195], off
	s_waitcnt lgkmcnt(8)
	s_barrier
	s_waitcnt lgkmcnt(0)
	s_waitcnt lgkmcnt(0)
	v_mfma_f32_16x16x32_bf16 v[158:161], v[0:3], v[16:19], v[158:161]
	v_mfma_f32_16x16x32_bf16 v[142:145], v[8:11], v[16:19], v[142:145]
	v_mfma_f32_16x16x32_bf16 v[154:157], v[0:3], v[24:27], v[154:157]
	v_mfma_f32_16x16x32_bf16 v[138:141], v[8:11], v[24:27], v[138:141]
	v_mfma_f32_16x16x32_bf16 v[150:153], v[0:3], v[162:165], v[150:153]
	v_mfma_f32_16x16x32_bf16 v[134:137], v[8:11], v[162:165], v[134:137]
	v_mfma_f32_16x16x32_bf16 v[146:149], v[0:3], v[170:173], v[146:149]
	v_mfma_f32_16x16x32_bf16 v[130:133], v[8:11], v[170:173], v[130:133]
	v_mfma_f32_16x16x32_bf16 v[158:161], v[4:7], v[20:23], v[158:161]
	v_mfma_f32_16x16x32_bf16 v[142:145], v[12:15], v[20:23], v[142:145]
	v_mfma_f32_16x16x32_bf16 v[154:157], v[4:7], v[28:31], v[154:157]
	v_mfma_f32_16x16x32_bf16 v[138:141], v[12:15], v[28:31], v[138:141]
	v_mfma_f32_16x16x32_bf16 v[150:153], v[4:7], v[166:169], v[150:153]
	v_mfma_f32_16x16x32_bf16 v[134:137], v[12:15], v[166:169], v[134:137]
	v_mfma_f32_16x16x32_bf16 v[146:149], v[4:7], v[174:177], v[146:149]
	v_mfma_f32_16x16x32_bf16 v[130:133], v[12:15], v[174:177], v[130:133]
	s_barrier
	s_add_i32 s58, 0, 0x14000
	v_add_u32_e32 v194, s58, v212
	s_add_i32 s53, s53, s7
	ds_read_b128 v[222:225], v194
	ds_read_b128 v[226:229], v194 offset:1024
	ds_read_b128 v[230:233], v194 offset:2048
	ds_read_b128 v[234:237], v194 offset:3072
	v_lshl_add_u64 v[194:195], s[44:45], 0, v[180:181]
	s_mov_b32 m0, s53
	s_nop 0
	global_load_lds_dwordx4 v[194:195], off
	v_lshl_add_u64 v[194:195], s[44:45], 0, v[184:185]
	s_add_i32 m0, s53, 0x2000
	s_nop 0
	global_load_lds_dwordx4 v[194:195], off
	s_barrier
	s_waitcnt lgkmcnt(0)
	s_waitcnt lgkmcnt(0)
	v_mfma_f32_16x16x32_bf16 v[126:129], v[222:225], v[16:19], v[126:129]
	v_mfma_f32_16x16x32_bf16 v[16:19], v[230:233], v[16:19], v[110:113]
	v_mfma_f32_16x16x32_bf16 v[126:129], v[226:229], v[20:23], v[126:129]
	v_mfma_f32_16x16x32_bf16 v[16:19], v[234:237], v[20:23], v[16:19]
	v_mfma_f32_16x16x32_bf16 v[20:23], v[222:225], v[24:27], v[122:125]
	v_mfma_f32_16x16x32_bf16 v[24:27], v[230:233], v[24:27], v[106:109]
	v_mfma_f32_16x16x32_bf16 v[102:105], v[230:233], v[162:165], v[102:105]
	v_mfma_f32_16x16x32_bf16 v[106:109], v[222:225], v[170:173], v[114:117]
	v_mfma_f32_16x16x32_bf16 v[98:101], v[230:233], v[170:173], v[98:101]
	v_mfma_f32_16x16x32_bf16 v[20:23], v[226:229], v[28:31], v[20:23]
	v_mfma_f32_16x16x32_bf16 v[24:27], v[234:237], v[28:31], v[24:27]
	v_mfma_f32_16x16x32_bf16 v[28:31], v[222:225], v[162:165], v[118:121]
	v_mfma_f32_16x16x32_bf16 v[102:105], v[234:237], v[166:169], v[102:105]
	v_mfma_f32_16x16x32_bf16 v[114:117], v[226:229], v[174:177], v[106:109]
	v_mfma_f32_16x16x32_bf16 v[98:101], v[234:237], v[174:177], v[98:101]
	v_mfma_f32_16x16x32_bf16 v[28:31], v[226:229], v[166:169], v[28:31]
	s_mov_b32 m0, s11
	v_lshl_add_u64 v[194:195], s[48:49], 0, v[178:179]
	s_barrier
	ds_read_b128 v[106:109], v218 offset:16384
	ds_read_b128 v[110:113], v218 offset:17408
	ds_read_b128 v[118:121], v218 offset:18432
	ds_read_b128 v[122:125], v218 offset:19456
	ds_read_b128 v[162:165], v218 offset:20480
	ds_read_b128 v[166:169], v218 offset:21504
	ds_read_b128 v[170:173], v218 offset:22528
	ds_read_b128 v[174:177], v218 offset:23552
	global_load_lds_dwordx4 v[194:195], off
	v_lshl_add_u64 v[198:199], s[48:49], 0, v[182:183]
	s_mov_b32 m0, s17
	s_nop 0
	global_load_lds_dwordx4 v[198:199], off
	s_barrier
	s_waitcnt lgkmcnt(0)
	s_waitcnt lgkmcnt(0)
	v_mfma_f32_16x16x32_bf16 v[94:97], v[0:3], v[106:109], v[94:97]
	v_mfma_f32_16x16x32_bf16 v[78:81], v[8:11], v[106:109], v[78:81]
	v_mfma_f32_16x16x32_bf16 v[90:93], v[0:3], v[118:121], v[90:93]
	v_mfma_f32_16x16x32_bf16 v[74:77], v[8:11], v[118:121], v[74:77]
	v_mfma_f32_16x16x32_bf16 v[86:89], v[0:3], v[162:165], v[86:89]
	v_mfma_f32_16x16x32_bf16 v[70:73], v[8:11], v[162:165], v[70:73]
	v_mfma_f32_16x16x32_bf16 v[0:3], v[0:3], v[170:173], v[82:85]
	v_mfma_f32_16x16x32_bf16 v[94:97], v[4:7], v[110:113], v[94:97]
	v_mfma_f32_16x16x32_bf16 v[78:81], v[12:15], v[110:113], v[78:81]
	v_mfma_f32_16x16x32_bf16 v[90:93], v[4:7], v[122:125], v[90:93]
	v_mfma_f32_16x16x32_bf16 v[74:77], v[12:15], v[122:125], v[74:77]
	v_mfma_f32_16x16x32_bf16 v[86:89], v[4:7], v[166:169], v[86:89]
	v_mfma_f32_16x16x32_bf16 v[70:73], v[12:15], v[166:169], v[70:73]
	v_mfma_f32_16x16x32_bf16 v[0:3], v[4:7], v[174:177], v[0:3]
	v_mfma_f32_16x16x32_bf16 v[4:7], v[8:11], v[170:173], v[66:69]
	v_mfma_f32_16x16x32_bf16 v[4:7], v[12:15], v[174:177], v[4:7]
	s_barrier
; #define PG8_STAGE(bufoff, gbase, voff) do { _Pragma("unroll") for (int _i = 0; _i < 2; ++_i) \
;     __builtin_amdgcn_global_load_lds((const unsigned*)((const char*)(gbase) + (voff)[_i]), (LAS unsigned*)(lds + (bufoff) + ldsw + _i * 8192), 16, 0, 0); } while (0)
; #define PG8_LDA(dst, b, h) do { _Pragma("unroll") for (int m = 0; m < 4; ++m) _Pragma("unroll") for (int k = 0; k < 2; ++k) dst[m][k] = *(const LAS bf16x8*)(lds + PG8_SA(b, h) + aoff + m * 2048 + k * 1024); } while (0)
; #define PG8_LDB(dst, b, h) do { _Pragma("unroll") for (int n = 0; n < 2; ++n) _Pragma("unroll") for (int k = 0; k < 2; ++k) dst[n][k] = *(const LAS bf16x8*)(lds + PG8_SB(b, h) + boff + n * 2048 + k * 1024); } while (0)
; #define PG8_MMA(ai, bj, At, Bt) do { __builtin_amdgcn_s_setprio(1); _Pragma("unroll") for (int m = 0; m < 4; ++m) _Pragma("unroll") for (int n = 0; n < 2; ++n) _Pragma("unroll") for (int k = 0; k < 2; ++k) \
;     acc[ai][bj][m][n] = __builtin_amdgcn_mfma_f32_16x16x32_bf16(Bt[n][k], At[m][k], acc[ai][bj][m][n], 0, 0, 0); __builtin_amdgcn_s_setprio(0); } while (0)
; #define PG8_WAIT_V(n) asm volatile("s_waitcnt vmcnt(" #n ")" ::: "memory")
; #define PG8_WAIT_L(n) asm volatile("s_waitcnt lgkmcnt(" #n ")" ::: "memory")
; #define PG8_BAR __builtin_amdgcn_s_barrier()
; #define PG8_SCHED __builtin_amdgcn_sched_barrier(0)
; template <class Epi, class Sched, bool ABLK = false>
; __device__ __forceinline__ void gemm_phase(LAS unsigned char* lds, const Gemm g, const Sched& S, const Epi& E) {
;     ...
;       PG8_STAGE(PG8_SB(0, 1), b2 + hstepB, voffB);
;       PG8_WAIT_V(6); PG8_BAR; PG8_MMA(1, 1, At, B1); PG8_BAR;
;       PG8_LDB(B0, 1, 0); PG8_SCHED; PG8_LDA(At, 1, 0); PG8_STAGE(PG8_SA(0, 1), a2 + hstep, voffA);
;       PG8_WAIT_L(8); PG8_BAR; PG8_WAIT_L(0); PG8_MMA(0, 0, At, B0); PG8_BAR; PG8_SCHED;
;       PG8_LDB(B1, 1, 1); PG8_STAGE(PG8_SB(1, 0), b3, voffB);
;       PG8_BAR; PG8_WAIT_L(0); PG8_MMA(0, 1, At, B1); PG8_BAR;
	s_add_u32 s54, s44, 0x4000
	s_addc_u32 s55, s45, 0
	s_add_i32 s53, s58, s7
	v_lshl_add_u64 v[8:9], s[54:55], 0, v[180:181]
	s_mov_b32 m0, s53
	s_nop 0
	global_load_lds_dwordx4 v[8:9], off
	v_lshl_add_u64 v[8:9], s[54:55], 0, v[184:185]
	s_add_i32 m0, s53, 0x2000
	s_nop 0
	global_load_lds_dwordx4 v[8:9], off
	s_waitcnt vmcnt(6)
	s_barrier
	v_mfma_f32_16x16x32_bf16 v[12:15], v[230:233], v[106:109], v[46:49]
	v_mfma_f32_16x16x32_bf16 v[46:49], v[222:225], v[118:121], v[58:61]
	v_mfma_f32_16x16x32_bf16 v[58:61], v[226:229], v[122:125], v[46:49]
	v_mfma_f32_16x16x32_bf16 v[46:49], v[222:225], v[162:165], v[54:57]
	v_mfma_f32_16x16x32_bf16 v[42:45], v[230:233], v[118:121], v[42:45]
	v_mfma_f32_16x16x32_bf16 v[54:57], v[226:229], v[166:169], v[46:49]
	v_mfma_f32_16x16x32_bf16 v[38:41], v[230:233], v[162:165], v[38:41]
	v_mfma_f32_16x16x32_bf16 v[46:49], v[222:225], v[170:173], v[50:53]
	v_mfma_f32_16x16x32_bf16 v[34:37], v[230:233], v[170:173], v[34:37]
	v_mfma_f32_16x16x32_bf16 v[8:11], v[222:225], v[106:109], v[62:65]
	v_mfma_f32_16x16x32_bf16 v[42:45], v[234:237], v[122:125], v[42:45]
	v_mfma_f32_16x16x32_bf16 v[38:41], v[234:237], v[166:169], v[38:41]
	v_mfma_f32_16x16x32_bf16 v[50:53], v[226:229], v[174:177], v[46:49]
	v_mfma_f32_16x16x32_bf16 v[34:37], v[234:237], v[174:177], v[34:37]
	v_mfma_f32_16x16x32_bf16 v[8:11], v[226:229], v[110:113], v[8:11]
	v_mfma_f32_16x16x32_bf16 v[12:15], v[234:237], v[110:113], v[12:15]
	s_add_i32 s53, 0, 0x18000
	v_add_u32_e32 v82, s53, v212
	s_barrier
	ds_read_b128 v[46:49], v82
	ds_read_b128 v[62:65], v82 offset:1024
	ds_read_b128 v[66:69], v82 offset:2048
	ds_read_b128 v[162:165], v82 offset:3072
	s_add_u32 s48, s48, 0x80000
	s_addc_u32 s49, s49, 0
	s_mov_b32 m0, s27
	v_lshl_add_u64 v[110:111], s[48:49], 0, v[178:179]
	ds_read_b128 v[82:85], v218 offset:32768
	ds_read_b128 v[106:109], v218 offset:33792
	ds_read_b128 v[118:121], v218 offset:34816
	ds_read_b128 v[166:169], v218 offset:35840
	ds_read_b128 v[170:173], v218 offset:36864
	ds_read_b128 v[174:177], v218 offset:37888
	ds_read_b128 v[222:225], v218 offset:38912
	ds_read_b128 v[226:229], v218 offset:39936
	global_load_lds_dwordx4 v[110:111], off
	v_lshl_add_u64 v[110:111], s[48:49], 0, v[182:183]
	s_mov_b32 m0, s29
	s_nop 0
	global_load_lds_dwordx4 v[110:111], off
	s_waitcnt lgkmcnt(8)
	s_barrier
	s_waitcnt lgkmcnt(0)
	s_waitcnt lgkmcnt(0)
	v_mfma_f32_16x16x32_bf16 v[110:113], v[46:49], v[82:85], v[158:161]
	v_mfma_f32_16x16x32_bf16 v[158:161], v[62:65], v[106:109], v[110:113]
	v_mfma_f32_16x16x32_bf16 v[110:113], v[66:69], v[82:85], v[142:145]
	v_mfma_f32_16x16x32_bf16 v[142:145], v[162:165], v[106:109], v[110:113]
	v_mfma_f32_16x16x32_bf16 v[110:113], v[46:49], v[118:121], v[154:157]
	v_mfma_f32_16x16x32_bf16 v[154:157], v[62:65], v[166:169], v[110:113]
	v_mfma_f32_16x16x32_bf16 v[110:113], v[66:69], v[118:121], v[138:141]
	v_mfma_f32_16x16x32_bf16 v[138:141], v[162:165], v[166:169], v[110:113]
	v_mfma_f32_16x16x32_bf16 v[110:113], v[46:49], v[170:173], v[150:153]
	v_mfma_f32_16x16x32_bf16 v[150:153], v[62:65], v[174:177], v[110:113]
	v_mfma_f32_16x16x32_bf16 v[110:113], v[66:69], v[170:173], v[134:137]
	v_mfma_f32_16x16x32_bf16 v[134:137], v[162:165], v[174:177], v[110:113]
	v_mfma_f32_16x16x32_bf16 v[110:113], v[46:49], v[222:225], v[146:149]
	v_mfma_f32_16x16x32_bf16 v[146:149], v[62:65], v[226:229], v[110:113]
	v_mfma_f32_16x16x32_bf16 v[110:113], v[66:69], v[222:225], v[130:133]
	v_mfma_f32_16x16x32_bf16 v[130:133], v[162:165], v[226:229], v[110:113]
	s_barrier
	s_add_i32 s54, 0, 0x1c000
	s_add_u32 s48, s44, 0x8000
	s_nop 2
	v_add_u32_e32 v110, s54, v212
	s_addc_u32 s49, s45, 0
	s_add_i32 s53, s53, s7
	ds_read_b128 v[230:233], v110
	ds_read_b128 v[234:237], v110 offset:1024
	ds_read_b128 v[238:241], v110 offset:2048
	ds_read_b128 v[242:245], v110 offset:3072
	v_lshl_add_u64 v[110:111], s[48:49], 0, v[180:181]
	s_mov_b32 m0, s53
	s_nop 0
	global_load_lds_dwordx4 v[110:111], off
	v_lshl_add_u64 v[110:111], s[48:49], 0, v[184:185]
	s_add_i32 m0, s53, 0x2000
	s_nop 0
	global_load_lds_dwordx4 v[110:111], off
	s_barrier
; #define PG8_STAGE(bufoff, gbase, voff) do { _Pragma("unroll") for (int _i = 0; _i < 2; ++_i) \
;     __builtin_amdgcn_global_load_lds((const unsigned*)((const char*)(gbase) + (voff)[_i]), (LAS unsigned*)(lds + (bufoff) + ldsw + _i * 8192), 16, 0, 0); } while (0)
; #define PG8_LDA(dst, b, h) do { _Pragma("unroll") for (int m = 0; m < 4; ++m) _Pragma("unroll") for (int k = 0; k < 2; ++k) dst[m][k] = *(const LAS bf16x8*)(lds + PG8_SA(b, h) + aoff + m * 2048 + k * 1024); } while (0)
; #define PG8_MMA(ai, bj, At, Bt) do { __builtin_amdgcn_s_setprio(1); _Pragma("unroll") for (int m = 0; m < 4; ++m) _Pragma("unroll") for (int n = 0; n < 2; ++n) _Pragma("unroll") for (int k = 0; k < 2; ++k) \
;     acc[ai][bj][m][n] = __builtin_amdgcn_mfma_f32_16x16x32_bf16(Bt[n][k], At[m][k], acc[ai][bj][m][n], 0, 0, 0); __builtin_amdgcn_s_setprio(0); } while (0)
; #define PG8_WAIT_V(n) asm volatile("s_waitcnt vmcnt(" #n ")" ::: "memory")
; #define PG8_WAIT_L(n) asm volatile("s_waitcnt lgkmcnt(" #n ")" ::: "memory")
; #define PG8_BAR __builtin_amdgcn_s_barrier()
; #define PG8_SCHED __builtin_amdgcn_sched_barrier(0)
; template <class Epi, class Sched, bool ABLK = false>
; __device__ __forceinline__ void gemm_phase(LAS unsigned char* lds, const Gemm g, const Sched& S, const Epi& E) {
;     ...
;       PG8_BAR; PG8_WAIT_L(0); PG8_MMA(0, 1, At, B1); PG8_BAR;
;       PG8_LDA(At, 1, 1); PG8_STAGE(PG8_SA(1, 0), a3, voffA);
;       PG8_BAR; PG8_WAIT_L(0); PG8_MMA(1, 0, At, B0); PG8_BAR; PG8_SCHED;
;       PG8_STAGE(PG8_SB(1, 1), b3 + hstepB, voffB);
;       PG8_WAIT_V(6); PG8_BAR; PG8_MMA(1, 1, At, B1); PG8_BAR;
;     }
;   __device__ __forceinline__ void operator()(const f32x4 (&acc)[2][2][4][2], const Unit& u, int wr, int wc, int fr, int fq) const {
;     ...
;     if (u.pn < 12) {
;       const int tok0 = u.pm * BM; size_t base; int L, t0;
;       if (tok0 < MP) { L = LP; const int s = tok0 >> 14; t0 = tok0 & (LP - 1); base = (size_t)s * 3072 * LP; }
;       else { L = LSQ; const int tk = tok0 - MP, s = tk >> 13; t0 = tk & (LSQ - 1); base = (size_t)2 * 3072 * LP + (size_t)s * 3072 * LSQ; }
	s_waitcnt lgkmcnt(0)
	s_waitcnt lgkmcnt(0)
	v_mfma_f32_16x16x32_bf16 v[110:113], v[230:233], v[82:85], v[126:129]
	v_mfma_f32_16x16x32_bf16 v[16:19], v[238:241], v[82:85], v[16:19]
	v_mfma_f32_16x16x32_bf16 v[126:129], v[234:237], v[106:109], v[110:113]
	v_mfma_f32_16x16x32_bf16 v[110:113], v[242:245], v[106:109], v[16:19]
	v_mfma_f32_16x16x32_bf16 v[16:19], v[230:233], v[118:121], v[20:23]
	v_mfma_f32_16x16x32_bf16 v[122:125], v[234:237], v[166:169], v[16:19]
	v_mfma_f32_16x16x32_bf16 v[16:19], v[238:241], v[118:121], v[24:27]
	v_mfma_f32_16x16x32_bf16 v[106:109], v[242:245], v[166:169], v[16:19]
	v_mfma_f32_16x16x32_bf16 v[16:19], v[230:233], v[170:173], v[28:31]
	v_mfma_f32_16x16x32_bf16 v[118:121], v[234:237], v[174:177], v[16:19]
	v_mfma_f32_16x16x32_bf16 v[16:19], v[238:241], v[170:173], v[102:105]
	v_mfma_f32_16x16x32_bf16 v[102:105], v[242:245], v[174:177], v[16:19]
	v_mfma_f32_16x16x32_bf16 v[16:19], v[230:233], v[222:225], v[114:117]
	v_mfma_f32_16x16x32_bf16 v[114:117], v[234:237], v[226:229], v[16:19]
	v_mfma_f32_16x16x32_bf16 v[16:19], v[238:241], v[222:225], v[98:101]
	v_mfma_f32_16x16x32_bf16 v[98:101], v[242:245], v[226:229], v[16:19]
	s_mov_b32 m0, s31
	v_lshl_add_u64 v[82:83], v[194:195], 0, s[80:81]
	s_barrier
	s_nop 2
	ds_read_b128 v[16:19], v218 offset:49152
	ds_read_b128 v[20:23], v218 offset:50176
	ds_read_b128 v[24:27], v218 offset:51200
	ds_read_b128 v[28:31], v218 offset:52224
	ds_read_b128 v[166:169], v218 offset:53248
	ds_read_b128 v[170:173], v218 offset:54272
	ds_read_b128 v[174:177], v218 offset:55296
	ds_read_b128 v[222:225], v218 offset:56320
	global_load_lds_dwordx4 v[82:83], off
	v_lshl_add_u64 v[82:83], v[198:199], 0, s[80:81]
	s_mov_b32 m0, s56
	s_nop 0
	global_load_lds_dwordx4 v[82:83], off
	s_barrier
	s_waitcnt lgkmcnt(0)
	s_waitcnt lgkmcnt(0)
	v_mfma_f32_16x16x32_bf16 v[82:85], v[46:49], v[16:19], v[94:97]
	v_mfma_f32_16x16x32_bf16 v[94:97], v[62:65], v[20:23], v[82:85]
	v_mfma_f32_16x16x32_bf16 v[82:85], v[46:49], v[24:27], v[90:93]
	v_mfma_f32_16x16x32_bf16 v[90:93], v[62:65], v[28:31], v[82:85]
	v_mfma_f32_16x16x32_bf16 v[82:85], v[46:49], v[166:169], v[86:89]
	v_mfma_f32_16x16x32_bf16 v[0:3], v[46:49], v[174:177], v[0:3]
	v_mfma_f32_16x16x32_bf16 v[78:81], v[66:69], v[16:19], v[78:81]
	v_mfma_f32_16x16x32_bf16 v[74:77], v[66:69], v[24:27], v[74:77]
	v_mfma_f32_16x16x32_bf16 v[86:89], v[62:65], v[170:173], v[82:85]
	v_mfma_f32_16x16x32_bf16 v[70:73], v[66:69], v[166:169], v[70:73]
	v_mfma_f32_16x16x32_bf16 v[82:85], v[62:65], v[222:225], v[0:3]
	v_mfma_f32_16x16x32_bf16 v[0:3], v[66:69], v[174:177], v[4:7]
	v_mfma_f32_16x16x32_bf16 v[78:81], v[162:165], v[20:23], v[78:81]
	v_mfma_f32_16x16x32_bf16 v[74:77], v[162:165], v[28:31], v[74:77]
	v_mfma_f32_16x16x32_bf16 v[70:73], v[162:165], v[170:173], v[70:73]
	v_mfma_f32_16x16x32_bf16 v[66:69], v[162:165], v[222:225], v[0:3]
	s_barrier
	s_add_u32 s44, s44, 0xc000
	s_addc_u32 s45, s45, 0
	s_add_i32 s48, s54, s7
	v_lshl_add_u64 v[0:1], s[44:45], 0, v[180:181]
	s_mov_b32 m0, s48
	s_nop 0
	global_load_lds_dwordx4 v[0:1], off
	v_lshl_add_u64 v[0:1], s[44:45], 0, v[184:185]
	s_add_i32 m0, s48, 0x2000
	s_nop 0
	global_load_lds_dwordx4 v[0:1], off
	s_waitcnt vmcnt(6)
	s_barrier
	v_mfma_f32_16x16x32_bf16 v[0:3], v[230:233], v[16:19], v[8:11]
	v_mfma_f32_16x16x32_bf16 v[62:65], v[234:237], v[20:23], v[0:3]
	v_mfma_f32_16x16x32_bf16 v[0:3], v[238:241], v[16:19], v[12:15]
	v_mfma_f32_16x16x32_bf16 v[46:49], v[242:245], v[20:23], v[0:3]
	v_mfma_f32_16x16x32_bf16 v[0:3], v[230:233], v[24:27], v[58:61]
	v_mfma_f32_16x16x32_bf16 v[58:61], v[234:237], v[28:31], v[0:3]
	v_mfma_f32_16x16x32_bf16 v[0:3], v[238:241], v[24:27], v[42:45]
	v_mfma_f32_16x16x32_bf16 v[42:45], v[242:245], v[28:31], v[0:3]
	v_mfma_f32_16x16x32_bf16 v[0:3], v[230:233], v[166:169], v[54:57]
	v_mfma_f32_16x16x32_bf16 v[54:57], v[234:237], v[170:173], v[0:3]
	v_mfma_f32_16x16x32_bf16 v[0:3], v[238:241], v[166:169], v[38:41]
	v_mfma_f32_16x16x32_bf16 v[38:41], v[242:245], v[170:173], v[0:3]
	v_mfma_f32_16x16x32_bf16 v[0:3], v[230:233], v[174:177], v[50:53]
	v_mfma_f32_16x16x32_bf16 v[50:53], v[234:237], v[222:225], v[0:3]
	v_mfma_f32_16x16x32_bf16 v[0:3], v[238:241], v[174:177], v[34:37]
	v_mfma_f32_16x16x32_bf16 v[34:37], v[242:245], v[222:225], v[0:3]
	s_add_i32 s52, s52, 2
	s_add_u32 s50, s50, 0x10000
	s_addc_u32 s51, s51, 0
	s_add_u32 s14, s14, 0x100
	s_addc_u32 s15, s15, 0
	s_cmp_gt_u32 s52, 29
	s_barrier
	s_cbranch_scc0 .LBB0_1185
	s_lshl_b32 s23, s28, 8
	s_cmp_gt_i32 s26, 11
	s_mov_b64 s[14:15], -1
	s_cbranch_scc0 .LBB0_1238
	s_lshl_b32 s14, s26, 8
	s_add_i32 s25, s14, 0xfffff400
	s_mul_hi_u32 s15, s25, 0xaaaaaaab
	s_lshr_b32 s48, s15, 10
	s_addk_i32 s14, 0xe800
	s_cmpk_lt_u32 s14, 0x600
	v_readlane_b32 s14, v253, 49
	v_readlane_b32 s15, v253, 50
	s_cbranch_scc1 .LBB0_1189
	v_readlane_b32 s80, v255, 25
	s_mul_i32 s14, s48, 0x9000000
	v_readlane_b32 s82, v255, 27
	s_mul_hi_u32 s15, s48, 0x9000000
	v_readlane_b32 s83, v255, 28
	s_add_u32 s14, s82, s14
	s_addc_u32 s15, s83, s15
	v_readlane_b32 s81, v255, 26
	v_readlane_b32 s84, v255, 29
	v_readlane_b32 s85, v255, 30
	v_readlane_b32 s86, v255, 31
	v_readlane_b32 s87, v255, 32

; #define PG8_STAGE(bufoff, gbase, voff) do { _Pragma("unroll") for (int _i = 0; _i < 2; ++_i) \
;     __builtin_amdgcn_global_load_lds((const unsigned*)((const char*)(gbase) + (voff)[_i]), (LAS unsigned*)(lds + (bufoff) + ldsw + _i * 8192), 16, 0, 0); } while (0)
; #define PG8_LDA(dst, b, h) do { _Pragma("unroll") for (int m = 0; m < 4; ++m) _Pragma("unroll") for (int k = 0; k < 2; ++k) dst[m][k] = *(const LAS bf16x8*)(lds + PG8_SA(b, h) + aoff + m * 2048 + k * 1024); } while (0)
; #define PG8_LDB(dst, b, h) do { _Pragma("unroll") for (int n = 0; n < 2; ++n) _Pragma("unroll") for (int k = 0; k < 2; ++k) dst[n][k] = *(const LAS bf16x8*)(lds + PG8_SB(b, h) + boff + n * 2048 + k * 1024); } while (0)
; #define PG8_MMA(ai, bj, At, Bt) do { __builtin_amdgcn_s_setprio(1); _Pragma("unroll") for (int m = 0; m < 4; ++m) _Pragma("unroll") for (int n = 0; n < 2; ++n) _Pragma("unroll") for (int k = 0; k < 2; ++k) \
;     acc[ai][bj][m][n] = __builtin_amdgcn_mfma_f32_16x16x32_bf16(Bt[n][k], At[m][k], acc[ai][bj][m][n], 0, 0, 0); __builtin_amdgcn_s_setprio(0); } while (0)
; #define PG8_WAIT_V(n) asm volatile("s_waitcnt vmcnt(" #n ")" ::: "memory")
; template <class Epi, class Sched, bool ABLK = false>
; __device__ __forceinline__ void gemm_phase(LAS unsigned char* lds, const Gemm g, const Sched& S, const Epi& E) {
;     ...
;     const char* nA = has_next ? (const char*)g.A + (size_t)nxt.pm * tstep : cA; const char* nB = has_next ? (const char*)g.Bt + (size_t)nxt.pn * tstep : cB;
;     for (int t = 0; t < nt; t += 2) {
;       const bool last = (t == nt - 2);
;       const char* a1 = cA + (size_t)(t + 1) * kstep;
;       const char* a2 = last ? nA : cA + (size_t)(t + 2) * kstep; const char* b2 = last ? nB : cB + (size_t)(t + 2) * kstepB;
;       const char* a3 = a2 + kstep; const char* b3 = b2 + kstepB;
;       PG8_LDB(B0, 0, 0); PG8_SCHED; PG8_LDA(At, 0, 0); PG8_STAGE(PG8_SA(1, 1), a1 + hstep, voffA);
;       PG8_WAIT_L(8); PG8_BAR; PG8_WAIT_L(0); PG8_MMA(0, 0, At, B0); PG8_BAR; PG8_SCHED;
;       PG8_LDB(B1, 0, 1); PG8_STAGE(PG8_SB(0, 0), b2, voffB);
;       PG8_BAR; PG8_WAIT_L(0); PG8_MMA(0, 1, At, B1); PG8_BAR;
;       PG8_LDA(At, 0, 1); PG8_STAGE(PG8_SA(0, 0), a2, voffA);
;       PG8_BAR; PG8_WAIT_L(0); PG8_MMA(1, 0, At, B0); PG8_BAR; PG8_SCHED;
;       PG8_STAGE(PG8_SB(0, 1), b2 + hstepB, voffB);
;       PG8_WAIT_V(6); PG8_BAR; PG8_MMA(1, 1, At, B1); PG8_BAR;
.LBB0_1351:
	s_add_u32 s26, s24, 0x4000
	s_addc_u32 s27, s25, 0
	s_cmpk_eq_i32 s42, 0x54
	s_cselect_b32 s36, s20, s26
	s_cselect_b32 s37, s21, s27
	s_cselect_b32 s26, s22, s38
	s_cselect_b32 s27, s23, s39
	s_add_u32 s28, s36, 0x8000
	s_addc_u32 s29, s37, 0
	s_add_i32 s43, 0, 0x10000
	v_add_u32_e32 v140, s43, v143
	ds_read_b128 v[148:151], v140
	ds_read_b128 v[152:155], v140 offset:1024
	ds_read_b128 v[156:159], v140 offset:2048
	ds_read_b128 v[160:163], v140 offset:3072
	v_lshl_add_u64 v[140:141], s[24:25], 0, v[136:137]
	s_add_i32 m0, s11, 0xc000
	ds_read_b128 v[164:167], v146
	ds_read_b128 v[168:171], v146 offset:1024
	ds_read_b128 v[172:175], v146 offset:2048
	ds_read_b128 v[176:179], v146 offset:3072
	ds_read_b128 v[180:183], v146 offset:4096
	ds_read_b128 v[184:187], v146 offset:5120
	ds_read_b128 v[188:191], v146 offset:6144
	ds_read_b128 v[192:195], v146 offset:7168
	global_load_lds_dwordx4 v[140:141], off
	v_lshl_add_u64 v[140:141], s[24:25], 0, v[138:139]
	s_add_i32 m0, s11, 0xe000
	s_nop 0
	global_load_lds_dwordx4 v[140:141], off
	s_waitcnt lgkmcnt(8)
	s_barrier
	s_waitcnt lgkmcnt(0)
	s_waitcnt lgkmcnt(0)
	v_mfma_f32_16x16x32_bf16 v[126:129], v[148:151], v[164:167], v[126:129]
	v_mfma_f32_16x16x32_bf16 v[122:125], v[156:159], v[164:167], v[122:125]
	v_mfma_f32_16x16x32_bf16 v[114:117], v[148:151], v[172:175], v[114:117]
	v_mfma_f32_16x16x32_bf16 v[106:109], v[156:159], v[172:175], v[106:109]
	v_mfma_f32_16x16x32_bf16 v[98:101], v[148:151], v[180:183], v[98:101]
	v_mfma_f32_16x16x32_bf16 v[90:93], v[156:159], v[180:183], v[90:93]
	v_mfma_f32_16x16x32_bf16 v[82:85], v[148:151], v[188:191], v[82:85]
	v_mfma_f32_16x16x32_bf16 v[74:77], v[156:159], v[188:191], v[74:77]
	v_mfma_f32_16x16x32_bf16 v[126:129], v[152:155], v[168:171], v[126:129]
	v_mfma_f32_16x16x32_bf16 v[122:125], v[160:163], v[168:171], v[122:125]
	v_mfma_f32_16x16x32_bf16 v[114:117], v[152:155], v[176:179], v[114:117]
	v_mfma_f32_16x16x32_bf16 v[106:109], v[160:163], v[176:179], v[106:109]
	v_mfma_f32_16x16x32_bf16 v[98:101], v[152:155], v[184:187], v[98:101]
	v_mfma_f32_16x16x32_bf16 v[90:93], v[160:163], v[184:187], v[90:93]
	v_mfma_f32_16x16x32_bf16 v[82:85], v[152:155], v[192:195], v[82:85]
	v_mfma_f32_16x16x32_bf16 v[74:77], v[160:163], v[192:195], v[74:77]
	s_barrier
	s_add_i32 s46, 0, 0x14000
	v_add_u32_e32 v140, s46, v143
	s_add_i32 s43, s43, s7
	ds_read_b128 v[212:215], v140
	ds_read_b128 v[216:219], v140 offset:1024
	ds_read_b128 v[220:223], v140 offset:2048
	ds_read_b128 v[224:227], v140 offset:3072
	v_lshl_add_u64 v[140:141], s[26:27], 0, v[32:33]
	s_mov_b32 m0, s43
	s_nop 0
	global_load_lds_dwordx4 v[140:141], off
	v_lshl_add_u64 v[140:141], s[26:27], 0, v[134:135]
	s_add_i32 m0, s43, 0x2000
	s_nop 0
	global_load_lds_dwordx4 v[140:141], off
	s_barrier
	s_waitcnt lgkmcnt(0)
	s_waitcnt lgkmcnt(0)
	v_mfma_f32_16x16x32_bf16 v[118:121], v[212:215], v[164:167], v[118:121]
	v_mfma_f32_16x16x32_bf16 v[110:113], v[220:223], v[164:167], v[110:113]
	v_mfma_f32_16x16x32_bf16 v[102:105], v[212:215], v[172:175], v[102:105]
	v_mfma_f32_16x16x32_bf16 v[94:97], v[220:223], v[172:175], v[94:97]
	v_mfma_f32_16x16x32_bf16 v[86:89], v[212:215], v[180:183], v[86:89]
	v_mfma_f32_16x16x32_bf16 v[78:81], v[220:223], v[180:183], v[78:81]
	v_mfma_f32_16x16x32_bf16 v[70:73], v[212:215], v[188:191], v[70:73]
	v_mfma_f32_16x16x32_bf16 v[66:69], v[220:223], v[188:191], v[66:69]
	v_mfma_f32_16x16x32_bf16 v[118:121], v[216:219], v[168:171], v[118:121]
	v_mfma_f32_16x16x32_bf16 v[110:113], v[224:227], v[168:171], v[110:113]
	v_mfma_f32_16x16x32_bf16 v[102:105], v[216:219], v[176:179], v[102:105]
	v_mfma_f32_16x16x32_bf16 v[94:97], v[224:227], v[176:179], v[94:97]
	v_mfma_f32_16x16x32_bf16 v[86:89], v[216:219], v[184:187], v[86:89]
	v_mfma_f32_16x16x32_bf16 v[78:81], v[224:227], v[184:187], v[78:81]
	v_mfma_f32_16x16x32_bf16 v[70:73], v[216:219], v[192:195], v[70:73]
	v_mfma_f32_16x16x32_bf16 v[66:69], v[224:227], v[192:195], v[66:69]
	s_mov_b32 m0, s11
	v_lshl_add_u64 v[140:141], s[36:37], 0, v[130:131]
	s_barrier
	ds_read_b128 v[164:167], v146 offset:16384
	ds_read_b128 v[168:171], v146 offset:17408
	ds_read_b128 v[172:175], v146 offset:18432
	ds_read_b128 v[176:179], v146 offset:19456
	ds_read_b128 v[180:183], v146 offset:20480
	ds_read_b128 v[184:187], v146 offset:21504
	ds_read_b128 v[188:191], v146 offset:22528
	ds_read_b128 v[192:195], v146 offset:23552
	global_load_lds_dwordx4 v[140:141], off
	v_lshl_add_u64 v[140:141], s[36:37], 0, v[132:133]
	s_mov_b32 m0, s17
	s_nop 0
	global_load_lds_dwordx4 v[140:141], off
	s_barrier
	s_waitcnt lgkmcnt(0)
	s_waitcnt lgkmcnt(0)
	v_mfma_f32_16x16x32_bf16 v[62:65], v[148:151], v[164:167], v[62:65]
	v_mfma_f32_16x16x32_bf16 v[58:61], v[156:159], v[164:167], v[58:61]
	v_mfma_f32_16x16x32_bf16 v[54:57], v[148:151], v[172:175], v[54:57]
	v_mfma_f32_16x16x32_bf16 v[46:49], v[156:159], v[172:175], v[46:49]
	v_mfma_f32_16x16x32_bf16 v[38:41], v[148:151], v[180:183], v[38:41]
	v_mfma_f32_16x16x32_bf16 v[28:31], v[156:159], v[180:183], v[28:31]
	v_mfma_f32_16x16x32_bf16 v[20:23], v[148:151], v[188:191], v[20:23]
	v_mfma_f32_16x16x32_bf16 v[12:15], v[156:159], v[188:191], v[12:15]
	v_mfma_f32_16x16x32_bf16 v[62:65], v[152:155], v[168:171], v[62:65]
	v_mfma_f32_16x16x32_bf16 v[58:61], v[160:163], v[168:171], v[58:61]
	v_mfma_f32_16x16x32_bf16 v[54:57], v[152:155], v[176:179], v[54:57]
	v_mfma_f32_16x16x32_bf16 v[46:49], v[160:163], v[176:179], v[46:49]
	v_mfma_f32_16x16x32_bf16 v[38:41], v[152:155], v[184:187], v[38:41]
	v_mfma_f32_16x16x32_bf16 v[28:31], v[160:163], v[184:187], v[28:31]
	v_mfma_f32_16x16x32_bf16 v[20:23], v[152:155], v[192:195], v[20:23]
	v_mfma_f32_16x16x32_bf16 v[12:15], v[160:163], v[192:195], v[12:15]
	s_barrier
; #define PG8_STAGE(bufoff, gbase, voff) do { _Pragma("unroll") for (int _i = 0; _i < 2; ++_i) \
;     __builtin_amdgcn_global_load_lds((const unsigned*)((const char*)(gbase) + (voff)[_i]), (LAS unsigned*)(lds + (bufoff) + ldsw + _i * 8192), 16, 0, 0); } while (0)
; #define PG8_LDA(dst, b, h) do { _Pragma("unroll") for (int m = 0; m < 4; ++m) _Pragma("unroll") for (int k = 0; k < 2; ++k) dst[m][k] = *(const LAS bf16x8*)(lds + PG8_SA(b, h) + aoff + m * 2048 + k * 1024); } while (0)
; #define PG8_LDB(dst, b, h) do { _Pragma("unroll") for (int n = 0; n < 2; ++n) _Pragma("unroll") for (int k = 0; k < 2; ++k) dst[n][k] = *(const LAS bf16x8*)(lds + PG8_SB(b, h) + boff + n * 2048 + k * 1024); } while (0)
; #define PG8_MMA(ai, bj, At, Bt) do { __builtin_amdgcn_s_setprio(1); _Pragma("unroll") for (int m = 0; m < 4; ++m) _Pragma("unroll") for (int n = 0; n < 2; ++n) _Pragma("unroll") for (int k = 0; k < 2; ++k) \
;     acc[ai][bj][m][n] = __builtin_amdgcn_mfma_f32_16x16x32_bf16(Bt[n][k], At[m][k], acc[ai][bj][m][n], 0, 0, 0); __builtin_amdgcn_s_setprio(0); } while (0)
; #define PG8_WAIT_V(n) asm volatile("s_waitcnt vmcnt(" #n ")" ::: "memory")
; #define PG8_WAIT_L(n) asm volatile("s_waitcnt lgkmcnt(" #n ")" ::: "memory")
; #define PG8_BAR __builtin_amdgcn_s_barrier()
; #define PG8_SCHED __builtin_amdgcn_sched_barrier(0)
; template <class Epi, class Sched, bool ABLK = false>
; __device__ __forceinline__ void gemm_phase(LAS unsigned char* lds, const Gemm g, const Sched& S, const Epi& E) {
;     ...
;       PG8_WAIT_V(6); PG8_BAR; PG8_MMA(1, 1, At, B1); PG8_BAR;
;       PG8_LDB(B0, 1, 0); PG8_SCHED; PG8_LDA(At, 1, 0); PG8_STAGE(PG8_SA(0, 1), a2 + hstep, voffA);
;       PG8_WAIT_L(8); PG8_BAR; PG8_WAIT_L(0); PG8_MMA(0, 0, At, B0); PG8_BAR; PG8_SCHED;
;       PG8_LDB(B1, 1, 1); PG8_STAGE(PG8_SB(1, 0), b3, voffB);
;       PG8_BAR; PG8_WAIT_L(0); PG8_MMA(0, 1, At, B1); PG8_BAR;
;       PG8_LDA(At, 1, 1); PG8_STAGE(PG8_SA(1, 0), a3, voffA);
;       PG8_BAR; PG8_WAIT_L(0); PG8_MMA(1, 0, At, B0); PG8_BAR; PG8_SCHED;
	s_add_u32 s44, s26, 0x4000
	s_addc_u32 s45, s27, 0
	s_add_i32 s43, s46, s7
	v_lshl_add_u64 v[140:141], s[44:45], 0, v[32:33]
	s_mov_b32 m0, s43
	s_nop 0
	global_load_lds_dwordx4 v[140:141], off
	v_lshl_add_u64 v[140:141], s[44:45], 0, v[134:135]
	s_add_i32 m0, s43, 0x2000
	s_nop 0
	global_load_lds_dwordx4 v[140:141], off
	s_waitcnt vmcnt(6)
	s_barrier
	v_mfma_f32_16x16x32_bf16 v[50:53], v[212:215], v[164:167], v[50:53]
	v_mfma_f32_16x16x32_bf16 v[42:45], v[220:223], v[164:167], v[42:45]
	v_mfma_f32_16x16x32_bf16 v[34:37], v[212:215], v[172:175], v[34:37]
	v_mfma_f32_16x16x32_bf16 v[24:27], v[220:223], v[172:175], v[24:27]
	v_mfma_f32_16x16x32_bf16 v[16:19], v[212:215], v[180:183], v[16:19]
	v_mfma_f32_16x16x32_bf16 v[8:11], v[220:223], v[180:183], v[8:11]
	v_mfma_f32_16x16x32_bf16 v[4:7], v[212:215], v[188:191], v[4:7]
	v_mfma_f32_16x16x32_bf16 v[0:3], v[220:223], v[188:191], v[0:3]
	v_mfma_f32_16x16x32_bf16 v[50:53], v[216:219], v[168:171], v[50:53]
	v_mfma_f32_16x16x32_bf16 v[42:45], v[224:227], v[168:171], v[42:45]
	v_mfma_f32_16x16x32_bf16 v[34:37], v[216:219], v[176:179], v[34:37]
	v_mfma_f32_16x16x32_bf16 v[24:27], v[224:227], v[176:179], v[24:27]
	v_mfma_f32_16x16x32_bf16 v[16:19], v[216:219], v[184:187], v[16:19]
	v_mfma_f32_16x16x32_bf16 v[8:11], v[224:227], v[184:187], v[8:11]
	v_mfma_f32_16x16x32_bf16 v[4:7], v[216:219], v[192:195], v[4:7]
	v_mfma_f32_16x16x32_bf16 v[0:3], v[224:227], v[192:195], v[0:3]
	s_add_i32 s43, 0, 0x18000
	v_add_u32_e32 v140, s43, v143
	s_barrier
	ds_read_b128 v[148:151], v140
	ds_read_b128 v[152:155], v140 offset:1024
	ds_read_b128 v[156:159], v140 offset:2048
	ds_read_b128 v[160:163], v140 offset:3072
	s_add_u32 s36, s36, 0x4000
	s_addc_u32 s37, s37, 0
	s_mov_b32 m0, s31
	v_lshl_add_u64 v[140:141], s[36:37], 0, v[130:131]
	ds_read_b128 v[164:167], v146 offset:32768
	ds_read_b128 v[168:171], v146 offset:33792
	ds_read_b128 v[172:175], v146 offset:34816
	ds_read_b128 v[176:179], v146 offset:35840
	ds_read_b128 v[180:183], v146 offset:36864
	ds_read_b128 v[184:187], v146 offset:37888
	ds_read_b128 v[188:191], v146 offset:38912
	ds_read_b128 v[192:195], v146 offset:39936
	global_load_lds_dwordx4 v[140:141], off
	v_lshl_add_u64 v[140:141], s[36:37], 0, v[132:133]
	s_mov_b32 m0, s50
	s_nop 0
	global_load_lds_dwordx4 v[140:141], off
	s_waitcnt lgkmcnt(8)
	s_barrier
	s_waitcnt lgkmcnt(0)
	s_waitcnt lgkmcnt(0)
	v_mfma_f32_16x16x32_bf16 v[126:129], v[148:151], v[164:167], v[126:129]
	v_mfma_f32_16x16x32_bf16 v[122:125], v[156:159], v[164:167], v[122:125]
	v_mfma_f32_16x16x32_bf16 v[114:117], v[148:151], v[172:175], v[114:117]
	v_mfma_f32_16x16x32_bf16 v[106:109], v[156:159], v[172:175], v[106:109]
	v_mfma_f32_16x16x32_bf16 v[98:101], v[148:151], v[180:183], v[98:101]
	v_mfma_f32_16x16x32_bf16 v[90:93], v[156:159], v[180:183], v[90:93]
	v_mfma_f32_16x16x32_bf16 v[82:85], v[148:151], v[188:191], v[82:85]
	v_mfma_f32_16x16x32_bf16 v[74:77], v[156:159], v[188:191], v[74:77]
	v_mfma_f32_16x16x32_bf16 v[126:129], v[152:155], v[168:171], v[126:129]
	v_mfma_f32_16x16x32_bf16 v[122:125], v[160:163], v[168:171], v[122:125]
	v_mfma_f32_16x16x32_bf16 v[114:117], v[152:155], v[176:179], v[114:117]
	v_mfma_f32_16x16x32_bf16 v[106:109], v[160:163], v[176:179], v[106:109]
	v_mfma_f32_16x16x32_bf16 v[98:101], v[152:155], v[184:187], v[98:101]
	v_mfma_f32_16x16x32_bf16 v[90:93], v[160:163], v[184:187], v[90:93]
	v_mfma_f32_16x16x32_bf16 v[82:85], v[152:155], v[192:195], v[82:85]
	v_mfma_f32_16x16x32_bf16 v[74:77], v[160:163], v[192:195], v[74:77]
	s_barrier
	s_add_i32 s44, 0, 0x1c000
	s_add_u32 s36, s26, 0x8000
	v_add_u32_e32 v140, s44, v143
	s_addc_u32 s37, s27, 0
	s_add_i32 s43, s43, s7
	ds_read_b128 v[212:215], v140
	ds_read_b128 v[216:219], v140 offset:1024
	ds_read_b128 v[220:223], v140 offset:2048
	ds_read_b128 v[224:227], v140 offset:3072
	v_lshl_add_u64 v[140:141], s[36:37], 0, v[32:33]
	s_mov_b32 m0, s43
	s_nop 0
	global_load_lds_dwordx4 v[140:141], off
	v_lshl_add_u64 v[140:141], s[36:37], 0, v[134:135]
	s_add_i32 m0, s43, 0x2000
	s_nop 0
	global_load_lds_dwordx4 v[140:141], off
	s_barrier
	s_waitcnt lgkmcnt(0)
	s_waitcnt lgkmcnt(0)
	v_mfma_f32_16x16x32_bf16 v[118:121], v[212:215], v[164:167], v[118:121]
	v_mfma_f32_16x16x32_bf16 v[110:113], v[220:223], v[164:167], v[110:113]
	v_mfma_f32_16x16x32_bf16 v[102:105], v[212:215], v[172:175], v[102:105]
	v_mfma_f32_16x16x32_bf16 v[94:97], v[220:223], v[172:175], v[94:97]
	v_mfma_f32_16x16x32_bf16 v[86:89], v[212:215], v[180:183], v[86:89]
	v_mfma_f32_16x16x32_bf16 v[78:81], v[220:223], v[180:183], v[78:81]
	v_mfma_f32_16x16x32_bf16 v[70:73], v[212:215], v[188:191], v[70:73]
	v_mfma_f32_16x16x32_bf16 v[66:69], v[220:223], v[188:191], v[66:69]
	v_mfma_f32_16x16x32_bf16 v[118:121], v[216:219], v[168:171], v[118:121]
	v_mfma_f32_16x16x32_bf16 v[110:113], v[224:227], v[168:171], v[110:113]
	v_mfma_f32_16x16x32_bf16 v[102:105], v[216:219], v[176:179], v[102:105]
	v_mfma_f32_16x16x32_bf16 v[94:97], v[224:227], v[176:179], v[94:97]
	v_mfma_f32_16x16x32_bf16 v[86:89], v[216:219], v[184:187], v[86:89]
	v_mfma_f32_16x16x32_bf16 v[78:81], v[224:227], v[184:187], v[78:81]
	v_mfma_f32_16x16x32_bf16 v[70:73], v[216:219], v[192:195], v[70:73]
	v_mfma_f32_16x16x32_bf16 v[66:69], v[224:227], v[192:195], v[66:69]
	s_mov_b32 m0, s51
	v_lshl_add_u64 v[140:141], s[28:29], 0, v[130:131]
	s_barrier
	ds_read_b128 v[164:167], v146 offset:49152
	ds_read_b128 v[168:171], v146 offset:50176
	ds_read_b128 v[172:175], v146 offset:51200
	ds_read_b128 v[176:179], v146 offset:52224
	ds_read_b128 v[180:183], v146 offset:53248
	ds_read_b128 v[184:187], v146 offset:54272
	ds_read_b128 v[188:191], v146 offset:55296
	ds_read_b128 v[192:195], v146 offset:56320
	global_load_lds_dwordx4 v[140:141], off
	v_lshl_add_u64 v[140:141], s[28:29], 0, v[132:133]
	s_mov_b32 m0, s52
	s_nop 0
	global_load_lds_dwordx4 v[140:141], off
	s_barrier
; #define PG8_STAGE(bufoff, gbase, voff) do { _Pragma("unroll") for (int _i = 0; _i < 2; ++_i) \
;     __builtin_amdgcn_global_load_lds((const unsigned*)((const char*)(gbase) + (voff)[_i]), (LAS unsigned*)(lds + (bufoff) + ldsw + _i * 8192), 16, 0, 0); } while (0)
; #define PG8_MMA(ai, bj, At, Bt) do { __builtin_amdgcn_s_setprio(1); _Pragma("unroll") for (int m = 0; m < 4; ++m) _Pragma("unroll") for (int n = 0; n < 2; ++n) _Pragma("unroll") for (int k = 0; k < 2; ++k) \
;     acc[ai][bj][m][n] = __builtin_amdgcn_mfma_f32_16x16x32_bf16(Bt[n][k], At[m][k], acc[ai][bj][m][n], 0, 0, 0); __builtin_amdgcn_s_setprio(0); } while (0)
; #define PG8_WAIT_V(n) asm volatile("s_waitcnt vmcnt(" #n ")" ::: "memory")
; #define PG8_WAIT_L(n) asm volatile("s_waitcnt lgkmcnt(" #n ")" ::: "memory")
; #define PG8_BAR __builtin_amdgcn_s_barrier()
; #define PG8_SCHED __builtin_amdgcn_sched_barrier(0)
; template <class Epi, class Sched, bool ABLK = false>
; __device__ __forceinline__ void gemm_phase(LAS unsigned char* lds, const Gemm g, const Sched& S, const Epi& E) {
;     ...
;       PG8_BAR; PG8_WAIT_L(0); PG8_MMA(1, 0, At, B0); PG8_BAR; PG8_SCHED;
;       PG8_STAGE(PG8_SB(1, 1), b3 + hstepB, voffB);
;       PG8_WAIT_V(6); PG8_BAR; PG8_MMA(1, 1, At, B1); PG8_BAR;
;     }
	s_waitcnt lgkmcnt(0)
	s_waitcnt lgkmcnt(0)
	v_mfma_f32_16x16x32_bf16 v[62:65], v[148:151], v[164:167], v[62:65]
	v_mfma_f32_16x16x32_bf16 v[58:61], v[156:159], v[164:167], v[58:61]
	v_mfma_f32_16x16x32_bf16 v[54:57], v[148:151], v[172:175], v[54:57]
	v_mfma_f32_16x16x32_bf16 v[46:49], v[156:159], v[172:175], v[46:49]
	v_mfma_f32_16x16x32_bf16 v[38:41], v[148:151], v[180:183], v[38:41]
	v_mfma_f32_16x16x32_bf16 v[28:31], v[156:159], v[180:183], v[28:31]
	v_mfma_f32_16x16x32_bf16 v[20:23], v[148:151], v[188:191], v[20:23]
	v_mfma_f32_16x16x32_bf16 v[12:15], v[156:159], v[188:191], v[12:15]
	v_mfma_f32_16x16x32_bf16 v[62:65], v[152:155], v[168:171], v[62:65]
	v_mfma_f32_16x16x32_bf16 v[58:61], v[160:163], v[168:171], v[58:61]
	v_mfma_f32_16x16x32_bf16 v[54:57], v[152:155], v[176:179], v[54:57]
	v_mfma_f32_16x16x32_bf16 v[46:49], v[160:163], v[176:179], v[46:49]
	v_mfma_f32_16x16x32_bf16 v[38:41], v[152:155], v[184:187], v[38:41]
	v_mfma_f32_16x16x32_bf16 v[28:31], v[160:163], v[184:187], v[28:31]
	v_mfma_f32_16x16x32_bf16 v[20:23], v[152:155], v[192:195], v[20:23]
	v_mfma_f32_16x16x32_bf16 v[12:15], v[160:163], v[192:195], v[12:15]
	s_barrier
	s_add_u32 s26, s26, 0xc000
	s_addc_u32 s27, s27, 0
	s_add_i32 s28, s44, s7
	v_lshl_add_u64 v[140:141], s[26:27], 0, v[32:33]
	s_mov_b32 m0, s28
	s_nop 0
	global_load_lds_dwordx4 v[140:141], off
	v_lshl_add_u64 v[140:141], s[26:27], 0, v[134:135]
	s_add_i32 m0, s28, 0x2000
	s_nop 0
	global_load_lds_dwordx4 v[140:141], off
	s_waitcnt vmcnt(6)
	s_barrier
	v_mfma_f32_16x16x32_bf16 v[50:53], v[212:215], v[164:167], v[50:53]
	v_mfma_f32_16x16x32_bf16 v[42:45], v[220:223], v[164:167], v[42:45]
	v_mfma_f32_16x16x32_bf16 v[34:37], v[212:215], v[172:175], v[34:37]
	v_mfma_f32_16x16x32_bf16 v[24:27], v[220:223], v[172:175], v[24:27]
	v_mfma_f32_16x16x32_bf16 v[16:19], v[212:215], v[180:183], v[16:19]
	v_mfma_f32_16x16x32_bf16 v[8:11], v[220:223], v[180:183], v[8:11]
	v_mfma_f32_16x16x32_bf16 v[4:7], v[212:215], v[188:191], v[4:7]
	v_mfma_f32_16x16x32_bf16 v[0:3], v[220:223], v[188:191], v[0:3]
	v_mfma_f32_16x16x32_bf16 v[50:53], v[216:219], v[168:171], v[50:53]
	v_mfma_f32_16x16x32_bf16 v[42:45], v[224:227], v[168:171], v[42:45]
	v_mfma_f32_16x16x32_bf16 v[34:37], v[216:219], v[176:179], v[34:37]
	v_mfma_f32_16x16x32_bf16 v[24:27], v[224:227], v[176:179], v[24:27]
	v_mfma_f32_16x16x32_bf16 v[16:19], v[216:219], v[184:187], v[16:19]
	v_mfma_f32_16x16x32_bf16 v[8:11], v[224:227], v[184:187], v[8:11]
	v_mfma_f32_16x16x32_bf16 v[4:7], v[216:219], v[192:195], v[4:7]
	v_mfma_f32_16x16x32_bf16 v[0:3], v[224:227], v[192:195], v[0:3]
	s_add_i32 s42, s42, 2
	s_add_u32 s24, s24, 0x10000
	s_addc_u32 s25, s25, 0
	s_add_u32 s38, s38, 0x10000
	s_addc_u32 s39, s39, 0
	s_cmpk_gt_u32 s42, 0x55
	s_barrier
	s_cbranch_scc0 .LBB0_1351
; __device__ __forceinline__ unsigned cvt_pk_bf16(float lo, float hi) { unsigned r; asm volatile("v_cvt_pk_bf16_f32 %0, %1, %2" : "=v"(r) : "v"(lo), "v"(hi)); return r; }
; #define PG8_WAIT_V(n) asm volatile("s_waitcnt vmcnt(" #n ")" ::: "memory")
; #define PG8_BAR __builtin_amdgcn_s_barrier()
;   __device__ __forceinline__ float2 operator()(int i) const { const float2 wv = unpk2(Wd[i]); return half ? cmul(wv, twid((float)(i & (L - 1)) * invTurn)) : wv; }
; template <class Epi, class Sched, bool ABLK = false>
; __device__ __forceinline__ void gemm_phase(LAS unsigned char* lds, const Gemm g, const Sched& S, const Epi& E) {
;     ...
;     cur = nxt; cA = nA; cB = nB; ++ui;
;   }
;   PG8_WAIT_V(0);
;   if (wr == 0) PG8_BAR;
;   PG8_BAR;
;   __device__ __forceinline__ void operator()(const f32x4 (&acc)[2][2][4][2], const Unit& u, int wr, int wc, int fr, int fq) const {
;     const int row0 = u.pm * BM + wr * 64 + fr, col0 = u.pn * BM + wc * 32 + 8 * fq;
; #pragma unroll
;     for (int ai = 0; ai < 2; ++ai)
; #pragma unroll
;       for (int m = 0; m < 4; ++m) { bf16_t* rowp = O + (size_t)(row0 + ai * HALF + m * 16) * ldc + col0;
; #pragma unroll
;         for (int bj = 0; bj < 2; ++bj) { const f32x4 v0 = acc[ai][bj][m][0], v1 = acc[ai][bj][m][1];
;           u32x4 w; w.x = cvt_pk_bf16(v0[0], v0[1]); w.y = cvt_pk_bf16(v0[2], v0[3]); w.z = cvt_pk_bf16(v1[0], v1[1]); w.w = cvt_pk_bf16(v1[2], v1[3]);
;           *(u32x4*)(rowp + bj * HALF) = w; } }
;   }
	v_lshl_add_u32 v148, s58, 8, v142
	v_lshl_or_b32 v140, s56, 8, v145
	v_ashrrev_i32_e32 v149, 31, v148
	v_readlane_b32 s24, v251, 14
	v_ashrrev_i32_e32 v141, 31, v140
	v_lshlrev_b64 v[150:151], 12, v[148:149]
	v_readlane_b32 s25, v251, 15
	v_lshlrev_b64 v[152:153], 1, v[140:141]
	v_cvt_pk_bf16_f32 v126, v126, v127
	v_cvt_pk_bf16_f32 v127, v128, v129
	v_cvt_pk_bf16_f32 v128, v122, v123
	v_cvt_pk_bf16_f32 v129, v124, v125
	s_nop 0
	v_lshl_add_u64 v[150:151], s[24:25], 0, v[150:151]
	v_lshl_add_u64 v[140:141], v[150:151], 0, v[152:153]
	global_store_dwordx4 v[140:141], v[126:129], off
	v_cvt_pk_bf16_f32 v118, v118, v119
	v_cvt_pk_bf16_f32 v119, v120, v121
	v_cvt_pk_bf16_f32 v120, v110, v111
	v_or_b32_e32 v110, 16, v148
	v_ashrrev_i32_e32 v111, 31, v110
	v_lshlrev_b64 v[110:111], 12, v[110:111]
	v_lshl_add_u64 v[110:111], s[24:25], 0, v[110:111]
	v_cvt_pk_bf16_f32 v121, v112, v113
	global_store_dwordx4 v[140:141], v[118:121], off offset:256
	s_mov_b32 s56, s54
	s_mov_b32 s58, s55
	v_lshl_add_u64 v[118:119], v[110:111], 0, v[152:153]
	v_cvt_pk_bf16_f32 v110, v114, v115
	v_cvt_pk_bf16_f32 v111, v116, v117
	v_cvt_pk_bf16_f32 v112, v106, v107
	v_cvt_pk_bf16_f32 v113, v108, v109
	global_store_dwordx4 v[118:119], v[110:113], off
	v_cvt_pk_bf16_f32 v102, v102, v103
	v_cvt_pk_bf16_f32 v103, v104, v105
	v_cvt_pk_bf16_f32 v104, v94, v95
	v_or_b32_e32 v94, 32, v148
	v_ashrrev_i32_e32 v95, 31, v94
	v_lshlrev_b64 v[94:95], 12, v[94:95]
	v_lshl_add_u64 v[94:95], s[24:25], 0, v[94:95]
	v_cvt_pk_bf16_f32 v105, v96, v97
	global_store_dwordx4 v[118:119], v[102:105], off offset:256
	s_mov_b64 s[26:27], s[22:23]
	s_nop 0
	v_lshl_add_u64 v[102:103], v[94:95], 0, v[152:153]
	v_cvt_pk_bf16_f32 v94, v98, v99
	v_cvt_pk_bf16_f32 v95, v100, v101
	v_cvt_pk_bf16_f32 v96, v90, v91
	v_cvt_pk_bf16_f32 v97, v92, v93
	global_store_dwordx4 v[102:103], v[94:97], off
	v_cvt_pk_bf16_f32 v86, v86, v87
	v_cvt_pk_bf16_f32 v87, v88, v89
	v_cvt_pk_bf16_f32 v88, v78, v79
	v_or_b32_e32 v78, 48, v148
	v_ashrrev_i32_e32 v79, 31, v78
	v_lshlrev_b64 v[78:79], 12, v[78:79]
	v_lshl_add_u64 v[78:79], s[24:25], 0, v[78:79]
	v_cvt_pk_bf16_f32 v89, v80, v81
	global_store_dwordx4 v[102:103], v[86:89], off offset:256
	s_mov_b64 s[24:25], 0x80000
	s_nop 0
	v_lshl_add_u64 v[86:87], v[78:79], 0, v[152:153]
	v_cvt_pk_bf16_f32 v78, v82, v83
	v_cvt_pk_bf16_f32 v79, v84, v85
	v_cvt_pk_bf16_f32 v80, v74, v75
	v_cvt_pk_bf16_f32 v81, v76, v77
	global_store_dwordx4 v[86:87], v[78:81], off
	v_cvt_pk_bf16_f32 v70, v70, v71
	v_cvt_pk_bf16_f32 v71, v72, v73
	v_cvt_pk_bf16_f32 v72, v66, v67
	v_lshl_add_u64 v[66:67], v[140:141], 0, s[24:25]
	s_mov_b32 s24, 0x80000
	v_cvt_pk_bf16_f32 v73, v68, v69
	global_store_dwordx4 v[86:87], v[70:73], off offset:256
	v_cvt_pk_bf16_f32 v62, v62, v63
	v_cvt_pk_bf16_f32 v63, v64, v65
	v_cvt_pk_bf16_f32 v64, v58, v59
	v_add_co_u32_e32 v58, vcc, s24, v140
	v_cvt_pk_bf16_f32 v65, v60, v61
	s_mov_b64 s[24:25], 0x90000
	s_nop 0
	v_addc_co_u32_e32 v59, vcc, 0, v141, vcc
	global_store_dwordx4 v[58:59], v[62:65], off
	v_cvt_pk_bf16_f32 v50, v50, v51
	v_cvt_pk_bf16_f32 v51, v52, v53
	v_cvt_pk_bf16_f32 v52, v42, v43
	v_cvt_pk_bf16_f32 v53, v44, v45
	global_store_dwordx4 v[66:67], v[50:53], off offset:256
	v_cvt_pk_bf16_f32 v42, v54, v55
	v_cvt_pk_bf16_f32 v43, v56, v57
	v_cvt_pk_bf16_f32 v44, v46, v47
	v_cvt_pk_bf16_f32 v45, v48, v49
	s_nop 1
	v_lshl_add_u64 v[50:51], v[140:141], 0, s[24:25]
	s_mov_b32 s24, 0x90000
	v_add_co_u32_e32 v46, vcc, s24, v140
	s_mov_b64 s[24:25], 0xa0000
	s_nop 0
	v_addc_co_u32_e32 v47, vcc, 0, v141, vcc
	global_store_dwordx4 v[46:47], v[42:45], off
	v_cvt_pk_bf16_f32 v34, v34, v35
	v_cvt_pk_bf16_f32 v35, v36, v37
	v_cvt_pk_bf16_f32 v36, v24, v25
	v_cvt_pk_bf16_f32 v37, v26, v27
	global_store_dwordx4 v[50:51], v[34:37], off offset:256
	v_cvt_pk_bf16_f32 v24, v38, v39
	v_cvt_pk_bf16_f32 v25, v40, v41
	v_cvt_pk_bf16_f32 v26, v28, v29
	v_cvt_pk_bf16_f32 v27, v30, v31
	s_nop 1
	v_lshl_add_u64 v[34:35], v[140:141], 0, s[24:25]
	s_mov_b32 s24, 0xa0000
	v_add_co_u32_e32 v28, vcc, s24, v140
	s_mov_b64 s[24:25], 0xb0000
	s_nop 0
	v_addc_co_u32_e32 v29, vcc, 0, v141, vcc
	global_store_dwordx4 v[28:29], v[24:27], off
	v_cvt_pk_bf16_f32 v16, v16, v17
	v_cvt_pk_bf16_f32 v17, v18, v19
	v_cvt_pk_bf16_f32 v18, v8, v9
	v_cvt_pk_bf16_f32 v19, v10, v11
	global_store_dwordx4 v[34:35], v[16:19], off offset:256
	v_cvt_pk_bf16_f32 v8, v20, v21
	v_cvt_pk_bf16_f32 v9, v22, v23
	v_cvt_pk_bf16_f32 v10, v12, v13
	v_cvt_pk_bf16_f32 v11, v14, v15
	s_nop 1
	v_lshl_add_u64 v[16:17], v[140:141], 0, s[24:25]
	s_mov_b32 s24, 0xb0000
	v_add_co_u32_e32 v12, vcc, s24, v140
	s_mov_b64 s[24:25], s[20:21]
	s_nop 0
	v_addc_co_u32_e32 v13, vcc, 0, v141, vcc
	s_and_b64 vcc, exec, s[14:15]
	global_store_dwordx4 v[12:13], v[8:11], off
	v_cvt_pk_bf16_f32 v4, v4, v5
	v_cvt_pk_bf16_f32 v5, v6, v7
	v_cvt_pk_bf16_f32 v6, v0, v1
	v_cvt_pk_bf16_f32 v7, v2, v3
	global_store_dwordx4 v[16:17], v[4:7], off offset:256
	s_cbranch_vccz .LBB0_1314
	s_waitcnt vmcnt(0)
	s_cmpk_gt_u32 s5, 0xff
	v_mov_b32_e32 v131, v147
	s_cbranch_scc1 .LBB0_1355
	s_barrier

; #define PG8_STAGE(bufoff, gbase, voff) do { _Pragma("unroll") for (int _i = 0; _i < 2; ++_i) \
;     __builtin_amdgcn_global_load_lds((const unsigned*)((const char*)(gbase) + (voff)[_i]), (LAS unsigned*)(lds + (bufoff) + ldsw + _i * 8192), 16, 0, 0); } while (0)
; #define PG8_LDA(dst, b, h) do { _Pragma("unroll") for (int m = 0; m < 4; ++m) _Pragma("unroll") for (int k = 0; k < 2; ++k) dst[m][k] = *(const LAS bf16x8*)(lds + PG8_SA(b, h) + aoff + m * 2048 + k * 1024); } while (0)
; #define PG8_LDB(dst, b, h) do { _Pragma("unroll") for (int n = 0; n < 2; ++n) _Pragma("unroll") for (int k = 0; k < 2; ++k) dst[n][k] = *(const LAS bf16x8*)(lds + PG8_SB(b, h) + boff + n * 2048 + k * 1024); } while (0)
; #define PG8_MMA(ai, bj, At, Bt) do { __builtin_amdgcn_s_setprio(1); _Pragma("unroll") for (int m = 0; m < 4; ++m) _Pragma("unroll") for (int n = 0; n < 2; ++n) _Pragma("unroll") for (int k = 0; k < 2; ++k) \
;     acc[ai][bj][m][n] = __builtin_amdgcn_mfma_f32_16x16x32_bf16(Bt[n][k], At[m][k], acc[ai][bj][m][n], 0, 0, 0); __builtin_amdgcn_s_setprio(0); } while (0)
; #define PG8_WAIT_V(n) asm volatile("s_waitcnt vmcnt(" #n ")" ::: "memory")
; #define PG8_WAIT_L(n) asm volatile("s_waitcnt lgkmcnt(" #n ")" ::: "memory")
; #define PG8_BAR __builtin_amdgcn_s_barrier()
; template <class Epi, class Sched, bool ABLK = false>
; __device__ __forceinline__ void gemm_phase(LAS unsigned char* lds, const Gemm g, const Sched& S, const Epi& E) {
;     ...
;     for (int t = 0; t < nt; t += 2) {
;       const bool last = (t == nt - 2);
;       const char* a1 = cA + (size_t)(t + 1) * kstep;
;       const char* a2 = last ? nA : cA + (size_t)(t + 2) * kstep; const char* b2 = last ? nB : cB + (size_t)(t + 2) * kstepB;
;       const char* a3 = a2 + kstep; const char* b3 = b2 + kstepB;
;       PG8_LDB(B0, 0, 0); PG8_SCHED; PG8_LDA(At, 0, 0); PG8_STAGE(PG8_SA(1, 1), a1 + hstep, voffA);
;       PG8_WAIT_L(8); PG8_BAR; PG8_WAIT_L(0); PG8_MMA(0, 0, At, B0); PG8_BAR; PG8_SCHED;
;       PG8_LDB(B1, 0, 1); PG8_STAGE(PG8_SB(0, 0), b2, voffB);
;       PG8_BAR; PG8_WAIT_L(0); PG8_MMA(0, 1, At, B1); PG8_BAR;
;       PG8_LDA(At, 0, 1); PG8_STAGE(PG8_SA(0, 0), a2, voffA);
;       PG8_BAR; PG8_WAIT_L(0); PG8_MMA(1, 0, At, B0); PG8_BAR; PG8_SCHED;
;       PG8_STAGE(PG8_SB(0, 1), b2 + hstepB, voffB);
;       PG8_WAIT_V(6); PG8_BAR; PG8_MMA(1, 1, At, B1); PG8_BAR;
.LBB0_1429:
	s_add_u32 s42, s38, 0xfff80080
	s_addc_u32 s43, s39, -1
	s_add_i32 s48, 0, 0x10000
	v_add_u32_e32 v161, s48, v158
	ds_read_b128 v[162:165], v161
	ds_read_b128 v[166:169], v161 offset:1024
	ds_read_b128 v[170:173], v161 offset:2048
	ds_read_b128 v[174:177], v161 offset:3072
	s_cmp_eq_u32 s47, 28
	s_cselect_b32 s45, s25, s43
	s_cselect_b32 s44, s24, s42
	s_cselect_b32 s43, s15, s46
	s_cselect_b32 s42, s21, s29
	v_lshl_add_u64 v[194:195], s[38:39], 0, v[154:155]
	s_add_i32 m0, s11, 0xc000
	ds_read_b128 v[178:181], v159
	ds_read_b128 v[182:185], v159 offset:1024
	ds_read_b128 v[186:189], v159 offset:2048
	ds_read_b128 v[190:193], v159 offset:3072
	ds_read_b128 v[212:215], v159 offset:4096
	ds_read_b128 v[216:219], v159 offset:5120
	ds_read_b128 v[220:223], v159 offset:6144
	ds_read_b128 v[224:227], v159 offset:7168
	global_load_lds_dwordx4 v[194:195], off
	v_lshl_add_u64 v[194:195], s[38:39], 0, v[156:157]
	s_add_i32 m0, s11, 0xe000
	s_nop 0
	global_load_lds_dwordx4 v[194:195], off
	s_waitcnt lgkmcnt(8)
	s_barrier
	s_waitcnt lgkmcnt(0)
	s_waitcnt lgkmcnt(0)
	v_mfma_f32_16x16x32_bf16 v[126:129], v[162:165], v[178:181], v[126:129]
	v_mfma_f32_16x16x32_bf16 v[118:121], v[170:173], v[178:181], v[118:121]
	v_mfma_f32_16x16x32_bf16 v[110:113], v[162:165], v[186:189], v[110:113]
	v_mfma_f32_16x16x32_bf16 v[102:105], v[170:173], v[186:189], v[102:105]
	v_mfma_f32_16x16x32_bf16 v[94:97], v[162:165], v[212:215], v[94:97]
	v_mfma_f32_16x16x32_bf16 v[86:89], v[170:173], v[212:215], v[86:89]
	v_mfma_f32_16x16x32_bf16 v[78:81], v[162:165], v[220:223], v[78:81]
	v_mfma_f32_16x16x32_bf16 v[70:73], v[170:173], v[220:223], v[70:73]
	v_mfma_f32_16x16x32_bf16 v[126:129], v[166:169], v[182:185], v[126:129]
	v_mfma_f32_16x16x32_bf16 v[118:121], v[174:177], v[182:185], v[118:121]
	v_mfma_f32_16x16x32_bf16 v[110:113], v[166:169], v[190:193], v[110:113]
	v_mfma_f32_16x16x32_bf16 v[102:105], v[174:177], v[190:193], v[102:105]
	v_mfma_f32_16x16x32_bf16 v[94:97], v[166:169], v[216:219], v[94:97]
	v_mfma_f32_16x16x32_bf16 v[86:89], v[174:177], v[216:219], v[86:89]
	v_mfma_f32_16x16x32_bf16 v[78:81], v[166:169], v[224:227], v[78:81]
	v_mfma_f32_16x16x32_bf16 v[70:73], v[174:177], v[224:227], v[70:73]
	s_barrier
	s_add_i32 s50, 0, 0x14000
	s_add_i32 s48, s48, s7
	v_add_u32_e32 v161, s50, v158
	v_lshl_add_u64 v[194:195], s[42:43], 0, v[132:133]
	s_mov_b32 m0, s48
	ds_read_b128 v[228:231], v161
	ds_read_b128 v[232:235], v161 offset:1024
	ds_read_b128 v[236:239], v161 offset:2048
	ds_read_b128 v[240:243], v161 offset:3072
	global_load_lds_dwordx4 v[194:195], off
	v_lshl_add_u64 v[194:195], s[42:43], 0, v[136:137]
	s_add_i32 m0, s48, 0x2000
	s_nop 0
	global_load_lds_dwordx4 v[194:195], off
	s_barrier
	s_waitcnt lgkmcnt(0)
	s_waitcnt lgkmcnt(0)
	v_mfma_f32_16x16x32_bf16 v[122:125], v[228:231], v[178:181], v[122:125]
	v_mfma_f32_16x16x32_bf16 v[114:117], v[236:239], v[178:181], v[114:117]
	v_mfma_f32_16x16x32_bf16 v[106:109], v[228:231], v[186:189], v[106:109]
	v_mfma_f32_16x16x32_bf16 v[98:101], v[236:239], v[186:189], v[98:101]
	v_mfma_f32_16x16x32_bf16 v[90:93], v[228:231], v[212:215], v[90:93]
	v_mfma_f32_16x16x32_bf16 v[82:85], v[236:239], v[212:215], v[82:85]
	v_mfma_f32_16x16x32_bf16 v[74:77], v[228:231], v[220:223], v[74:77]
	v_mfma_f32_16x16x32_bf16 v[66:69], v[236:239], v[220:223], v[66:69]
	v_mfma_f32_16x16x32_bf16 v[122:125], v[232:235], v[182:185], v[122:125]
	v_mfma_f32_16x16x32_bf16 v[114:117], v[240:243], v[182:185], v[114:117]
	v_mfma_f32_16x16x32_bf16 v[106:109], v[232:235], v[190:193], v[106:109]
	v_mfma_f32_16x16x32_bf16 v[98:101], v[240:243], v[190:193], v[98:101]
	v_mfma_f32_16x16x32_bf16 v[90:93], v[232:235], v[216:219], v[90:93]
	v_mfma_f32_16x16x32_bf16 v[82:85], v[240:243], v[216:219], v[82:85]
	v_mfma_f32_16x16x32_bf16 v[74:77], v[232:235], v[224:227], v[74:77]
	v_mfma_f32_16x16x32_bf16 v[66:69], v[240:243], v[224:227], v[66:69]
	s_mov_b32 m0, s11
	v_lshl_add_u64 v[194:195], s[44:45], 0, v[130:131]
	s_barrier
	ds_read_b128 v[178:181], v159 offset:16384
	ds_read_b128 v[182:185], v159 offset:17408
	ds_read_b128 v[186:189], v159 offset:18432
	ds_read_b128 v[190:193], v159 offset:19456
	ds_read_b128 v[212:215], v159 offset:20480
	ds_read_b128 v[216:219], v159 offset:21504
	ds_read_b128 v[220:223], v159 offset:22528
	ds_read_b128 v[224:227], v159 offset:23552
	global_load_lds_dwordx4 v[194:195], off
	v_lshl_add_u64 v[198:199], s[44:45], 0, v[134:135]
	s_mov_b32 m0, s17
	s_nop 0
	global_load_lds_dwordx4 v[198:199], off
	s_barrier
	s_waitcnt lgkmcnt(0)
	s_waitcnt lgkmcnt(0)
	v_mfma_f32_16x16x32_bf16 v[62:65], v[162:165], v[178:181], v[62:65]
	v_mfma_f32_16x16x32_bf16 v[54:57], v[170:173], v[178:181], v[54:57]
	v_mfma_f32_16x16x32_bf16 v[46:49], v[162:165], v[186:189], v[46:49]
	v_mfma_f32_16x16x32_bf16 v[38:41], v[170:173], v[186:189], v[38:41]
	v_mfma_f32_16x16x32_bf16 v[28:31], v[162:165], v[212:215], v[28:31]
	v_mfma_f32_16x16x32_bf16 v[20:23], v[170:173], v[212:215], v[20:23]
	v_mfma_f32_16x16x32_bf16 v[12:15], v[162:165], v[220:223], v[12:15]
	v_mfma_f32_16x16x32_bf16 v[4:7], v[170:173], v[220:223], v[4:7]
	v_mfma_f32_16x16x32_bf16 v[62:65], v[166:169], v[182:185], v[62:65]
	v_mfma_f32_16x16x32_bf16 v[54:57], v[174:177], v[182:185], v[54:57]
	v_mfma_f32_16x16x32_bf16 v[46:49], v[166:169], v[190:193], v[46:49]
	v_mfma_f32_16x16x32_bf16 v[38:41], v[174:177], v[190:193], v[38:41]
	v_mfma_f32_16x16x32_bf16 v[28:31], v[166:169], v[216:219], v[28:31]
	v_mfma_f32_16x16x32_bf16 v[20:23], v[174:177], v[216:219], v[20:23]
	v_mfma_f32_16x16x32_bf16 v[12:15], v[166:169], v[224:227], v[12:15]
	v_mfma_f32_16x16x32_bf16 v[4:7], v[174:177], v[224:227], v[4:7]
	s_barrier
; #define PG8_STAGE(bufoff, gbase, voff) do { _Pragma("unroll") for (int _i = 0; _i < 2; ++_i) \
;     __builtin_amdgcn_global_load_lds((const unsigned*)((const char*)(gbase) + (voff)[_i]), (LAS unsigned*)(lds + (bufoff) + ldsw + _i * 8192), 16, 0, 0); } while (0)
; #define PG8_LDA(dst, b, h) do { _Pragma("unroll") for (int m = 0; m < 4; ++m) _Pragma("unroll") for (int k = 0; k < 2; ++k) dst[m][k] = *(const LAS bf16x8*)(lds + PG8_SA(b, h) + aoff + m * 2048 + k * 1024); } while (0)
; #define PG8_LDB(dst, b, h) do { _Pragma("unroll") for (int n = 0; n < 2; ++n) _Pragma("unroll") for (int k = 0; k < 2; ++k) dst[n][k] = *(const LAS bf16x8*)(lds + PG8_SB(b, h) + boff + n * 2048 + k * 1024); } while (0)
; #define PG8_MMA(ai, bj, At, Bt) do { __builtin_amdgcn_s_setprio(1); _Pragma("unroll") for (int m = 0; m < 4; ++m) _Pragma("unroll") for (int n = 0; n < 2; ++n) _Pragma("unroll") for (int k = 0; k < 2; ++k) \
;     acc[ai][bj][m][n] = __builtin_amdgcn_mfma_f32_16x16x32_bf16(Bt[n][k], At[m][k], acc[ai][bj][m][n], 0, 0, 0); __builtin_amdgcn_s_setprio(0); } while (0)
; #define PG8_WAIT_V(n) asm volatile("s_waitcnt vmcnt(" #n ")" ::: "memory")
; #define PG8_WAIT_L(n) asm volatile("s_waitcnt lgkmcnt(" #n ")" ::: "memory")
; #define PG8_BAR __builtin_amdgcn_s_barrier()
; #define PG8_SCHED __builtin_amdgcn_sched_barrier(0)
; template <class Epi, class Sched, bool ABLK = false>
; __device__ __forceinline__ void gemm_phase(LAS unsigned char* lds, const Gemm g, const Sched& S, const Epi& E) {
;     ...
;       PG8_WAIT_V(6); PG8_BAR; PG8_MMA(1, 1, At, B1); PG8_BAR;
;       PG8_LDB(B0, 1, 0); PG8_SCHED; PG8_LDA(At, 1, 0); PG8_STAGE(PG8_SA(0, 1), a2 + hstep, voffA);
;       PG8_WAIT_L(8); PG8_BAR; PG8_WAIT_L(0); PG8_MMA(0, 0, At, B0); PG8_BAR; PG8_SCHED;
;       PG8_LDB(B1, 1, 1); PG8_STAGE(PG8_SB(1, 0), b3, voffB);
;       PG8_BAR; PG8_WAIT_L(0); PG8_MMA(0, 1, At, B1); PG8_BAR;
;       PG8_LDA(At, 1, 1); PG8_STAGE(PG8_SA(1, 0), a3, voffA);
;       PG8_BAR; PG8_WAIT_L(0); PG8_MMA(1, 0, At, B0); PG8_BAR; PG8_SCHED;
	s_add_u32 s48, s42, 0x4000
	s_addc_u32 s49, s43, 0
	s_add_i32 s50, s50, s7
	v_lshl_add_u64 v[162:163], s[48:49], 0, v[132:133]
	s_mov_b32 m0, s50
	s_nop 0
	global_load_lds_dwordx4 v[162:163], off
	v_lshl_add_u64 v[162:163], s[48:49], 0, v[136:137]
	s_add_i32 m0, s50, 0x2000
	s_nop 0
	global_load_lds_dwordx4 v[162:163], off
	s_waitcnt vmcnt(6)
	s_barrier
	v_mfma_f32_16x16x32_bf16 v[58:61], v[228:231], v[178:181], v[58:61]
	v_mfma_f32_16x16x32_bf16 v[50:53], v[236:239], v[178:181], v[50:53]
	v_mfma_f32_16x16x32_bf16 v[42:45], v[228:231], v[186:189], v[42:45]
	v_mfma_f32_16x16x32_bf16 v[34:37], v[236:239], v[186:189], v[34:37]
	v_mfma_f32_16x16x32_bf16 v[24:27], v[228:231], v[212:215], v[24:27]
	v_mfma_f32_16x16x32_bf16 v[16:19], v[236:239], v[212:215], v[16:19]
	v_mfma_f32_16x16x32_bf16 v[8:11], v[228:231], v[220:223], v[8:11]
	v_mfma_f32_16x16x32_bf16 v[0:3], v[236:239], v[220:223], v[0:3]
	v_mfma_f32_16x16x32_bf16 v[58:61], v[232:235], v[182:185], v[58:61]
	v_mfma_f32_16x16x32_bf16 v[50:53], v[240:243], v[182:185], v[50:53]
	v_mfma_f32_16x16x32_bf16 v[42:45], v[232:235], v[190:193], v[42:45]
	v_mfma_f32_16x16x32_bf16 v[34:37], v[240:243], v[190:193], v[34:37]
	v_mfma_f32_16x16x32_bf16 v[24:27], v[232:235], v[216:219], v[24:27]
	v_mfma_f32_16x16x32_bf16 v[16:19], v[240:243], v[216:219], v[16:19]
	v_mfma_f32_16x16x32_bf16 v[8:11], v[232:235], v[224:227], v[8:11]
	v_mfma_f32_16x16x32_bf16 v[0:3], v[240:243], v[224:227], v[0:3]
	s_add_i32 s48, 0, 0x18000
	v_add_u32_e32 v161, s48, v158
	s_barrier
	ds_read_b128 v[162:165], v161
	ds_read_b128 v[166:169], v161 offset:1024
	ds_read_b128 v[170:173], v161 offset:2048
	ds_read_b128 v[174:177], v161 offset:3072
	s_add_u32 s44, s44, 0x80000
	s_addc_u32 s45, s45, 0
	s_mov_b32 m0, s31
	v_lshl_add_u64 v[208:209], s[44:45], 0, v[130:131]
	ds_read_b128 v[178:181], v159 offset:32768
	ds_read_b128 v[182:185], v159 offset:33792
	ds_read_b128 v[186:189], v159 offset:34816
	ds_read_b128 v[190:193], v159 offset:35840
	ds_read_b128 v[212:215], v159 offset:36864
	ds_read_b128 v[216:219], v159 offset:37888
	ds_read_b128 v[220:223], v159 offset:38912
	ds_read_b128 v[224:227], v159 offset:39936
	global_load_lds_dwordx4 v[208:209], off
	v_lshl_add_u64 v[208:209], s[44:45], 0, v[134:135]
	s_mov_b32 m0, s37
	s_nop 0
	global_load_lds_dwordx4 v[208:209], off
	s_waitcnt lgkmcnt(8)
	s_barrier
	s_waitcnt lgkmcnt(0)
	s_waitcnt lgkmcnt(0)
	v_mfma_f32_16x16x32_bf16 v[126:129], v[162:165], v[178:181], v[126:129]
	v_mfma_f32_16x16x32_bf16 v[118:121], v[170:173], v[178:181], v[118:121]
	v_mfma_f32_16x16x32_bf16 v[110:113], v[162:165], v[186:189], v[110:113]
	v_mfma_f32_16x16x32_bf16 v[102:105], v[170:173], v[186:189], v[102:105]
	v_mfma_f32_16x16x32_bf16 v[94:97], v[162:165], v[212:215], v[94:97]
	v_mfma_f32_16x16x32_bf16 v[86:89], v[170:173], v[212:215], v[86:89]
	v_mfma_f32_16x16x32_bf16 v[78:81], v[162:165], v[220:223], v[78:81]
	v_mfma_f32_16x16x32_bf16 v[70:73], v[170:173], v[220:223], v[70:73]
	v_mfma_f32_16x16x32_bf16 v[126:129], v[166:169], v[182:185], v[126:129]
	v_mfma_f32_16x16x32_bf16 v[118:121], v[174:177], v[182:185], v[118:121]
	v_mfma_f32_16x16x32_bf16 v[110:113], v[166:169], v[190:193], v[110:113]
	v_mfma_f32_16x16x32_bf16 v[102:105], v[174:177], v[190:193], v[102:105]
	v_mfma_f32_16x16x32_bf16 v[94:97], v[166:169], v[216:219], v[94:97]
	v_mfma_f32_16x16x32_bf16 v[86:89], v[174:177], v[216:219], v[86:89]
	v_mfma_f32_16x16x32_bf16 v[78:81], v[166:169], v[224:227], v[78:81]
	v_mfma_f32_16x16x32_bf16 v[70:73], v[174:177], v[224:227], v[70:73]
	s_barrier
	s_add_i32 s49, 0, 0x1c000
	s_add_u32 s44, s42, 0x8000
	s_addc_u32 s45, s43, 0
	s_add_i32 s48, s48, s7
	v_add_u32_e32 v161, s49, v158
	v_lshl_add_u64 v[208:209], s[44:45], 0, v[132:133]
	s_mov_b32 m0, s48
	ds_read_b128 v[228:231], v161
	ds_read_b128 v[232:235], v161 offset:1024
	ds_read_b128 v[236:239], v161 offset:2048
	ds_read_b128 v[240:243], v161 offset:3072
	global_load_lds_dwordx4 v[208:209], off
	v_lshl_add_u64 v[208:209], s[44:45], 0, v[136:137]
	s_add_i32 m0, s48, 0x2000
	s_nop 0
	global_load_lds_dwordx4 v[208:209], off
	s_barrier
	s_waitcnt lgkmcnt(0)
	s_waitcnt lgkmcnt(0)
	v_mfma_f32_16x16x32_bf16 v[122:125], v[228:231], v[178:181], v[122:125]
	v_mfma_f32_16x16x32_bf16 v[114:117], v[236:239], v[178:181], v[114:117]
	v_mfma_f32_16x16x32_bf16 v[106:109], v[228:231], v[186:189], v[106:109]
	v_mfma_f32_16x16x32_bf16 v[98:101], v[236:239], v[186:189], v[98:101]
	v_mfma_f32_16x16x32_bf16 v[90:93], v[228:231], v[212:215], v[90:93]
	v_mfma_f32_16x16x32_bf16 v[82:85], v[236:239], v[212:215], v[82:85]
	v_mfma_f32_16x16x32_bf16 v[74:77], v[228:231], v[220:223], v[74:77]
	v_mfma_f32_16x16x32_bf16 v[66:69], v[236:239], v[220:223], v[66:69]
	v_mfma_f32_16x16x32_bf16 v[122:125], v[232:235], v[182:185], v[122:125]
	v_mfma_f32_16x16x32_bf16 v[114:117], v[240:243], v[182:185], v[114:117]
	v_mfma_f32_16x16x32_bf16 v[106:109], v[232:235], v[190:193], v[106:109]
	v_mfma_f32_16x16x32_bf16 v[98:101], v[240:243], v[190:193], v[98:101]
	v_mfma_f32_16x16x32_bf16 v[90:93], v[232:235], v[216:219], v[90:93]
	v_mfma_f32_16x16x32_bf16 v[82:85], v[240:243], v[216:219], v[82:85]
	v_mfma_f32_16x16x32_bf16 v[74:77], v[232:235], v[224:227], v[74:77]
	v_mfma_f32_16x16x32_bf16 v[66:69], v[240:243], v[224:227], v[66:69]
	s_mov_b32 m0, s69
	v_lshl_add_u64 v[194:195], v[194:195], 0, s[52:53]
	s_barrier
	ds_read_b128 v[178:181], v159 offset:49152
	ds_read_b128 v[182:185], v159 offset:50176
	ds_read_b128 v[186:189], v159 offset:51200
	ds_read_b128 v[190:193], v159 offset:52224
	ds_read_b128 v[212:215], v159 offset:53248
	ds_read_b128 v[216:219], v159 offset:54272
	ds_read_b128 v[220:223], v159 offset:55296
	ds_read_b128 v[224:227], v159 offset:56320
	global_load_lds_dwordx4 v[194:195], off
	v_lshl_add_u64 v[194:195], v[198:199], 0, s[52:53]
	s_mov_b32 m0, s77
	s_nop 0
	global_load_lds_dwordx4 v[194:195], off
	s_barrier
; __device__ __forceinline__ unsigned cvt_pk_bf16(float lo, float hi) { unsigned r; asm volatile("v_cvt_pk_bf16_f32 %0, %1, %2" : "=v"(r) : "v"(lo), "v"(hi)); return r; }
; __device__ __forceinline__ float sigmoidf_(float x) { return __builtin_amdgcn_rcpf(1.0f + __expf(-x)); }
; #define PG8_STAGE(bufoff, gbase, voff) do { _Pragma("unroll") for (int _i = 0; _i < 2; ++_i) \
;     __builtin_amdgcn_global_load_lds((const unsigned*)((const char*)(gbase) + (voff)[_i]), (LAS unsigned*)(lds + (bufoff) + ldsw + _i * 8192), 16, 0, 0); } while (0)
; #define PG8_MMA(ai, bj, At, Bt) do { __builtin_amdgcn_s_setprio(1); _Pragma("unroll") for (int m = 0; m < 4; ++m) _Pragma("unroll") for (int n = 0; n < 2; ++n) _Pragma("unroll") for (int k = 0; k < 2; ++k) \
;     acc[ai][bj][m][n] = __builtin_amdgcn_mfma_f32_16x16x32_bf16(Bt[n][k], At[m][k], acc[ai][bj][m][n], 0, 0, 0); __builtin_amdgcn_s_setprio(0); } while (0)
; #define PG8_WAIT_V(n) asm volatile("s_waitcnt vmcnt(" #n ")" ::: "memory")
; #define PG8_WAIT_L(n) asm volatile("s_waitcnt lgkmcnt(" #n ")" ::: "memory")
; #define PG8_BAR __builtin_amdgcn_s_barrier()
; template <class Epi, class Sched, bool ABLK = false>
; __device__ __forceinline__ void gemm_phase(LAS unsigned char* lds, const Gemm g, const Sched& S, const Epi& E) {
;     ...
;       PG8_BAR; PG8_WAIT_L(0); PG8_MMA(1, 0, At, B0); PG8_BAR; PG8_SCHED;
;       PG8_STAGE(PG8_SB(1, 1), b3 + hstepB, voffB);
;       PG8_WAIT_V(6); PG8_BAR; PG8_MMA(1, 1, At, B1); PG8_BAR;
;     }
;   __device__ __forceinline__ void operator()(const f32x4 (&acc)[2][2][4][2], const Unit& u, int wr, int wc, int fr, int fq) const {
;     const int row0 = u.pm * BM + wr * 64 + fr, col0 = u.pn * HALF + wc * 32 + 8 * fq;
; #pragma unroll
;     for (int ai = 0; ai < 2; ++ai)
; #pragma unroll
;       for (int m = 0; m < 4; ++m) {
;         float h[8];
; #pragma unroll
;         for (int n = 0; n < 2; ++n)
; #pragma unroll
;           for (int j = 0; j < 4; ++j) { const float gt = acc[ai][0][m][n][j], up = acc[ai][1][m][n][j]; h[n * 4 + j] = gt * sigmoidf_(gt) * up; }
;         u32x4 w; w.x = cvt_pk_bf16(h[0], h[1]); w.y = cvt_pk_bf16(h[2], h[3]); w.z = cvt_pk_bf16(h[4], h[5]); w.w = cvt_pk_bf16(h[6], h[7]);
;         const int rloc = wr * 64 + fr + ai * HALF + m * 16;
;         *(u32x4*)(H + ((size_t)(u.pm * (DFF / 64) + (col0 >> 6)) * 256 + rloc) * 64 + (col0 & 63)) = w; }
	s_waitcnt lgkmcnt(0)
	s_waitcnt lgkmcnt(0)
	v_mfma_f32_16x16x32_bf16 v[62:65], v[162:165], v[178:181], v[62:65]
	v_mfma_f32_16x16x32_bf16 v[54:57], v[170:173], v[178:181], v[54:57]
	v_mfma_f32_16x16x32_bf16 v[46:49], v[162:165], v[186:189], v[46:49]
	v_mfma_f32_16x16x32_bf16 v[38:41], v[170:173], v[186:189], v[38:41]
	v_mfma_f32_16x16x32_bf16 v[28:31], v[162:165], v[212:215], v[28:31]
	v_mfma_f32_16x16x32_bf16 v[20:23], v[170:173], v[212:215], v[20:23]
	v_mfma_f32_16x16x32_bf16 v[12:15], v[162:165], v[220:223], v[12:15]
	v_mfma_f32_16x16x32_bf16 v[4:7], v[170:173], v[220:223], v[4:7]
	v_mfma_f32_16x16x32_bf16 v[62:65], v[166:169], v[182:185], v[62:65]
	v_mfma_f32_16x16x32_bf16 v[54:57], v[174:177], v[182:185], v[54:57]
	v_mfma_f32_16x16x32_bf16 v[46:49], v[166:169], v[190:193], v[46:49]
	v_mfma_f32_16x16x32_bf16 v[38:41], v[174:177], v[190:193], v[38:41]
	v_mfma_f32_16x16x32_bf16 v[28:31], v[166:169], v[216:219], v[28:31]
	v_mfma_f32_16x16x32_bf16 v[20:23], v[174:177], v[216:219], v[20:23]
	v_mfma_f32_16x16x32_bf16 v[12:15], v[166:169], v[224:227], v[12:15]
	v_mfma_f32_16x16x32_bf16 v[4:7], v[174:177], v[224:227], v[4:7]
	s_barrier
	s_add_u32 s42, s42, 0xc000
	s_addc_u32 s43, s43, 0
	s_add_i32 s44, s49, s7
	v_lshl_add_u64 v[162:163], s[42:43], 0, v[132:133]
	s_mov_b32 m0, s44
	s_nop 0
	global_load_lds_dwordx4 v[162:163], off
	v_lshl_add_u64 v[162:163], s[42:43], 0, v[136:137]
	s_add_i32 m0, s44, 0x2000
	s_nop 0
	global_load_lds_dwordx4 v[162:163], off
	s_waitcnt vmcnt(6)
	s_barrier
	v_mfma_f32_16x16x32_bf16 v[58:61], v[228:231], v[178:181], v[58:61]
	v_mfma_f32_16x16x32_bf16 v[50:53], v[236:239], v[178:181], v[50:53]
	v_mfma_f32_16x16x32_bf16 v[42:45], v[228:231], v[186:189], v[42:45]
	v_mfma_f32_16x16x32_bf16 v[34:37], v[236:239], v[186:189], v[34:37]
	v_mfma_f32_16x16x32_bf16 v[24:27], v[228:231], v[212:215], v[24:27]
	v_mfma_f32_16x16x32_bf16 v[16:19], v[236:239], v[212:215], v[16:19]
	v_mfma_f32_16x16x32_bf16 v[8:11], v[228:231], v[220:223], v[8:11]
	v_mfma_f32_16x16x32_bf16 v[0:3], v[236:239], v[220:223], v[0:3]
	v_mfma_f32_16x16x32_bf16 v[58:61], v[232:235], v[182:185], v[58:61]
	v_mfma_f32_16x16x32_bf16 v[50:53], v[240:243], v[182:185], v[50:53]
	v_mfma_f32_16x16x32_bf16 v[42:45], v[232:235], v[190:193], v[42:45]
	v_mfma_f32_16x16x32_bf16 v[34:37], v[240:243], v[190:193], v[34:37]
	v_mfma_f32_16x16x32_bf16 v[24:27], v[232:235], v[216:219], v[24:27]
	v_mfma_f32_16x16x32_bf16 v[16:19], v[240:243], v[216:219], v[16:19]
	v_mfma_f32_16x16x32_bf16 v[8:11], v[232:235], v[224:227], v[8:11]
	v_mfma_f32_16x16x32_bf16 v[0:3], v[240:243], v[224:227], v[0:3]
	s_add_i32 s47, s47, 2
	s_add_u32 s29, s29, 0x10000
	s_addc_u32 s46, s46, 0
	s_add_u32 s38, s38, 0x100
	s_addc_u32 s39, s39, 0
	s_cmp_gt_u32 s47, 29
	s_barrier
	s_cbranch_scc0 .LBB0_1429
	v_mul_f32_e32 v161, 0xbfb8aa3b, v126
	v_exp_f32_e32 v161, v161
	s_lshl_b32 s15, s28, 7
	s_or_b32 s15, s15, s56
	s_mul_i32 s21, s36, 0x58
	v_add_f32_e32 v161, 1.0, v161
	v_rcp_f32_e32 v161, v161
	s_ashr_i32 s15, s15, 6
	s_add_i32 s28, s15, s21
	s_ashr_i32 s29, s28, 31
	v_mul_f32_e32 v126, v126, v161
	v_mul_f32_e32 v122, v126, v122
	v_mul_f32_e32 v126, 0xbfb8aa3b, v127
	v_exp_f32_e32 v126, v126
	s_lshl_b64 s[28:29], s[28:29], 15
	v_readlane_b32 s38, v252, 36
	v_readlane_b32 s39, v252, 37
	v_add_f32_e32 v126, 1.0, v126
	v_rcp_f32_e32 v126, v126
	s_add_u32 s28, s38, s28
	s_addc_u32 s29, s39, s29
	s_and_b64 vcc, exec, s[22:23]
	v_mul_f32_e32 v126, v127, v126
	v_mul_f32_e32 v123, v126, v123
	v_mul_f32_e32 v126, 0xbfb8aa3b, v128
	v_exp_f32_e32 v126, v126
	s_mov_b32 s36, s20
	s_mov_b64 s[38:39], s[26:27]
	s_mov_b64 s[42:43], s[24:25]
	v_add_f32_e32 v126, 1.0, v126
	v_rcp_f32_e32 v126, v126
	s_nop 0
	v_mul_f32_e32 v126, v128, v126
	v_mul_f32_e32 v124, v126, v124
	v_mul_f32_e32 v126, 0xbfb8aa3b, v129
	v_exp_f32_e32 v126, v126
	s_nop 0
	v_add_f32_e32 v126, 1.0, v126
	v_rcp_f32_e32 v126, v126
	s_nop 0
	v_mul_f32_e32 v126, v129, v126
	v_mul_f32_e32 v125, v126, v125
	v_mul_f32_e32 v126, 0xbfb8aa3b, v118
	v_exp_f32_e32 v126, v126
	s_nop 0
	v_add_f32_e32 v126, 1.0, v126
	v_rcp_f32_e32 v126, v126
	s_nop 0
	v_mul_f32_e32 v118, v118, v126
	v_mul_f32_e32 v118, v118, v114
	v_mul_f32_e32 v114, 0xbfb8aa3b, v119
	v_exp_f32_e32 v114, v114
	s_nop 0
	v_add_f32_e32 v114, 1.0, v114
	v_rcp_f32_e32 v114, v114
	s_nop 0
	v_mul_f32_e32 v114, v119, v114
	v_mul_f32_e32 v119, v114, v115
	v_mul_f32_e32 v114, 0xbfb8aa3b, v120
	v_exp_f32_e32 v114, v114
	s_nop 0
	v_add_f32_e32 v114, 1.0, v114
	v_rcp_f32_e32 v114, v114
	s_nop 0
	v_mul_f32_e32 v114, v120, v114
	v_mul_f32_e32 v120, v114, v116
	v_mul_f32_e32 v114, 0xbfb8aa3b, v121
	v_exp_f32_e32 v114, v114
	s_nop 0
	v_add_f32_e32 v114, 1.0, v114
	v_rcp_f32_e32 v114, v114
	s_nop 0
	v_mul_f32_e32 v114, v121, v114
	v_mul_f32_e32 v117, v114, v117
	v_cvt_pk_bf16_f32 v114, v122, v123
	v_cvt_pk_bf16_f32 v115, v124, v125
	v_cvt_pk_bf16_f32 v116, v118, v119
	v_lshl_add_u64 v[118:119], s[28:29], 0, v[138:139]
	v_lshl_add_u64 v[118:119], v[118:119], 0, v[32:33]
	v_cvt_pk_bf16_f32 v117, v120, v117
	global_store_dwordx4 v[118:119], v[114:117], off
	s_nop 1
	v_mul_f32_e32 v114, 0xbfb8aa3b, v110
	v_exp_f32_e32 v114, v114
	s_nop 0
	v_add_f32_e32 v114, 1.0, v114
	v_rcp_f32_e32 v114, v114
	s_nop 0
	v_mul_f32_e32 v110, v110, v114
	v_mul_f32_e32 v106, v110, v106
	v_mul_f32_e32 v110, 0xbfb8aa3b, v111
	v_exp_f32_e32 v110, v110
	s_nop 0
	v_add_f32_e32 v110, 1.0, v110
	v_rcp_f32_e32 v110, v110
	s_nop 0
	v_mul_f32_e32 v110, v111, v110
	v_mul_f32_e32 v107, v110, v107
	v_mul_f32_e32 v110, 0xbfb8aa3b, v112
	v_exp_f32_e32 v110, v110
	s_nop 0
	v_add_f32_e32 v110, 1.0, v110
	v_rcp_f32_e32 v110, v110
	s_nop 0
	v_mul_f32_e32 v110, v112, v110
; __device__ __forceinline__ unsigned cvt_pk_bf16(float lo, float hi) { unsigned r; asm volatile("v_cvt_pk_bf16_f32 %0, %1, %2" : "=v"(r) : "v"(lo), "v"(hi)); return r; }
; __device__ __forceinline__ float sigmoidf_(float x) { return __builtin_amdgcn_rcpf(1.0f + __expf(-x)); }
;   __device__ __forceinline__ void operator()(const f32x4 (&acc)[2][2][4][2], const Unit& u, int wr, int wc, int fr, int fq) const {
;     ...
;     for (int ai = 0; ai < 2; ++ai)
; #pragma unroll
;       for (int m = 0; m < 4; ++m) {
;         float h[8];
; #pragma unroll
;         for (int n = 0; n < 2; ++n)
; #pragma unroll
;           for (int j = 0; j < 4; ++j) { const float gt = acc[ai][0][m][n][j], up = acc[ai][1][m][n][j]; h[n * 4 + j] = gt * sigmoidf_(gt) * up; }
;         u32x4 w; w.x = cvt_pk_bf16(h[0], h[1]); w.y = cvt_pk_bf16(h[2], h[3]); w.z = cvt_pk_bf16(h[4], h[5]); w.w = cvt_pk_bf16(h[6], h[7]);
;         const int rloc = wr * 64 + fr + ai * HALF + m * 16;
;         *(u32x4*)(H + ((size_t)(u.pm * (DFF / 64) + (col0 >> 6)) * 256 + rloc) * 64 + (col0 & 63)) = w; }
	v_mul_f32_e32 v108, v110, v108
	v_mul_f32_e32 v110, 0xbfb8aa3b, v113
	v_exp_f32_e32 v110, v110
	s_nop 0
	v_add_f32_e32 v110, 1.0, v110
	v_rcp_f32_e32 v110, v110
	s_nop 0
	v_mul_f32_e32 v110, v113, v110
	v_mul_f32_e32 v109, v110, v109
	v_mul_f32_e32 v110, 0xbfb8aa3b, v102
	v_exp_f32_e32 v110, v110
	s_nop 0
	v_add_f32_e32 v110, 1.0, v110
	v_rcp_f32_e32 v110, v110
	s_nop 0
	v_mul_f32_e32 v102, v102, v110
	v_mul_f32_e32 v102, v102, v98
	v_mul_f32_e32 v98, 0xbfb8aa3b, v103
	v_exp_f32_e32 v98, v98
	s_nop 0
	v_add_f32_e32 v98, 1.0, v98
	v_rcp_f32_e32 v98, v98
	s_nop 0
	v_mul_f32_e32 v98, v103, v98
	v_mul_f32_e32 v103, v98, v99
	v_mul_f32_e32 v98, 0xbfb8aa3b, v104
	v_exp_f32_e32 v98, v98
	s_nop 0
	v_add_f32_e32 v98, 1.0, v98
	v_rcp_f32_e32 v98, v98
	s_nop 0
	v_mul_f32_e32 v98, v104, v98
	v_mul_f32_e32 v104, v98, v100
	v_mul_f32_e32 v98, 0xbfb8aa3b, v105
	v_exp_f32_e32 v98, v98
	s_nop 0
	v_add_f32_e32 v98, 1.0, v98
	v_rcp_f32_e32 v98, v98
	s_nop 0
	v_mul_f32_e32 v98, v105, v98
	v_mul_f32_e32 v101, v98, v101
	v_cvt_pk_bf16_f32 v98, v106, v107
	v_cvt_pk_bf16_f32 v99, v108, v109
	v_cvt_pk_bf16_f32 v100, v102, v103
	v_lshl_add_u64 v[102:103], s[28:29], 0, v[140:141]
	v_lshl_add_u64 v[102:103], v[102:103], 0, v[32:33]
	v_cvt_pk_bf16_f32 v101, v104, v101
	global_store_dwordx4 v[102:103], v[98:101], off
	s_nop 1
	v_mul_f32_e32 v98, 0xbfb8aa3b, v94
	v_exp_f32_e32 v98, v98
	s_nop 0
	v_add_f32_e32 v98, 1.0, v98
	v_rcp_f32_e32 v98, v98
	s_nop 0
	v_mul_f32_e32 v94, v94, v98
	v_mul_f32_e32 v90, v94, v90
	v_mul_f32_e32 v94, 0xbfb8aa3b, v95
	v_exp_f32_e32 v94, v94
	s_nop 0
	v_add_f32_e32 v94, 1.0, v94
	v_rcp_f32_e32 v94, v94
	s_nop 0
	v_mul_f32_e32 v94, v95, v94
	v_mul_f32_e32 v91, v94, v91
	v_mul_f32_e32 v94, 0xbfb8aa3b, v96
	v_exp_f32_e32 v94, v94
	s_nop 0
	v_add_f32_e32 v94, 1.0, v94
	v_rcp_f32_e32 v94, v94
	s_nop 0
	v_mul_f32_e32 v94, v96, v94
	v_mul_f32_e32 v92, v94, v92
	v_mul_f32_e32 v94, 0xbfb8aa3b, v97
	v_exp_f32_e32 v94, v94
	s_nop 0
	v_add_f32_e32 v94, 1.0, v94
	v_rcp_f32_e32 v94, v94
	s_nop 0
	v_mul_f32_e32 v94, v97, v94
	v_mul_f32_e32 v93, v94, v93
	v_mul_f32_e32 v94, 0xbfb8aa3b, v86
	v_exp_f32_e32 v94, v94
	s_nop 0
	v_add_f32_e32 v94, 1.0, v94
	v_rcp_f32_e32 v94, v94
	s_nop 0
	v_mul_f32_e32 v86, v86, v94
	v_mul_f32_e32 v86, v86, v82
	v_mul_f32_e32 v82, 0xbfb8aa3b, v87
	v_exp_f32_e32 v82, v82
	s_nop 0
	v_add_f32_e32 v82, 1.0, v82
	v_rcp_f32_e32 v82, v82
	s_nop 0
	v_mul_f32_e32 v82, v87, v82
	v_mul_f32_e32 v87, v82, v83
	v_mul_f32_e32 v82, 0xbfb8aa3b, v88
	v_exp_f32_e32 v82, v82
	s_nop 0
	v_add_f32_e32 v82, 1.0, v82
	v_rcp_f32_e32 v82, v82
	s_nop 0
	v_mul_f32_e32 v82, v88, v82
	v_mul_f32_e32 v88, v82, v84
	v_mul_f32_e32 v82, 0xbfb8aa3b, v89
	v_exp_f32_e32 v82, v82
	s_nop 0
	v_add_f32_e32 v82, 1.0, v82
	v_rcp_f32_e32 v82, v82
	s_nop 0
	v_mul_f32_e32 v82, v89, v82
	v_mul_f32_e32 v85, v82, v85
	v_cvt_pk_bf16_f32 v82, v90, v91
	v_cvt_pk_bf16_f32 v83, v92, v93
	v_cvt_pk_bf16_f32 v84, v86, v87
	v_lshl_add_u64 v[86:87], s[28:29], 0, v[142:143]
	v_lshl_add_u64 v[86:87], v[86:87], 0, v[32:33]
	v_cvt_pk_bf16_f32 v85, v88, v85
	global_store_dwordx4 v[86:87], v[82:85], off
	s_nop 1
	v_mul_f32_e32 v82, 0xbfb8aa3b, v78
	v_exp_f32_e32 v82, v82
	s_nop 0
	v_add_f32_e32 v82, 1.0, v82
	v_rcp_f32_e32 v82, v82
	s_nop 0
	v_mul_f32_e32 v78, v78, v82
	v_mul_f32_e32 v74, v78, v74
	v_mul_f32_e32 v78, 0xbfb8aa3b, v79
	v_exp_f32_e32 v78, v78
	s_nop 0
	v_add_f32_e32 v78, 1.0, v78
	v_rcp_f32_e32 v78, v78
	s_nop 0
	v_mul_f32_e32 v78, v79, v78
	v_mul_f32_e32 v75, v78, v75
	v_mul_f32_e32 v78, 0xbfb8aa3b, v80
	v_exp_f32_e32 v78, v78
	s_nop 0
	v_add_f32_e32 v78, 1.0, v78
	v_rcp_f32_e32 v78, v78
	s_nop 0
	v_mul_f32_e32 v78, v80, v78
	v_mul_f32_e32 v76, v78, v76
	v_mul_f32_e32 v78, 0xbfb8aa3b, v81
	v_exp_f32_e32 v78, v78
	s_nop 0
	v_add_f32_e32 v78, 1.0, v78
	v_rcp_f32_e32 v78, v78
	s_nop 0
	v_mul_f32_e32 v78, v81, v78
	v_mul_f32_e32 v77, v78, v77
	v_mul_f32_e32 v78, 0xbfb8aa3b, v70
	v_exp_f32_e32 v78, v78
	s_nop 0
	v_add_f32_e32 v78, 1.0, v78
	v_rcp_f32_e32 v78, v78
	s_nop 0
	v_mul_f32_e32 v70, v70, v78
	v_mul_f32_e32 v70, v70, v66
	v_mul_f32_e32 v66, 0xbfb8aa3b, v71
	v_exp_f32_e32 v66, v66
	s_nop 0
	v_add_f32_e32 v66, 1.0, v66
	v_rcp_f32_e32 v66, v66
	s_nop 0
	v_mul_f32_e32 v66, v71, v66
	v_mul_f32_e32 v71, v66, v67
	v_mul_f32_e32 v66, 0xbfb8aa3b, v72
	v_exp_f32_e32 v66, v66
	s_nop 0
	v_add_f32_e32 v66, 1.0, v66
	v_rcp_f32_e32 v66, v66
	s_nop 0
	v_mul_f32_e32 v66, v72, v66
	v_mul_f32_e32 v72, v66, v68
	v_mul_f32_e32 v66, 0xbfb8aa3b, v73
	v_exp_f32_e32 v66, v66
	s_nop 0
	v_add_f32_e32 v66, 1.0, v66
	v_rcp_f32_e32 v66, v66
	s_nop 0
	v_mul_f32_e32 v66, v73, v66
	v_mul_f32_e32 v69, v66, v69
	v_cvt_pk_bf16_f32 v66, v74, v75
	v_cvt_pk_bf16_f32 v67, v76, v77
	v_cvt_pk_bf16_f32 v68, v70, v71
	v_lshl_add_u64 v[70:71], s[28:29], 0, v[144:145]
	v_lshl_add_u64 v[70:71], v[70:71], 0, v[32:33]
	v_cvt_pk_bf16_f32 v69, v72, v69
	global_store_dwordx4 v[70:71], v[66:69], off
	s_nop 1
	v_mul_f32_e32 v66, 0xbfb8aa3b, v62
	v_exp_f32_e32 v66, v66
	s_nop 0
	v_add_f32_e32 v66, 1.0, v66
	v_rcp_f32_e32 v66, v66
	s_nop 0
	v_mul_f32_e32 v62, v62, v66
	v_mul_f32_e32 v58, v62, v58
	v_mul_f32_e32 v62, 0xbfb8aa3b, v63
	v_exp_f32_e32 v62, v62
	s_nop 0
	v_add_f32_e32 v62, 1.0, v62
	v_rcp_f32_e32 v62, v62
	s_nop 0
	v_mul_f32_e32 v62, v63, v62
	v_mul_f32_e32 v59, v62, v59
	v_mul_f32_e32 v62, 0xbfb8aa3b, v64
	v_exp_f32_e32 v62, v62
	s_nop 0
	v_add_f32_e32 v62, 1.0, v62
	v_rcp_f32_e32 v62, v62
	s_nop 0
	v_mul_f32_e32 v62, v64, v62
	v_mul_f32_e32 v60, v62, v60
	v_mul_f32_e32 v62, 0xbfb8aa3b, v65
	v_exp_f32_e32 v62, v62
	s_nop 0
	v_add_f32_e32 v62, 1.0, v62
	v_rcp_f32_e32 v62, v62
	s_nop 0
	v_mul_f32_e32 v62, v65, v62
; __device__ __forceinline__ unsigned cvt_pk_bf16(float lo, float hi) { unsigned r; asm volatile("v_cvt_pk_bf16_f32 %0, %1, %2" : "=v"(r) : "v"(lo), "v"(hi)); return r; }
; __device__ __forceinline__ float sigmoidf_(float x) { return __builtin_amdgcn_rcpf(1.0f + __expf(-x)); }
; #define PG8_WAIT_V(n) asm volatile("s_waitcnt vmcnt(" #n ")" ::: "memory")
; #define PG8_BAR __builtin_amdgcn_s_barrier()
; template <class Epi, class Sched, bool ABLK = false>
; __device__ __forceinline__ void gemm_phase(LAS unsigned char* lds, const Gemm g, const Sched& S, const Epi& E) {
;     ...
;     if (!has_next) break;
; #pragma unroll
;     for (int a = 0; a < 2; ++a)
; #pragma unroll
;       for (int b = 0; b < 2; ++b)
; #pragma unroll
;         for (int m = 0; m < 4; ++m)
; #pragma unroll
;           for (int n = 0; n < 2; ++n) acc[a][b][m][n] = (f32x4){0.f, 0.f, 0.f, 0.f};
;     cur = nxt; cA = nA; cB = nB; ++ui;
;   }
;   PG8_WAIT_V(0);
;   if (wr == 0) PG8_BAR;
;   PG8_BAR;
;   __device__ __forceinline__ void operator()(const f32x4 (&acc)[2][2][4][2], const Unit& u, int wr, int wc, int fr, int fq) const {
;     ...
;         float h[8];
; #pragma unroll
;         for (int n = 0; n < 2; ++n)
; #pragma unroll
;           for (int j = 0; j < 4; ++j) { const float gt = acc[ai][0][m][n][j], up = acc[ai][1][m][n][j]; h[n * 4 + j] = gt * sigmoidf_(gt) * up; }
;         u32x4 w; w.x = cvt_pk_bf16(h[0], h[1]); w.y = cvt_pk_bf16(h[2], h[3]); w.z = cvt_pk_bf16(h[4], h[5]); w.w = cvt_pk_bf16(h[6], h[7]);
;         const int rloc = wr * 64 + fr + ai * HALF + m * 16;
;         *(u32x4*)(H + ((size_t)(u.pm * (DFF / 64) + (col0 >> 6)) * 256 + rloc) * 64 + (col0 & 63)) = w; }
	v_mul_f32_e32 v61, v62, v61
	v_mul_f32_e32 v62, 0xbfb8aa3b, v54
	v_exp_f32_e32 v62, v62
	s_nop 0
	v_add_f32_e32 v62, 1.0, v62
	v_rcp_f32_e32 v62, v62
	s_nop 0
	v_mul_f32_e32 v54, v54, v62
	v_mul_f32_e32 v54, v54, v50
	v_mul_f32_e32 v50, 0xbfb8aa3b, v55
	v_exp_f32_e32 v50, v50
	s_nop 0
	v_add_f32_e32 v50, 1.0, v50
	v_rcp_f32_e32 v50, v50
	s_nop 0
	v_mul_f32_e32 v50, v55, v50
	v_mul_f32_e32 v55, v50, v51
	v_mul_f32_e32 v50, 0xbfb8aa3b, v56
	v_exp_f32_e32 v50, v50
	s_nop 0
	v_add_f32_e32 v50, 1.0, v50
	v_rcp_f32_e32 v50, v50
	s_nop 0
	v_mul_f32_e32 v50, v56, v50
	v_mul_f32_e32 v56, v50, v52
	v_mul_f32_e32 v50, 0xbfb8aa3b, v57
	v_exp_f32_e32 v50, v50
	s_nop 0
	v_add_f32_e32 v50, 1.0, v50
	v_rcp_f32_e32 v50, v50
	s_nop 0
	v_mul_f32_e32 v50, v57, v50
	v_mul_f32_e32 v53, v50, v53
	v_cvt_pk_bf16_f32 v50, v58, v59
	v_cvt_pk_bf16_f32 v51, v60, v61
	v_cvt_pk_bf16_f32 v52, v54, v55
	v_lshl_add_u64 v[54:55], s[28:29], 0, v[146:147]
	v_lshl_add_u64 v[54:55], v[54:55], 0, v[32:33]
	v_cvt_pk_bf16_f32 v53, v56, v53
	global_store_dwordx4 v[54:55], v[50:53], off
	s_nop 1
	v_mul_f32_e32 v50, 0xbfb8aa3b, v46
	v_exp_f32_e32 v50, v50
	s_nop 0
	v_add_f32_e32 v50, 1.0, v50
	v_rcp_f32_e32 v50, v50
	s_nop 0
	v_mul_f32_e32 v46, v46, v50
	v_mul_f32_e32 v42, v46, v42
	v_mul_f32_e32 v46, 0xbfb8aa3b, v47
	v_exp_f32_e32 v46, v46
	s_nop 0
	v_add_f32_e32 v46, 1.0, v46
	v_rcp_f32_e32 v46, v46
	s_nop 0
	v_mul_f32_e32 v46, v47, v46
	v_mul_f32_e32 v43, v46, v43
	v_mul_f32_e32 v46, 0xbfb8aa3b, v48
	v_exp_f32_e32 v46, v46
	s_nop 0
	v_add_f32_e32 v46, 1.0, v46
	v_rcp_f32_e32 v46, v46
	s_nop 0
	v_mul_f32_e32 v46, v48, v46
	v_mul_f32_e32 v44, v46, v44
	v_mul_f32_e32 v46, 0xbfb8aa3b, v49
	v_exp_f32_e32 v46, v46
	s_nop 0
	v_add_f32_e32 v46, 1.0, v46
	v_rcp_f32_e32 v46, v46
	s_nop 0
	v_mul_f32_e32 v46, v49, v46
	v_mul_f32_e32 v45, v46, v45
	v_mul_f32_e32 v46, 0xbfb8aa3b, v38
	v_exp_f32_e32 v46, v46
	s_nop 0
	v_add_f32_e32 v46, 1.0, v46
	v_rcp_f32_e32 v46, v46
	s_nop 0
	v_mul_f32_e32 v38, v38, v46
	v_mul_f32_e32 v38, v38, v34
	v_mul_f32_e32 v34, 0xbfb8aa3b, v39
	v_exp_f32_e32 v34, v34
	s_nop 0
	v_add_f32_e32 v34, 1.0, v34
	v_rcp_f32_e32 v34, v34
	s_nop 0
	v_mul_f32_e32 v34, v39, v34
	v_mul_f32_e32 v39, v34, v35
	v_mul_f32_e32 v34, 0xbfb8aa3b, v40
	v_exp_f32_e32 v34, v34
	s_nop 0
	v_add_f32_e32 v34, 1.0, v34
	v_rcp_f32_e32 v34, v34
	s_nop 0
	v_mul_f32_e32 v34, v40, v34
	v_mul_f32_e32 v40, v34, v36
	v_mul_f32_e32 v34, 0xbfb8aa3b, v41
	v_exp_f32_e32 v34, v34
	s_nop 0
	v_add_f32_e32 v34, 1.0, v34
	v_rcp_f32_e32 v34, v34
	s_nop 0
	v_mul_f32_e32 v34, v41, v34
	v_mul_f32_e32 v37, v34, v37
	v_cvt_pk_bf16_f32 v34, v42, v43
	v_cvt_pk_bf16_f32 v35, v44, v45
	v_cvt_pk_bf16_f32 v36, v38, v39
	v_lshl_add_u64 v[38:39], s[28:29], 0, v[148:149]
	v_lshl_add_u64 v[38:39], v[38:39], 0, v[32:33]
	v_cvt_pk_bf16_f32 v37, v40, v37
	global_store_dwordx4 v[38:39], v[34:37], off
	s_nop 1
	v_mul_f32_e32 v34, 0xbfb8aa3b, v28
	v_exp_f32_e32 v34, v34
	s_nop 0
	v_add_f32_e32 v34, 1.0, v34
	v_rcp_f32_e32 v34, v34
	s_nop 0
	v_mul_f32_e32 v28, v28, v34
	v_mul_f32_e32 v24, v28, v24
	v_mul_f32_e32 v28, 0xbfb8aa3b, v29
	v_exp_f32_e32 v28, v28
	s_nop 0
	v_add_f32_e32 v28, 1.0, v28
	v_rcp_f32_e32 v28, v28
	s_nop 0
	v_mul_f32_e32 v28, v29, v28
	v_mul_f32_e32 v25, v28, v25
	v_mul_f32_e32 v28, 0xbfb8aa3b, v30
	v_exp_f32_e32 v28, v28
	s_nop 0
	v_add_f32_e32 v28, 1.0, v28
	v_rcp_f32_e32 v28, v28
	s_nop 0
	v_mul_f32_e32 v28, v30, v28
	v_mul_f32_e32 v26, v28, v26
	v_mul_f32_e32 v28, 0xbfb8aa3b, v31
	v_exp_f32_e32 v28, v28
	s_nop 0
	v_add_f32_e32 v28, 1.0, v28
	v_rcp_f32_e32 v28, v28
	s_nop 0
	v_mul_f32_e32 v28, v31, v28
	v_mul_f32_e32 v27, v28, v27
	v_mul_f32_e32 v28, 0xbfb8aa3b, v20
	v_exp_f32_e32 v28, v28
	s_nop 0
	v_add_f32_e32 v28, 1.0, v28
	v_rcp_f32_e32 v28, v28
	s_nop 0
	v_mul_f32_e32 v20, v20, v28
	v_mul_f32_e32 v20, v20, v16
	v_mul_f32_e32 v16, 0xbfb8aa3b, v21
	v_exp_f32_e32 v16, v16
	s_nop 0
	v_add_f32_e32 v16, 1.0, v16
	v_rcp_f32_e32 v16, v16
	s_nop 0
	v_mul_f32_e32 v16, v21, v16
	v_mul_f32_e32 v21, v16, v17
	v_mul_f32_e32 v16, 0xbfb8aa3b, v22
	v_exp_f32_e32 v16, v16
	s_nop 0
	v_add_f32_e32 v16, 1.0, v16
	v_rcp_f32_e32 v16, v16
	s_nop 0
	v_mul_f32_e32 v16, v22, v16
	v_mul_f32_e32 v22, v16, v18
	v_mul_f32_e32 v16, 0xbfb8aa3b, v23
	v_exp_f32_e32 v16, v16
	s_nop 0
	v_add_f32_e32 v16, 1.0, v16
	v_rcp_f32_e32 v16, v16
	s_nop 0
	v_mul_f32_e32 v16, v23, v16
	v_mul_f32_e32 v19, v16, v19
	v_cvt_pk_bf16_f32 v16, v24, v25
	v_cvt_pk_bf16_f32 v17, v26, v27
	v_cvt_pk_bf16_f32 v18, v20, v21
	v_lshl_add_u64 v[20:21], s[28:29], 0, v[150:151]
	v_lshl_add_u64 v[20:21], v[20:21], 0, v[32:33]
	v_cvt_pk_bf16_f32 v19, v22, v19
	global_store_dwordx4 v[20:21], v[16:19], off
	s_nop 1
	v_mul_f32_e32 v16, 0xbfb8aa3b, v12
	v_exp_f32_e32 v16, v16
	s_nop 0
	v_add_f32_e32 v16, 1.0, v16
	v_rcp_f32_e32 v16, v16
	s_nop 0
	v_mul_f32_e32 v12, v12, v16
	v_mul_f32_e32 v8, v12, v8
	v_mul_f32_e32 v12, 0xbfb8aa3b, v13
	v_exp_f32_e32 v12, v12
	s_nop 0
	v_add_f32_e32 v12, 1.0, v12
	v_rcp_f32_e32 v12, v12
	s_nop 0
	v_mul_f32_e32 v12, v13, v12
	v_mul_f32_e32 v9, v12, v9
	v_mul_f32_e32 v12, 0xbfb8aa3b, v14
	v_exp_f32_e32 v12, v12
	s_nop 0
	v_add_f32_e32 v12, 1.0, v12
	v_rcp_f32_e32 v12, v12
	s_nop 0
	v_mul_f32_e32 v12, v14, v12
	v_mul_f32_e32 v10, v12, v10
	v_mul_f32_e32 v12, 0xbfb8aa3b, v15
	v_exp_f32_e32 v12, v12
	s_nop 0
	v_add_f32_e32 v12, 1.0, v12
	v_rcp_f32_e32 v12, v12
	s_nop 0
	v_mul_f32_e32 v12, v15, v12
	v_mul_f32_e32 v11, v12, v11
	v_mul_f32_e32 v12, 0xbfb8aa3b, v4
	v_exp_f32_e32 v12, v12
	s_nop 0
	v_add_f32_e32 v12, 1.0, v12
	v_rcp_f32_e32 v12, v12
	s_nop 0
	v_mul_f32_e32 v4, v4, v12
	v_mul_f32_e32 v4, v4, v0
	v_mul_f32_e32 v0, 0xbfb8aa3b, v5
	v_exp_f32_e32 v0, v0
	s_nop 0
	v_add_f32_e32 v0, 1.0, v0
	v_rcp_f32_e32 v0, v0
	s_nop 0
	v_mul_f32_e32 v0, v5, v0
	v_mul_f32_e32 v5, v0, v1
	v_mul_f32_e32 v0, 0xbfb8aa3b, v6
	v_exp_f32_e32 v0, v0
	s_nop 0
	v_add_f32_e32 v0, 1.0, v0
	v_rcp_f32_e32 v0, v0
	s_nop 0
	v_mul_f32_e32 v0, v6, v0
	v_mul_f32_e32 v6, v0, v2
	v_mul_f32_e32 v0, 0xbfb8aa3b, v7
	v_exp_f32_e32 v0, v0
	s_nop 0
	v_add_f32_e32 v0, 1.0, v0
	v_rcp_f32_e32 v0, v0
	s_nop 0
	v_mul_f32_e32 v0, v7, v0
	v_mul_f32_e32 v3, v0, v3
	v_cvt_pk_bf16_f32 v0, v8, v9
	v_cvt_pk_bf16_f32 v1, v10, v11
	v_cvt_pk_bf16_f32 v2, v4, v5
	v_lshl_add_u64 v[4:5], s[28:29], 0, v[152:153]
	v_lshl_add_u64 v[4:5], v[4:5], 0, v[32:33]
	s_mov_b32 s28, s14
	v_cvt_pk_bf16_f32 v3, v6, v3
	global_store_dwordx4 v[4:5], v[0:3], off
	s_cbranch_vccz .LBB0_1394
	s_waitcnt vmcnt(0)
	s_cmpk_gt_u32 s5, 0xff
	s_mov_b32 s77, s13
	s_cbranch_scc1 .LBB0_1433
	s_barrier
